# stack6 + PV V-fragment reads up front (4 steps of first-query copy) + list-entry LDS reads hoisted ahead of the stage writes (19 steps)
# baseline (speedup 1.0000x reference)
.LBB0_2559:
	s_waitcnt vmcnt(7)
	v_mov_b32_e32 v4, v0
	s_lshl_b32 s0, s4, 10
	v_and_b32_e32 v144, 3, v4
	v_lshl_or_b32 v134, v144, 8, s0
	v_lshl_add_u64 v[2:3], s[38:39], 0, v[134:135]
	v_and_b32_e32 v134, 48, v4
	v_bfe_u32 v145, v4, 4, 2
	s_waitcnt vmcnt(5)
	v_lshl_add_u64 v[14:15], v[2:3], 0, v[134:135]
	v_and_b32_e32 v146, 63, v4
	v_and_b32_e32 v1, 15, v4
	global_load_dwordx4 v[2:5], v[14:15], off
	global_load_dwordx4 v[6:9], v[14:15], off offset:64
	global_load_dwordx4 v[10:13], v[14:15], off offset:128
	v_lshl_add_u32 v142, v145, 2, v138
	global_load_dwordx4 v[14:17], v[14:15], off offset:192
	s_waitcnt vmcnt(11)
	ds_read2_b32 v[18:19], v142 offset1:4
	ds_read2_b32 v[20:21], v142 offset0:8 offset1:12
	s_lshl_b32 s0, s4, 8
	s_waitcnt vmcnt(7)
	ds_read2_b32 v[26:27], v142 offset0:40 offset1:44
	s_add_u32 s0, s58, s0
	s_waitcnt lgkmcnt(2)
	v_add_u32_e32 v22, s48, v18
	v_add_u32_e32 v18, s48, v19
	s_addc_u32 s1, s59, 0
	v_lshlrev_b32_e32 v114, 4, v1
	v_mov_b32_e32 v115, v135
	v_ashrrev_i32_e32 v23, 31, v22
	v_ashrrev_i32_e32 v19, 31, v18
	v_lshl_add_u64 v[136:137], s[0:1], 0, v[114:115]
	v_lshlrev_b64 v[22:23], 9, v[22:23]
	v_lshlrev_b64 v[18:19], 9, v[18:19]
	v_lshl_add_u64 v[22:23], v[136:137], 0, v[22:23]
	v_lshl_add_u64 v[18:19], v[136:137], 0, v[18:19]
	global_load_dwordx4 v[42:45], v[22:23], off
	global_load_dwordx4 v[50:53], v[18:19], off
	s_waitcnt lgkmcnt(1)
	v_add_u32_e32 v18, s48, v20
	s_waitcnt lgkmcnt(0)
	v_add_u32_e32 v28, s48, v26
	v_add_u32_e32 v26, s48, v27
	s_waitcnt vmcnt(7)
	ds_read2_b32 v[58:59], v142 offset0:72 offset1:76
	v_ashrrev_i32_e32 v19, 31, v18
	v_ashrrev_i32_e32 v27, 31, v26
	v_lshlrev_b64 v[18:19], 9, v[18:19]
	v_lshlrev_b64 v[26:27], 9, v[26:27]
	v_lshl_add_u64 v[18:19], v[136:137], 0, v[18:19]
	v_lshl_add_u64 v[26:27], v[136:137], 0, v[26:27]
	global_load_dwordx4 v[54:57], v[18:19], off
	global_load_dwordx4 v[38:41], v[26:27], off
	ds_read2_b32 v[26:27], v142 offset0:48 offset1:52
	s_waitcnt vmcnt(8) lgkmcnt(1)
	v_add_u32_e32 v46, s48, v58
	v_ashrrev_i32_e32 v29, 31, v28
	v_ashrrev_i32_e32 v47, 31, v46
	v_lshlrev_b64 v[28:29], 9, v[28:29]
	v_lshlrev_b64 v[46:47], 9, v[46:47]
	v_lshl_add_u64 v[28:29], v[136:137], 0, v[28:29]
	v_lshl_add_u64 v[46:47], v[136:137], 0, v[46:47]
	v_add_u32_e32 v18, s48, v21
	global_load_dwordx4 v[34:37], v[28:29], off
	v_ashrrev_i32_e32 v19, 31, v18
	global_load_dwordx4 v[46:49], v[46:47], off
	s_waitcnt lgkmcnt(0)
	v_add_u32_e32 v28, s48, v26
	v_add_u32_e32 v26, s48, v27
	v_ashrrev_i32_e32 v27, 31, v26
	v_lshlrev_b64 v[18:19], 9, v[18:19]
	v_lshlrev_b64 v[26:27], 9, v[26:27]
	v_lshl_add_u64 v[18:19], v[136:137], 0, v[18:19]
	v_lshl_add_u64 v[26:27], v[136:137], 0, v[26:27]
	global_load_dwordx4 v[66:69], v[18:19], off
	global_load_dwordx4 v[70:73], v[26:27], off
	ds_read2_b32 v[18:19], v142 offset0:16 offset1:20
	ds_read2_b32 v[26:27], v142 offset0:56 offset1:60
	v_add_u32_e32 v58, s48, v59
	v_ashrrev_i32_e32 v29, 31, v28
	v_ashrrev_i32_e32 v59, 31, v58
	s_waitcnt lgkmcnt(1)
	v_add_u32_e32 v20, s48, v18
	v_add_u32_e32 v18, s48, v19
	v_ashrrev_i32_e32 v21, 31, v20
	v_ashrrev_i32_e32 v19, 31, v18
	v_lshlrev_b64 v[20:21], 9, v[20:21]
	v_lshlrev_b64 v[18:19], 9, v[18:19]
	v_lshl_add_u64 v[20:21], v[136:137], 0, v[20:21]
	v_lshl_add_u64 v[18:19], v[136:137], 0, v[18:19]
	global_load_dwordx4 v[78:81], v[20:21], off
	global_load_dwordx4 v[90:93], v[18:19], off
	ds_read2_b32 v[18:19], v142 offset0:24 offset1:28
	v_lshlrev_b64 v[28:29], 9, v[28:29]
	v_lshlrev_b64 v[58:59], 9, v[58:59]
	ds_read2_b32 v[22:23], v142 offset0:32 offset1:36
	v_lshl_add_u64 v[28:29], v[136:137], 0, v[28:29]
	s_waitcnt lgkmcnt(1)
	v_add_u32_e32 v20, s48, v18
	v_ashrrev_i32_e32 v21, 31, v20
	v_add_u32_e32 v18, s48, v19
	v_lshlrev_b64 v[20:21], 9, v[20:21]
	v_ashrrev_i32_e32 v19, 31, v18
	v_lshl_add_u64 v[20:21], v[136:137], 0, v[20:21]
	v_lshlrev_b64 v[18:19], 9, v[18:19]
	global_load_dwordx4 v[102:105], v[20:21], off
	v_lshl_add_u64 v[18:19], v[136:137], 0, v[18:19]
	global_load_dwordx4 v[110:113], v[18:19], off
	ds_read2_b32 v[30:31], v142 offset0:64 offset1:68
	v_lshl_add_u64 v[58:59], v[136:137], 0, v[58:59]
	ds_read2_b32 v[82:83], v142 offset0:80 offset1:84
	ds_read2_b32 v[106:107], v142 offset0:88 offset1:92
	global_load_dwordx4 v[62:65], v[28:29], off
	s_waitcnt lgkmcnt(3)
	v_add_u32_e32 v18, s48, v22
	global_load_dwordx4 v[58:61], v[58:59], off
	v_add_u32_e32 v28, s48, v26
	v_add_u32_e32 v26, s48, v27
	v_ashrrev_i32_e32 v29, 31, v28
	v_ashrrev_i32_e32 v27, 31, v26
	v_lshlrev_b64 v[28:29], 9, v[28:29]
	v_lshlrev_b64 v[26:27], 9, v[26:27]
	v_lshl_add_u64 v[28:29], v[136:137], 0, v[28:29]
	v_lshl_add_u64 v[26:27], v[136:137], 0, v[26:27]
	v_add_u32_e32 v22, s48, v23
	global_load_dwordx4 v[86:89], v[28:29], off
	global_load_dwordx4 v[94:97], v[26:27], off
	s_waitcnt lgkmcnt(2)
	v_add_u32_e32 v26, s48, v30
	v_add_u32_e32 v30, s48, v31
	s_waitcnt lgkmcnt(1)
	v_add_u32_e32 v74, s48, v82
	v_add_u32_e32 v82, s48, v83
	s_waitcnt lgkmcnt(0)
	v_add_u32_e32 v98, s48, v106
	v_add_u32_e32 v106, s48, v107
	v_ashrrev_i32_e32 v19, 31, v18
	v_ashrrev_i32_e32 v23, 31, v22
	v_ashrrev_i32_e32 v27, 31, v26
	v_ashrrev_i32_e32 v31, 31, v30
	v_ashrrev_i32_e32 v75, 31, v74
	v_ashrrev_i32_e32 v83, 31, v82
	v_ashrrev_i32_e32 v99, 31, v98
	v_ashrrev_i32_e32 v107, 31, v106
	v_lshlrev_b64 v[18:19], 9, v[18:19]
	v_lshlrev_b64 v[22:23], 9, v[22:23]
	v_lshlrev_b64 v[26:27], 9, v[26:27]
	v_lshlrev_b64 v[30:31], 9, v[30:31]
	v_lshlrev_b64 v[74:75], 9, v[74:75]
	v_lshlrev_b64 v[82:83], 9, v[82:83]
	v_lshlrev_b64 v[98:99], 9, v[98:99]
	v_lshlrev_b64 v[106:107], 9, v[106:107]
	v_add_u32_e32 v139, v138, v114
	v_lshl_add_u64 v[18:19], v[136:137], 0, v[18:19]
	v_lshl_add_u64 v[22:23], v[136:137], 0, v[22:23]
	v_lshl_add_u64 v[26:27], v[136:137], 0, v[26:27]
	v_lshl_add_u64 v[30:31], v[136:137], 0, v[30:31]
	v_lshl_add_u64 v[74:75], v[136:137], 0, v[74:75]
	v_lshl_add_u64 v[82:83], v[136:137], 0, v[82:83]
	v_lshl_add_u64 v[98:99], v[136:137], 0, v[98:99]
	v_lshl_add_u64 v[106:107], v[136:137], 0, v[106:107]
	v_mad_u32_u24 v143, v145, s33, v139
	global_load_dwordx4 v[18:21], v[18:19], off
	v_add_u32_e32 v118, v138, v134
	global_load_dwordx4 v[22:25], v[22:23], off
	v_cmp_lt_u32_e64 s[10:11], 3, v1
	global_load_dwordx4 v[26:29], v[26:27], off
	v_mad_u32_u24 v119, v1, s33, v118
	global_load_dwordx4 v[30:33], v[30:31], off
	s_waitcnt vmcnt(23)
	v_cndmask_b32_e64 v5, v5, 0, s[10:11]
	global_load_dwordx4 v[74:77], v[74:75], off
	v_cndmask_b32_e64 v4, v4, 0, s[10:11]
	global_load_dwordx4 v[82:85], v[82:83], off
	v_cndmask_b32_e64 v3, v3, 0, s[10:11]
	global_load_dwordx4 v[98:101], v[98:99], off
	v_cndmask_b32_e64 v2, v2, 0, s[10:11]
	global_load_dwordx4 v[106:109], v[106:107], off
	ds_read2_b32 v[208:209], v142 offset0:96 offset1:100
	ds_read2_b32 v[210:211], v142 offset0:104 offset1:108
	ds_read2_b32 v[212:213], v142 offset0:112 offset1:116
	ds_read2_b32 v[214:215], v142 offset0:120 offset1:124
	s_waitcnt vmcnt(23)
	ds_write_b128 v143, v[42:45] offset:7168
	s_waitcnt vmcnt(22)
	ds_write_b128 v143, v[50:53] offset:8448
	s_waitcnt vmcnt(21)
	ds_write_b128 v143, v[54:57] offset:9728
	s_waitcnt vmcnt(17)
	ds_write_b128 v143, v[66:69] offset:11008
	s_waitcnt vmcnt(15)
	ds_write_b128 v143, v[78:81] offset:12288
	s_waitcnt vmcnt(14)
	ds_write_b128 v143, v[90:93] offset:13568
	s_waitcnt vmcnt(13)
	ds_write_b128 v143, v[102:105] offset:14848
	s_waitcnt vmcnt(12)
	ds_write_b128 v143, v[110:113] offset:16128
	s_nop 0
	s_nop 0
	s_nop 0
	s_nop 0
	ds_read_b128 v[114:117], v119 offset:7168
	ds_read_b128 v[120:123], v119 offset:7232
	ds_read_b128 v[174:177], v119 offset:7296
	ds_read_b128 v[178:181], v119 offset:7360
	s_waitcnt lgkmcnt(5)
	v_add_u32_e32 v42, s48, v208
	v_add_u32_e32 v50, s48, v209
	s_waitcnt lgkmcnt(4)
	v_add_u32_e32 v54, s48, v210
	v_add_u32_e32 v66, s48, v211
	s_waitcnt lgkmcnt(3)
	v_add_u32_e32 v78, s48, v212
	v_add_u32_e32 v90, s48, v213
	s_waitcnt lgkmcnt(2)
	v_add_u32_e32 v102, s48, v214
	v_add_u32_e32 v110, s48, v215
	v_ashrrev_i32_e32 v43, 31, v42
	v_ashrrev_i32_e32 v51, 31, v50
	v_ashrrev_i32_e32 v55, 31, v54
	v_ashrrev_i32_e32 v67, 31, v66
	v_ashrrev_i32_e32 v79, 31, v78
	v_ashrrev_i32_e32 v91, 31, v90
	v_ashrrev_i32_e32 v103, 31, v102
	v_ashrrev_i32_e32 v111, 31, v110
	v_lshlrev_b64 v[42:43], 9, v[42:43]
	v_lshlrev_b64 v[50:51], 9, v[50:51]
	v_lshlrev_b64 v[54:55], 9, v[54:55]
	v_lshlrev_b64 v[66:67], 9, v[66:67]
	v_lshlrev_b64 v[78:79], 9, v[78:79]
	v_lshlrev_b64 v[90:91], 9, v[90:91]
	v_lshlrev_b64 v[102:103], 9, v[102:103]
	v_lshlrev_b64 v[110:111], 9, v[110:111]
	v_lshl_add_u64 v[42:43], v[136:137], 0, v[42:43]
	v_lshl_add_u64 v[50:51], v[136:137], 0, v[50:51]
	v_lshl_add_u64 v[54:55], v[136:137], 0, v[54:55]
	v_lshl_add_u64 v[66:67], v[136:137], 0, v[66:67]
	v_lshl_add_u64 v[78:79], v[136:137], 0, v[78:79]
	v_lshl_add_u64 v[90:91], v[136:137], 0, v[90:91]
	v_lshl_add_u64 v[102:103], v[136:137], 0, v[102:103]
	v_lshl_add_u64 v[110:111], v[136:137], 0, v[110:111]
	global_load_dwordx4 v[42:45], v[42:43], off
	v_cndmask_b32_e64 v9, v9, 0, s[10:11]
	global_load_dwordx4 v[50:53], v[50:51], off
	v_cndmask_b32_e64 v8, v8, 0, s[10:11]
	global_load_dwordx4 v[54:57], v[54:55], off
	v_cndmask_b32_e64 v7, v7, 0, s[10:11]
	global_load_dwordx4 v[66:69], v[66:67], off
	v_cndmask_b32_e64 v6, v6, 0, s[10:11]
	global_load_dwordx4 v[78:81], v[78:79], off
	s_waitcnt lgkmcnt(1)
	v_mfma_f32_16x16x32_bf16 v[114:117], v[2:5], v[114:117], 0
	global_load_dwordx4 v[90:93], v[90:91], off
	v_cndmask_b32_e64 v13, v13, 0, s[10:11]
	global_load_dwordx4 v[102:105], v[102:103], off
	v_cndmask_b32_e64 v12, v12, 0, s[10:11]
	global_load_dwordx4 v[110:113], v[110:111], off
	v_cndmask_b32_e64 v11, v11, 0, s[10:11]
	v_cndmask_b32_e64 v10, v10, 0, s[10:11]
	s_waitcnt lgkmcnt(0)
	v_mfma_f32_16x16x32_bf16 v[114:117], v[6:9], v[120:123], v[114:117]
	s_nop 0
	v_cndmask_b32_e64 v17, v17, 0, s[10:11]
	v_cndmask_b32_e64 v16, v16, 0, s[10:11]
	v_cndmask_b32_e64 v15, v15, 0, s[10:11]
	v_cndmask_b32_e64 v14, v14, 0, s[10:11]
	s_waitcnt lgkmcnt(0)
	v_mfma_f32_16x16x32_bf16 v[114:117], v[10:13], v[174:177], v[114:117]
	s_nop 0
	v_cmp_gt_u32_e64 s[12:13], 16, v146
	s_waitcnt lgkmcnt(0)
	v_mfma_f32_16x16x32_bf16 v[114:117], v[14:17], v[178:181], v[114:117]
	s_and_saveexec_b64 s[0:1], s[12:13]
	s_nop 6
	ds_write_b128 v139, v[114:117] offset:1024
	s_or_b64 exec, exec, s[0:1]
	v_mul_u32_u24_e32 v114, 0x140, v1
	v_add_u32_e32 v140, v118, v114
	ds_read_b128 v[114:117], v140 offset:12288
	ds_read_b128 v[118:121], v140 offset:12352
	ds_read_b128 v[174:177], v140 offset:12416
	ds_read_b128 v[178:181], v140 offset:12480
	s_waitcnt lgkmcnt(1)
	v_mfma_f32_16x16x32_bf16 v[114:117], v[2:5], v[114:117], 0
	s_waitcnt lgkmcnt(0)
	v_mfma_f32_16x16x32_bf16 v[114:117], v[6:9], v[118:121], v[114:117]
	s_nop 0
	s_waitcnt lgkmcnt(0)
	v_mfma_f32_16x16x32_bf16 v[114:117], v[10:13], v[174:177], v[114:117]
	s_nop 0
	s_waitcnt lgkmcnt(0)
	v_mfma_f32_16x16x32_bf16 v[114:117], v[14:17], v[178:181], v[114:117]
	s_and_saveexec_b64 s[0:1], s[12:13]
	s_nop 6
	ds_write_b128 v139, v[114:117] offset:1280
	s_or_b64 exec, exec, s[0:1]
	ds_read2_b32 v[208:209], v142 offset0:128 offset1:132
	ds_read2_b32 v[210:211], v142 offset0:136 offset1:140
	s_waitcnt vmcnt(15)
	ds_write_b128 v143, v[18:21] offset:7168
	s_waitcnt vmcnt(14)
	ds_write_b128 v143, v[22:25] offset:8448
	ds_write_b128 v143, v[34:37] offset:9728
	ds_write_b128 v143, v[38:41] offset:11008
	ds_write_b128 v143, v[62:65] offset:12288
	ds_write_b128 v143, v[70:73] offset:13568
	ds_write_b128 v143, v[86:89] offset:14848
	ds_write_b128 v143, v[94:97] offset:16128
	s_nop 0
	s_nop 0
	s_waitcnt lgkmcnt(1)
	v_add_u32_e32 v22, s48, v208
	v_ashrrev_i32_e32 v23, 31, v22
	v_add_u32_e32 v18, s48, v209
	v_lshlrev_b64 v[22:23], 9, v[22:23]
	v_ashrrev_i32_e32 v19, 31, v18
	v_lshl_add_u64 v[22:23], v[136:137], 0, v[22:23]
	v_lshlrev_b64 v[18:19], 9, v[18:19]
	v_lshl_add_u64 v[18:19], v[136:137], 0, v[18:19]
	global_load_dwordx4 v[70:73], v[22:23], off
	global_load_dwordx4 v[86:89], v[18:19], off
	ds_read2_b32 v[22:23], v142 offset0:144 offset1:148
	s_waitcnt lgkmcnt(1)
	v_add_u32_e32 v18, s48, v210
	v_add_u32_e32 v20, s48, v211
	v_ashrrev_i32_e32 v19, 31, v18
	v_ashrrev_i32_e32 v21, 31, v20
	v_lshlrev_b64 v[18:19], 9, v[18:19]
	v_lshlrev_b64 v[20:21], 9, v[20:21]
	v_lshl_add_u64 v[18:19], v[136:137], 0, v[18:19]
	v_lshl_add_u64 v[20:21], v[136:137], 0, v[20:21]
	global_load_dwordx4 v[94:97], v[18:19], off
	global_load_dwordx4 v[114:117], v[20:21], off
	s_waitcnt lgkmcnt(0)
	v_add_u32_e32 v18, s48, v22
	v_add_u32_e32 v20, s48, v23
	ds_read2_b32 v[34:35], v142 offset0:152 offset1:156
	v_ashrrev_i32_e32 v19, 31, v18
	v_ashrrev_i32_e32 v21, 31, v20
	v_lshlrev_b64 v[18:19], 9, v[18:19]
	v_lshlrev_b64 v[20:21], 9, v[20:21]
	v_lshl_add_u64 v[18:19], v[136:137], 0, v[18:19]
	v_lshl_add_u64 v[20:21], v[136:137], 0, v[20:21]
	global_load_dwordx4 v[118:121], v[18:19], off
	global_load_dwordx4 v[122:125], v[20:21], off
	ds_read_b128 v[18:21], v140 offset:7168
	s_waitcnt lgkmcnt(1)
	v_add_u32_e32 v22, s48, v34
	v_ashrrev_i32_e32 v23, 31, v22
	v_lshlrev_b64 v[22:23], 9, v[22:23]
	v_lshl_add_u64 v[38:39], v[136:137], 0, v[22:23]
	ds_read_b128 v[22:25], v140 offset:7232
	s_waitcnt lgkmcnt(1)
	v_mfma_f32_16x16x32_bf16 v[18:21], v[2:5], v[18:21], 0
	v_add_u32_e32 v40, s48, v35
	v_ashrrev_i32_e32 v41, 31, v40
	ds_read_b128 v[34:37], v140 offset:7296
	s_waitcnt lgkmcnt(1)
	v_mfma_f32_16x16x32_bf16 v[18:21], v[6:9], v[22:25], v[18:21]
	v_lshlrev_b64 v[22:23], 9, v[40:41]
	v_lshl_add_u64 v[40:41], v[136:137], 0, v[22:23]
	ds_read_b128 v[22:25], v140 offset:7360
	global_load_dwordx4 v[126:129], v[38:39], off
	global_load_dwordx4 v[130:133], v[40:41], off
	s_waitcnt lgkmcnt(1)
	v_mfma_f32_16x16x32_bf16 v[18:21], v[10:13], v[34:37], v[18:21]
	s_waitcnt lgkmcnt(0)
	v_mfma_f32_16x16x32_bf16 v[18:21], v[14:17], v[22:25], v[18:21]
	s_and_saveexec_b64 s[0:1], s[12:13]
	s_nop 6
	ds_write_b128 v139, v[18:21] offset:1536
	s_or_b64 exec, exec, s[0:1]
	ds_read_b128 v[18:21], v140 offset:12288
	ds_read_b128 v[22:25], v140 offset:12352
	ds_read_b128 v[174:177], v140 offset:12416
	ds_read_b128 v[178:181], v140 offset:12480
	s_waitcnt lgkmcnt(1)
	v_mfma_f32_16x16x32_bf16 v[18:21], v[2:5], v[18:21], 0
	s_waitcnt lgkmcnt(0)
	v_mfma_f32_16x16x32_bf16 v[18:21], v[6:9], v[22:25], v[18:21]
	s_nop 0
	s_waitcnt lgkmcnt(0)
	v_mfma_f32_16x16x32_bf16 v[18:21], v[10:13], v[174:177], v[18:21]
	s_nop 0
	s_waitcnt lgkmcnt(0)
	v_mfma_f32_16x16x32_bf16 v[18:21], v[14:17], v[178:181], v[18:21]
	s_and_saveexec_b64 s[0:1], s[12:13]
	s_nop 6
	ds_write_b128 v139, v[18:21] offset:1792
	s_or_b64 exec, exec, s[0:1]
	ds_read2_b32 v[208:209], v142 offset0:160 offset1:164
	ds_read2_b32 v[210:211], v142 offset0:168 offset1:172
	s_waitcnt vmcnt(21)
	ds_write_b128 v143, v[26:29] offset:7168
	s_waitcnt vmcnt(20)
	ds_write_b128 v143, v[30:33] offset:8448
	ds_write_b128 v143, v[46:49] offset:9728
	ds_write_b128 v143, v[58:61] offset:11008
	s_waitcnt vmcnt(19)
	ds_write_b128 v143, v[74:77] offset:12288
	s_waitcnt vmcnt(18)
	ds_write_b128 v143, v[82:85] offset:13568
	s_waitcnt vmcnt(17)
	ds_write_b128 v143, v[98:101] offset:14848
	s_waitcnt vmcnt(16)
	ds_write_b128 v143, v[106:109] offset:16128
	s_nop 0
	s_nop 0
	s_waitcnt lgkmcnt(1)
	v_add_u32_e32 v20, s48, v208
	v_add_u32_e32 v18, s48, v209
	v_ashrrev_i32_e32 v21, 31, v20
	v_ashrrev_i32_e32 v19, 31, v18
	v_lshlrev_b64 v[20:21], 9, v[20:21]
	v_lshlrev_b64 v[18:19], 9, v[18:19]
	v_lshl_add_u64 v[20:21], v[136:137], 0, v[20:21]
	v_lshl_add_u64 v[22:23], v[136:137], 0, v[18:19]
	global_load_dwordx4 v[18:21], v[20:21], off
	s_nop 0
	global_load_dwordx4 v[22:25], v[22:23], off
	ds_read2_b32 v[34:35], v142 offset0:176 offset1:180
	s_waitcnt lgkmcnt(1)
	v_add_u32_e32 v28, s48, v210
	v_add_u32_e32 v26, s48, v211
	v_ashrrev_i32_e32 v29, 31, v28
	v_ashrrev_i32_e32 v27, 31, v26
	v_lshlrev_b64 v[28:29], 9, v[28:29]
	v_lshlrev_b64 v[26:27], 9, v[26:27]
	v_lshl_add_u64 v[28:29], v[136:137], 0, v[28:29]
	v_lshl_add_u64 v[30:31], v[136:137], 0, v[26:27]
	global_load_dwordx4 v[26:29], v[28:29], off
	s_nop 0
	global_load_dwordx4 v[30:33], v[30:31], off
	s_waitcnt lgkmcnt(0)
	v_add_u32_e32 v36, s48, v34
	v_add_u32_e32 v34, s48, v35
	ds_read2_b32 v[62:63], v142 offset0:184 offset1:188
	v_ashrrev_i32_e32 v37, 31, v36
	v_ashrrev_i32_e32 v35, 31, v34
	v_lshlrev_b64 v[36:37], 9, v[36:37]
	v_lshlrev_b64 v[34:35], 9, v[34:35]
	v_lshl_add_u64 v[36:37], v[136:137], 0, v[36:37]
	v_lshl_add_u64 v[38:39], v[136:137], 0, v[34:35]
	global_load_dwordx4 v[34:37], v[36:37], off
	s_nop 0
	global_load_dwordx4 v[38:41], v[38:39], off
	ds_read_b128 v[46:49], v140 offset:7168
	s_waitcnt lgkmcnt(1)
	v_add_u32_e32 v58, s48, v62
	v_ashrrev_i32_e32 v59, 31, v58
	v_lshlrev_b64 v[58:59], 9, v[58:59]
	v_lshl_add_u64 v[82:83], v[136:137], 0, v[58:59]
	ds_read_b128 v[58:61], v140 offset:7232
	s_waitcnt lgkmcnt(1)
	v_mfma_f32_16x16x32_bf16 v[46:49], v[2:5], v[46:49], 0
	v_add_u32_e32 v74, s48, v63
	ds_read_b128 v[62:65], v140 offset:7296
	v_ashrrev_i32_e32 v75, 31, v74
	s_waitcnt lgkmcnt(1)
	v_mfma_f32_16x16x32_bf16 v[46:49], v[6:9], v[58:61], v[46:49]
	v_lshlrev_b64 v[58:59], 9, v[74:75]
	v_lshl_add_u64 v[58:59], v[136:137], 0, v[58:59]
	ds_read_b128 v[74:77], v140 offset:7360
	s_waitcnt lgkmcnt(1)
	v_mfma_f32_16x16x32_bf16 v[62:65], v[10:13], v[62:65], v[46:49]
	s_nop 2
	global_load_dwordx4 v[46:49], v[82:83], off
	s_nop 0
	global_load_dwordx4 v[58:61], v[58:59], off
	s_waitcnt lgkmcnt(0)
	v_mfma_f32_16x16x32_bf16 v[62:65], v[14:17], v[74:77], v[62:65]
	s_and_saveexec_b64 s[0:1], s[12:13]
	s_nop 6
	ds_write_b128 v139, v[62:65] offset:2048
	s_or_b64 exec, exec, s[0:1]
	ds_read_b128 v[62:65], v140 offset:12288
	ds_read_b128 v[74:77], v140 offset:12352
	ds_read_b128 v[174:177], v140 offset:12416
	ds_read_b128 v[178:181], v140 offset:12480
	s_waitcnt lgkmcnt(1)
	v_mfma_f32_16x16x32_bf16 v[62:65], v[2:5], v[62:65], 0
	s_waitcnt lgkmcnt(0)
	v_mfma_f32_16x16x32_bf16 v[62:65], v[6:9], v[74:77], v[62:65]
	s_nop 0
	s_waitcnt lgkmcnt(0)
	v_mfma_f32_16x16x32_bf16 v[62:65], v[10:13], v[174:177], v[62:65]
	s_nop 0
	s_waitcnt lgkmcnt(0)
	v_mfma_f32_16x16x32_bf16 v[62:65], v[14:17], v[178:181], v[62:65]
	s_and_saveexec_b64 s[0:1], s[12:13]
	s_nop 6
	ds_write_b128 v139, v[62:65] offset:2304
	s_or_b64 exec, exec, s[0:1]
	ds_read2_b32 v[208:209], v142 offset0:192 offset1:196
	ds_read2_b32 v[210:211], v142 offset0:200 offset1:204
	s_waitcnt vmcnt(23)
	ds_write_b128 v143, v[42:45] offset:7168
	s_waitcnt vmcnt(22)
	ds_write_b128 v143, v[50:53] offset:8448
	s_waitcnt vmcnt(21)
	ds_write_b128 v143, v[54:57] offset:9728
	s_waitcnt vmcnt(20)
	ds_write_b128 v143, v[66:69] offset:11008
	s_waitcnt vmcnt(19)
	ds_write_b128 v143, v[78:81] offset:12288
	s_waitcnt vmcnt(18)
	ds_write_b128 v143, v[90:93] offset:13568
	s_waitcnt vmcnt(17)
	ds_write_b128 v143, v[102:105] offset:14848
	s_waitcnt vmcnt(16)
	ds_write_b128 v143, v[110:113] offset:16128
	s_nop 0
	s_nop 0
	s_waitcnt lgkmcnt(1)
	v_add_u32_e32 v44, s48, v208
	v_add_u32_e32 v42, s48, v209
	v_ashrrev_i32_e32 v45, 31, v44
	v_ashrrev_i32_e32 v43, 31, v42
	v_lshlrev_b64 v[44:45], 9, v[44:45]
	v_lshlrev_b64 v[42:43], 9, v[42:43]
	v_lshl_add_u64 v[44:45], v[136:137], 0, v[44:45]
	v_lshl_add_u64 v[50:51], v[136:137], 0, v[42:43]
	global_load_dwordx4 v[42:45], v[44:45], off
	s_nop 0
	global_load_dwordx4 v[50:53], v[50:51], off
	ds_read2_b32 v[66:67], v142 offset0:208 offset1:212
	s_waitcnt lgkmcnt(1)
	v_add_u32_e32 v56, s48, v210
	v_add_u32_e32 v54, s48, v211
	v_ashrrev_i32_e32 v57, 31, v56
	v_ashrrev_i32_e32 v55, 31, v54
	v_lshlrev_b64 v[56:57], 9, v[56:57]
	v_lshlrev_b64 v[54:55], 9, v[54:55]
	v_lshl_add_u64 v[56:57], v[136:137], 0, v[56:57]
	v_lshl_add_u64 v[62:63], v[136:137], 0, v[54:55]
	global_load_dwordx4 v[54:57], v[56:57], off
	s_nop 0
	global_load_dwordx4 v[62:65], v[62:63], off
	s_waitcnt lgkmcnt(0)
	v_add_u32_e32 v68, s48, v66
	v_add_u32_e32 v66, s48, v67
	ds_read2_b32 v[90:91], v142 offset0:216 offset1:220
	v_ashrrev_i32_e32 v69, 31, v68
	v_ashrrev_i32_e32 v67, 31, v66
	v_lshlrev_b64 v[68:69], 9, v[68:69]
	v_lshlrev_b64 v[66:67], 9, v[66:67]
	v_lshl_add_u64 v[68:69], v[136:137], 0, v[68:69]
	v_lshl_add_u64 v[74:75], v[136:137], 0, v[66:67]
	global_load_dwordx4 v[66:69], v[68:69], off
	s_nop 0
	global_load_dwordx4 v[74:77], v[74:75], off
	ds_read_b128 v[78:81], v140 offset:7168
	s_waitcnt lgkmcnt(1)
	v_add_u32_e32 v82, s48, v90
	v_ashrrev_i32_e32 v83, 31, v82
	v_lshlrev_b64 v[82:83], 9, v[82:83]
	v_lshl_add_u64 v[102:103], v[136:137], 0, v[82:83]
	ds_read_b128 v[82:85], v140 offset:7232
	s_waitcnt lgkmcnt(1)
	v_mfma_f32_16x16x32_bf16 v[78:81], v[2:5], v[78:81], 0
	v_add_u32_e32 v98, s48, v91
	ds_read_b128 v[90:93], v140 offset:7296
	v_ashrrev_i32_e32 v99, 31, v98
	s_waitcnt lgkmcnt(1)
	v_mfma_f32_16x16x32_bf16 v[78:81], v[6:9], v[82:85], v[78:81]
	v_lshlrev_b64 v[82:83], 9, v[98:99]
	v_lshl_add_u64 v[82:83], v[136:137], 0, v[82:83]
	ds_read_b128 v[98:101], v140 offset:7360
	s_waitcnt lgkmcnt(1)
	v_mfma_f32_16x16x32_bf16 v[90:93], v[10:13], v[90:93], v[78:81]
	s_nop 2
	global_load_dwordx4 v[78:81], v[102:103], off
	s_nop 0
	global_load_dwordx4 v[82:85], v[82:83], off
	s_waitcnt lgkmcnt(0)
	v_mfma_f32_16x16x32_bf16 v[90:93], v[14:17], v[98:101], v[90:93]
	s_and_saveexec_b64 s[0:1], s[12:13]
	s_nop 6
	ds_write_b128 v139, v[90:93] offset:2560
	s_or_b64 exec, exec, s[0:1]
	ds_read_b128 v[90:93], v140 offset:12288
	ds_read_b128 v[98:101], v140 offset:12352
	ds_read_b128 v[174:177], v140 offset:12416
	ds_read_b128 v[178:181], v140 offset:12480
	s_waitcnt lgkmcnt(1)
	v_mfma_f32_16x16x32_bf16 v[90:93], v[2:5], v[90:93], 0
	s_waitcnt lgkmcnt(0)
	v_mfma_f32_16x16x32_bf16 v[90:93], v[6:9], v[98:101], v[90:93]
	s_nop 0
	s_waitcnt lgkmcnt(0)
	v_mfma_f32_16x16x32_bf16 v[90:93], v[10:13], v[174:177], v[90:93]
	s_nop 0
	s_waitcnt lgkmcnt(0)
	v_mfma_f32_16x16x32_bf16 v[90:93], v[14:17], v[178:181], v[90:93]
	s_and_saveexec_b64 s[0:1], s[12:13]
	s_nop 6
	ds_write_b128 v139, v[90:93] offset:2816
	s_or_b64 exec, exec, s[0:1]
	ds_read2_b32 v[208:209], v142 offset0:224 offset1:228
	ds_read2_b32 v[210:211], v142 offset0:232 offset1:236
	ds_read2_b32 v[212:213], v142 offset0:240 offset1:244
	ds_read2_b32 v[214:215], v142 offset0:248 offset1:252
	s_waitcnt vmcnt(23)
	ds_write_b128 v143, v[70:73] offset:7168
	s_waitcnt vmcnt(22)
	ds_write_b128 v143, v[86:89] offset:8448
	s_waitcnt vmcnt(21)
	ds_write_b128 v143, v[94:97] offset:9728
	s_waitcnt vmcnt(20)
	ds_write_b128 v143, v[114:117] offset:11008
	s_waitcnt vmcnt(19)
	ds_write_b128 v143, v[118:121] offset:12288
	s_waitcnt vmcnt(18)
	ds_write_b128 v143, v[122:125] offset:13568
	s_waitcnt vmcnt(17)
	ds_write_b128 v143, v[126:129] offset:14848
	s_waitcnt vmcnt(16)
	ds_write_b128 v143, v[130:133] offset:16128
	s_nop 0
	s_nop 0
	s_nop 0
	s_nop 0
	ds_read_b128 v[114:117], v140 offset:7168
	ds_read_b128 v[118:121], v140 offset:7232
	ds_read_b128 v[174:177], v140 offset:7296
	ds_read_b128 v[178:181], v140 offset:7360
	s_waitcnt lgkmcnt(5)
	v_add_u32_e32 v70, s48, v208
	v_add_u32_e32 v86, s48, v209
	s_waitcnt lgkmcnt(4)
	v_add_u32_e32 v90, s48, v210
	v_add_u32_e32 v94, s48, v211
	s_waitcnt lgkmcnt(3)
	v_add_u32_e32 v98, s48, v212
	v_add_u32_e32 v102, s48, v213
	s_waitcnt lgkmcnt(2)
	v_add_u32_e32 v106, s48, v214
	v_add_u32_e32 v110, s48, v215
	v_ashrrev_i32_e32 v71, 31, v70
	v_ashrrev_i32_e32 v87, 31, v86
	v_ashrrev_i32_e32 v91, 31, v90
	v_ashrrev_i32_e32 v95, 31, v94
	v_ashrrev_i32_e32 v99, 31, v98
	v_ashrrev_i32_e32 v103, 31, v102
	v_ashrrev_i32_e32 v107, 31, v106
	v_ashrrev_i32_e32 v111, 31, v110
	v_lshlrev_b64 v[70:71], 9, v[70:71]
	v_lshlrev_b64 v[86:87], 9, v[86:87]
	v_lshlrev_b64 v[90:91], 9, v[90:91]
	v_lshlrev_b64 v[94:95], 9, v[94:95]
	v_lshlrev_b64 v[98:99], 9, v[98:99]
	v_lshlrev_b64 v[102:103], 9, v[102:103]
	v_lshlrev_b64 v[106:107], 9, v[106:107]
	v_lshlrev_b64 v[110:111], 9, v[110:111]
	v_lshl_add_u64 v[70:71], v[136:137], 0, v[70:71]
	v_lshl_add_u64 v[86:87], v[136:137], 0, v[86:87]
	v_lshl_add_u64 v[90:91], v[136:137], 0, v[90:91]
	v_lshl_add_u64 v[94:95], v[136:137], 0, v[94:95]
	v_lshl_add_u64 v[98:99], v[136:137], 0, v[98:99]
	v_lshl_add_u64 v[102:103], v[136:137], 0, v[102:103]
	v_lshl_add_u64 v[106:107], v[136:137], 0, v[106:107]
	v_lshl_add_u64 v[110:111], v[136:137], 0, v[110:111]
	global_load_dwordx4 v[70:73], v[70:71], off
	s_waitcnt lgkmcnt(1)
	v_mfma_f32_16x16x32_bf16 v[114:117], v[2:5], v[114:117], 0
	global_load_dwordx4 v[86:89], v[86:87], off
	s_nop 0
	global_load_dwordx4 v[90:93], v[90:91], off
	s_waitcnt lgkmcnt(0)
	v_mfma_f32_16x16x32_bf16 v[114:117], v[6:9], v[118:121], v[114:117]
	global_load_dwordx4 v[94:97], v[94:95], off
	s_nop 0
	global_load_dwordx4 v[98:101], v[98:99], off
	s_waitcnt lgkmcnt(0)
	v_mfma_f32_16x16x32_bf16 v[114:117], v[10:13], v[174:177], v[114:117]
	global_load_dwordx4 v[102:105], v[102:103], off
	s_nop 0
	global_load_dwordx4 v[106:109], v[106:107], off
	s_waitcnt lgkmcnt(0)
	v_mfma_f32_16x16x32_bf16 v[114:117], v[14:17], v[178:181], v[114:117]
	global_load_dwordx4 v[110:113], v[110:111], off
	s_and_saveexec_b64 s[0:1], s[12:13]
	s_nop 5
	ds_write_b128 v139, v[114:117] offset:3072
	s_or_b64 exec, exec, s[0:1]
	ds_read_b128 v[114:117], v140 offset:12288
	ds_read_b128 v[118:121], v140 offset:12352
	ds_read_b128 v[174:177], v140 offset:12416
	ds_read_b128 v[178:181], v140 offset:12480
	s_waitcnt lgkmcnt(1)
	v_mfma_f32_16x16x32_bf16 v[114:117], v[2:5], v[114:117], 0
	s_waitcnt lgkmcnt(0)
	v_mfma_f32_16x16x32_bf16 v[114:117], v[6:9], v[118:121], v[114:117]
	s_nop 0
	s_waitcnt lgkmcnt(0)
	v_mfma_f32_16x16x32_bf16 v[114:117], v[10:13], v[174:177], v[114:117]
	s_nop 0
	s_waitcnt lgkmcnt(0)
	v_mfma_f32_16x16x32_bf16 v[114:117], v[14:17], v[178:181], v[114:117]
	s_and_saveexec_b64 s[0:1], s[12:13]
	s_nop 6
	ds_write_b128 v139, v[114:117] offset:3328
	s_or_b64 exec, exec, s[0:1]
	s_waitcnt vmcnt(23)
	ds_write_b128 v143, v[18:21] offset:7168
	s_waitcnt vmcnt(22)
	ds_write_b128 v143, v[22:25] offset:8448
	s_waitcnt vmcnt(21)
	ds_write_b128 v143, v[26:29] offset:9728
	s_waitcnt vmcnt(20)
	ds_write_b128 v143, v[30:33] offset:11008
	s_waitcnt vmcnt(19)
	ds_write_b128 v143, v[34:37] offset:12288
	s_waitcnt vmcnt(18)
	ds_write_b128 v143, v[38:41] offset:13568
	s_waitcnt vmcnt(17)
	ds_write_b128 v143, v[46:49] offset:14848
	s_waitcnt vmcnt(16)
	ds_write_b128 v143, v[58:61] offset:16128
	ds_read_b128 v[18:21], v140 offset:7168
	ds_read_b128 v[22:25], v140 offset:7232
	s_waitcnt lgkmcnt(1)
	v_mfma_f32_16x16x32_bf16 v[18:21], v[2:5], v[18:21], 0
	s_waitcnt lgkmcnt(0)
	v_mfma_f32_16x16x32_bf16 v[18:21], v[6:9], v[22:25], v[18:21]
	ds_read_b128 v[22:25], v140 offset:7296
	ds_read_b128 v[26:29], v140 offset:7360
	s_waitcnt lgkmcnt(1)
	v_mfma_f32_16x16x32_bf16 v[18:21], v[10:13], v[22:25], v[18:21]
	s_waitcnt lgkmcnt(0)
	v_mfma_f32_16x16x32_bf16 v[18:21], v[14:17], v[26:29], v[18:21]
	s_and_saveexec_b64 s[0:1], s[12:13]
	s_nop 6
	ds_write_b128 v139, v[18:21] offset:3584
	s_or_b64 exec, exec, s[0:1]
	ds_read_b128 v[18:21], v140 offset:12288
	ds_read_b128 v[22:25], v140 offset:12352
	ds_read_b128 v[174:177], v140 offset:12416
	ds_read_b128 v[178:181], v140 offset:12480
	s_waitcnt lgkmcnt(1)
	v_mfma_f32_16x16x32_bf16 v[18:21], v[2:5], v[18:21], 0
	s_waitcnt lgkmcnt(0)
	v_mfma_f32_16x16x32_bf16 v[18:21], v[6:9], v[22:25], v[18:21]
	s_nop 0
	s_waitcnt lgkmcnt(0)
	v_mfma_f32_16x16x32_bf16 v[18:21], v[10:13], v[174:177], v[18:21]
	s_nop 0
	s_waitcnt lgkmcnt(0)
	v_mfma_f32_16x16x32_bf16 v[18:21], v[14:17], v[178:181], v[18:21]
	s_and_saveexec_b64 s[0:1], s[12:13]
	s_nop 6
	ds_write_b128 v139, v[18:21] offset:3840
	s_or_b64 exec, exec, s[0:1]
	s_waitcnt vmcnt(15)
	ds_write_b128 v143, v[42:45] offset:7168
	s_waitcnt vmcnt(14)
	ds_write_b128 v143, v[50:53] offset:8448
	s_waitcnt vmcnt(13)
	ds_write_b128 v143, v[54:57] offset:9728
	s_waitcnt vmcnt(12)
	ds_write_b128 v143, v[62:65] offset:11008
	s_waitcnt vmcnt(11)
	ds_write_b128 v143, v[66:69] offset:12288
	s_waitcnt vmcnt(10)
	ds_write_b128 v143, v[74:77] offset:13568
	s_waitcnt vmcnt(9)
	ds_write_b128 v143, v[78:81] offset:14848
	s_waitcnt vmcnt(8)
	ds_write_b128 v143, v[82:85] offset:16128
	ds_read_b128 v[18:21], v140 offset:7168
	ds_read_b128 v[22:25], v140 offset:7232
	s_waitcnt lgkmcnt(1)
	v_mfma_f32_16x16x32_bf16 v[18:21], v[2:5], v[18:21], 0
	s_waitcnt lgkmcnt(0)
	v_mfma_f32_16x16x32_bf16 v[18:21], v[6:9], v[22:25], v[18:21]
	ds_read_b128 v[22:25], v140 offset:7296
	ds_read_b128 v[26:29], v140 offset:7360
	s_waitcnt lgkmcnt(1)
	v_mfma_f32_16x16x32_bf16 v[18:21], v[10:13], v[22:25], v[18:21]
	s_waitcnt lgkmcnt(0)
	v_mfma_f32_16x16x32_bf16 v[18:21], v[14:17], v[26:29], v[18:21]
	s_and_saveexec_b64 s[0:1], s[12:13]
	s_nop 6
	ds_write_b128 v139, v[18:21] offset:4096
	s_or_b64 exec, exec, s[0:1]
	ds_read_b128 v[18:21], v140 offset:12288
	ds_read_b128 v[22:25], v140 offset:12352
	ds_read_b128 v[174:177], v140 offset:12416
	ds_read_b128 v[178:181], v140 offset:12480
	s_waitcnt lgkmcnt(1)
	v_mfma_f32_16x16x32_bf16 v[18:21], v[2:5], v[18:21], 0
	s_waitcnt lgkmcnt(0)
	v_mfma_f32_16x16x32_bf16 v[18:21], v[6:9], v[22:25], v[18:21]
	s_nop 0
	s_waitcnt lgkmcnt(0)
	v_mfma_f32_16x16x32_bf16 v[18:21], v[10:13], v[174:177], v[18:21]
	s_nop 0
	s_waitcnt lgkmcnt(0)
	v_mfma_f32_16x16x32_bf16 v[18:21], v[14:17], v[178:181], v[18:21]
	s_and_saveexec_b64 s[0:1], s[12:13]
	s_nop 6
	ds_write_b128 v139, v[18:21] offset:4352
	s_or_b64 exec, exec, s[0:1]
	s_waitcnt vmcnt(7)
	ds_write_b128 v143, v[70:73] offset:7168
	s_waitcnt vmcnt(6)
	ds_write_b128 v143, v[86:89] offset:8448
	s_waitcnt vmcnt(5)
	ds_write_b128 v143, v[90:93] offset:9728
	s_waitcnt vmcnt(4)
	ds_write_b128 v143, v[94:97] offset:11008
	s_waitcnt vmcnt(3)
	ds_write_b128 v143, v[98:101] offset:12288
	s_waitcnt vmcnt(2)
	ds_write_b128 v143, v[102:105] offset:13568
	s_waitcnt vmcnt(1)
	ds_write_b128 v143, v[106:109] offset:14848
	s_waitcnt vmcnt(0)
	ds_write_b128 v143, v[110:113] offset:16128
	ds_read_b128 v[18:21], v140 offset:7168
	ds_read_b128 v[22:25], v140 offset:7232
	s_waitcnt lgkmcnt(1)
	v_mfma_f32_16x16x32_bf16 v[18:21], v[2:5], v[18:21], 0
	s_waitcnt lgkmcnt(0)
	v_mfma_f32_16x16x32_bf16 v[18:21], v[6:9], v[22:25], v[18:21]
	ds_read_b128 v[22:25], v140 offset:7296
	ds_read_b128 v[26:29], v140 offset:7360
	s_waitcnt lgkmcnt(1)
	v_mfma_f32_16x16x32_bf16 v[18:21], v[10:13], v[22:25], v[18:21]
	s_waitcnt lgkmcnt(0)
	v_mfma_f32_16x16x32_bf16 v[18:21], v[14:17], v[26:29], v[18:21]
	s_and_saveexec_b64 s[0:1], s[12:13]
	s_nop 6
	ds_write_b128 v139, v[18:21] offset:4608
	s_or_b64 exec, exec, s[0:1]
	ds_read_b128 v[18:21], v140 offset:12288
	s_waitcnt lgkmcnt(0)
	v_mfma_f32_16x16x32_bf16 v[2:5], v[2:5], v[18:21], 0
	ds_read_b128 v[18:21], v140 offset:12352
	s_waitcnt lgkmcnt(0)
	v_mfma_f32_16x16x32_bf16 v[2:5], v[6:9], v[18:21], v[2:5]
	ds_read_b128 v[6:9], v140 offset:12416
	s_waitcnt lgkmcnt(0)
	v_mfma_f32_16x16x32_bf16 v[2:5], v[10:13], v[6:9], v[2:5]
	ds_read_b128 v[6:9], v140 offset:12480
	s_waitcnt lgkmcnt(0)
	v_mfma_f32_16x16x32_bf16 v[2:5], v[14:17], v[6:9], v[2:5]
	s_and_saveexec_b64 s[0:1], s[12:13]
	s_nop 6
	ds_write_b128 v139, v[2:5] offset:4864
	s_or_b64 exec, exec, s[0:1]
	ds_read2_b32 v[2:3], v142 offset1:4
	s_lshl_b32 s0, s4, 7
	s_lshl_b32 s0, s0, 1
	v_lshlrev_b32_e32 v4, 3, v1
	s_add_u32 s0, s60, s0
	s_addc_u32 s1, s61, 0
	v_lshlrev_b32_e32 v4, 1, v4
	v_mov_b32_e32 v5, v135
	v_lshl_add_u64 v[130:131], s[0:1], 0, v[4:5]
	ds_read2_b32 v[4:5], v142 offset0:8 offset1:12
	s_waitcnt lgkmcnt(1)
	v_add_u32_e32 v6, s48, v2
	v_ashrrev_i32_e32 v7, 31, v6
	v_add_u32_e32 v2, s48, v3
	v_lshlrev_b64 v[6:7], 9, v[6:7]
	v_ashrrev_i32_e32 v3, 31, v2
	v_lshl_add_u64 v[6:7], v[130:131], 0, v[6:7]
	v_lshlrev_b64 v[2:3], 9, v[2:3]
	v_lshl_add_u64 v[2:3], v[130:131], 0, v[2:3]
	global_load_dwordx4 v[10:13], v[6:7], off
	global_load_dwordx4 v[18:21], v[2:3], off
	ds_read2_b32 v[6:7], v142 offset0:16 offset1:20
	s_waitcnt lgkmcnt(1)
	v_add_u32_e32 v2, s48, v4
	v_add_u32_e32 v4, s48, v5
	v_ashrrev_i32_e32 v3, 31, v2
	v_ashrrev_i32_e32 v5, 31, v4
	v_lshlrev_b64 v[2:3], 9, v[2:3]
	v_lshlrev_b64 v[4:5], 9, v[4:5]
	v_lshl_add_u64 v[2:3], v[130:131], 0, v[2:3]
	v_lshl_add_u64 v[4:5], v[130:131], 0, v[4:5]
	global_load_dwordx4 v[30:33], v[2:3], off
	global_load_dwordx4 v[38:41], v[4:5], off
	s_waitcnt lgkmcnt(0)
	v_add_u32_e32 v2, s48, v6
	v_add_u32_e32 v4, s48, v7
	ds_read2_b32 v[6:7], v142 offset0:24 offset1:28
	v_ashrrev_i32_e32 v3, 31, v2
	v_lshlrev_b64 v[2:3], 9, v[2:3]
	v_ashrrev_i32_e32 v5, 31, v4
	v_lshl_add_u64 v[2:3], v[130:131], 0, v[2:3]
	v_lshlrev_b64 v[4:5], 9, v[4:5]
	v_lshl_add_u64 v[4:5], v[130:131], 0, v[4:5]
	global_load_dwordx4 v[50:53], v[2:3], off
	global_load_dwordx4 v[54:57], v[4:5], off
	s_waitcnt lgkmcnt(0)
	v_add_u32_e32 v2, s48, v6
	v_ashrrev_i32_e32 v3, 31, v2
	v_add_u32_e32 v4, s48, v7
	v_lshlrev_b64 v[2:3], 9, v[2:3]
	v_ashrrev_i32_e32 v5, 31, v4
	v_lshl_add_u64 v[2:3], v[130:131], 0, v[2:3]
	v_lshlrev_b64 v[4:5], 9, v[4:5]
	v_lshl_add_u64 v[4:5], v[130:131], 0, v[4:5]
	global_load_dwordx4 v[58:61], v[2:3], off
	global_load_dwordx4 v[62:65], v[4:5], off
	v_cndmask_b32_e64 v2, 0, 1, s[6:7]
	v_cmp_ne_u32_e64 s[16:17], 1, v2
	s_andn2_b64 vcc, exec, s[6:7]
	s_cbranch_vccnz .LBB0_2593
	ds_read2_b32 v[2:3], v142 offset0:32 offset1:36
	ds_read2_b32 v[14:15], v142 offset0:40 offset1:44
	s_waitcnt lgkmcnt(1)
	v_add_u32_e32 v2, s48, v2
	v_add_u32_e32 v4, s48, v3
	s_waitcnt lgkmcnt(0)
	v_add_u32_e32 v16, s48, v14
	v_add_u32_e32 v14, s48, v15
	v_ashrrev_i32_e32 v3, 31, v2
	v_ashrrev_i32_e32 v5, 31, v4
	v_ashrrev_i32_e32 v17, 31, v16
	v_ashrrev_i32_e32 v15, 31, v14
	v_lshlrev_b64 v[2:3], 9, v[2:3]
	v_lshlrev_b64 v[4:5], 9, v[4:5]
	v_lshlrev_b64 v[16:17], 9, v[16:17]
	v_lshlrev_b64 v[14:15], 9, v[14:15]
	v_lshl_add_u64 v[2:3], v[130:131], 0, v[2:3]
	v_lshl_add_u64 v[6:7], v[130:131], 0, v[4:5]
	v_lshl_add_u64 v[16:17], v[130:131], 0, v[16:17]
	v_lshl_add_u64 v[22:23], v[130:131], 0, v[14:15]
	global_load_dwordx4 v[2:5], v[2:3], off
	s_nop 0
	global_load_dwordx4 v[6:9], v[6:7], off
	ds_read2_b32 v[26:27], v142 offset0:48 offset1:52
	global_load_dwordx4 v[14:17], v[16:17], off
	s_nop 0
	global_load_dwordx4 v[22:25], v[22:23], off
	ds_read2_b32 v[42:43], v142 offset0:56 offset1:60
	s_waitcnt lgkmcnt(1)
	v_add_u32_e32 v28, s48, v26
	v_add_u32_e32 v26, s48, v27
	s_waitcnt lgkmcnt(0)
	v_add_u32_e32 v44, s48, v42
	v_add_u32_e32 v42, s48, v43
	v_ashrrev_i32_e32 v29, 31, v28
	v_ashrrev_i32_e32 v27, 31, v26
	v_ashrrev_i32_e32 v45, 31, v44
	v_ashrrev_i32_e32 v43, 31, v42
	v_lshlrev_b64 v[28:29], 9, v[28:29]
	v_lshlrev_b64 v[26:27], 9, v[26:27]
	v_lshlrev_b64 v[44:45], 9, v[44:45]
	v_lshlrev_b64 v[42:43], 9, v[42:43]
	v_lshl_add_u64 v[28:29], v[130:131], 0, v[28:29]
	v_lshl_add_u64 v[34:35], v[130:131], 0, v[26:27]
	v_lshl_add_u64 v[44:45], v[130:131], 0, v[44:45]
	v_lshl_add_u64 v[46:47], v[130:131], 0, v[42:43]
	global_load_dwordx4 v[26:29], v[28:29], off
	s_nop 0
	global_load_dwordx4 v[34:37], v[34:35], off
	s_nop 0
	global_load_dwordx4 v[42:45], v[44:45], off
	s_nop 0
	global_load_dwordx4 v[46:49], v[46:47], off

.LBB0_2629:
	v_lshl_add_u32 v98, v144, 9, v138
	v_lshlrev_b32_e32 v102, 3, v145
	v_add_u32_e32 v145, v98, v134
	ds_read_b128 v[98:101], v145 offset:5120
	v_lshrrev_b32_e32 v103, 2, v1
	v_or_b32_e32 v102, v102, v103
	v_mul_u32_u24_e32 v102, 0x140, v102
	v_lshlrev_b32_e32 v103, 3, v144
	v_add3_u32 v134, v138, v102, v103
	s_waitcnt lgkmcnt(0)
	v_cndmask_b32_e64 v113, v101, 0, s[10:11]
	v_cndmask_b32_e64 v112, v100, 0, s[10:11]
	v_cndmask_b32_e64 v111, v99, 0, s[10:11]
	v_cndmask_b32_e64 v110, v98, 0, s[10:11]
	ds_read_b64_tr_b16 v[100:101], v134 offset:8448
	ds_read_b64_tr_b16 v[98:99], v134 offset:7168
	ds_read_b64_tr_b16 v[102:103], v134 offset:7200
	ds_read_b64_tr_b16 v[114:115], v134 offset:7232
	ds_read_b64_tr_b16 v[118:119], v134 offset:7264
	ds_read_b64_tr_b16 v[104:105], v134 offset:8480
	ds_read_b64_tr_b16 v[116:117], v134 offset:8512
	ds_read_b64_tr_b16 v[120:121], v134 offset:8544
	s_waitcnt lgkmcnt(6)
	v_mfma_f32_16x16x32_bf16 v[122:125], v[110:113], v[98:101], 0
	v_cndmask_b32_e64 v144, 0, 1, s[28:29]
	s_and_b64 vcc, exec, s[16:17]
	v_cmp_ne_u32_e64 s[0:1], 1, v144
	s_waitcnt lgkmcnt(2)
	v_mfma_f32_16x16x32_bf16 v[106:109], v[110:113], v[102:105], 0
	s_waitcnt lgkmcnt(1)
	v_mfma_f32_16x16x32_bf16 v[102:105], v[110:113], v[114:117], 0
	s_waitcnt lgkmcnt(0)
	v_mfma_f32_16x16x32_bf16 v[98:101], v[110:113], v[118:121], 0
	ds_read_b64_tr_b16 v[116:117], v134 offset:8576
	ds_read_b64_tr_b16 v[114:115], v134 offset:7296
	ds_read_b64_tr_b16 v[118:119], v134 offset:7328
	ds_read_b64_tr_b16 v[146:147], v134 offset:7360
	ds_read_b64_tr_b16 v[150:151], v134 offset:7392
	ds_read_b64_tr_b16 v[120:121], v134 offset:8608
	ds_read_b64_tr_b16 v[148:149], v134 offset:8640
	ds_read_b64_tr_b16 v[152:153], v134 offset:8672
	s_waitcnt lgkmcnt(6)
	v_mfma_f32_16x16x32_bf16 v[126:129], v[110:113], v[114:117], 0
	s_waitcnt lgkmcnt(2)
	v_mfma_f32_16x16x32_bf16 v[118:121], v[110:113], v[118:121], 0
	s_waitcnt lgkmcnt(1)
	v_mfma_f32_16x16x32_bf16 v[114:117], v[110:113], v[146:149], 0
	s_waitcnt lgkmcnt(0)
	v_mfma_f32_16x16x32_bf16 v[110:113], v[110:113], v[150:153], 0
	s_cbranch_vccnz .LBB0_2633
	ds_read2_b32 v[208:209], v142 offset0:128 offset1:132
	ds_read2_b32 v[210:211], v142 offset0:136 offset1:140
	ds_write_b128 v143, v[2:5] offset:7168
	ds_write_b128 v143, v[6:9] offset:8448
	ds_write_b128 v143, v[14:17] offset:9728
	ds_write_b128 v143, v[22:25] offset:11008
	ds_write_b128 v143, v[26:29] offset:12288
	ds_write_b128 v143, v[34:37] offset:13568
	ds_write_b128 v143, v[42:45] offset:14848
	ds_write_b128 v143, v[46:49] offset:16128
	s_and_b64 vcc, exec, s[0:1]
	s_cbranch_vccnz .LBB0_2632
	s_nop 0
	s_nop 0
	s_waitcnt lgkmcnt(1)
	v_add_u32_e32 v2, s48, v208
	v_add_u32_e32 v4, s48, v209
	s_waitcnt lgkmcnt(0)
	v_add_u32_e32 v16, s48, v210
	v_add_u32_e32 v14, s48, v211
	v_ashrrev_i32_e32 v3, 31, v2
	v_ashrrev_i32_e32 v5, 31, v4
	v_ashrrev_i32_e32 v17, 31, v16
	v_ashrrev_i32_e32 v15, 31, v14
	v_lshlrev_b64 v[2:3], 9, v[2:3]
	v_lshlrev_b64 v[4:5], 9, v[4:5]
	v_lshlrev_b64 v[16:17], 9, v[16:17]
	v_lshlrev_b64 v[14:15], 9, v[14:15]
	v_lshl_add_u64 v[2:3], v[130:131], 0, v[2:3]
	v_lshl_add_u64 v[6:7], v[130:131], 0, v[4:5]
	v_lshl_add_u64 v[16:17], v[130:131], 0, v[16:17]
	v_lshl_add_u64 v[22:23], v[130:131], 0, v[14:15]
	global_load_dwordx4 v[2:5], v[2:3], off
	s_nop 0
	global_load_dwordx4 v[6:9], v[6:7], off
	ds_read2_b32 v[26:27], v142 offset0:144 offset1:148
	global_load_dwordx4 v[14:17], v[16:17], off
	s_nop 0
	global_load_dwordx4 v[22:25], v[22:23], off
	ds_read2_b32 v[42:43], v142 offset0:152 offset1:156
	s_waitcnt lgkmcnt(1)
	v_add_u32_e32 v28, s48, v26
	v_add_u32_e32 v26, s48, v27
	s_waitcnt lgkmcnt(0)
	v_add_u32_e32 v44, s48, v42
	v_add_u32_e32 v42, s48, v43
	v_ashrrev_i32_e32 v29, 31, v28
	v_ashrrev_i32_e32 v27, 31, v26
	v_ashrrev_i32_e32 v45, 31, v44
	v_ashrrev_i32_e32 v43, 31, v42
	v_lshlrev_b64 v[28:29], 9, v[28:29]
	v_lshlrev_b64 v[26:27], 9, v[26:27]
	v_lshlrev_b64 v[44:45], 9, v[44:45]
	v_lshlrev_b64 v[42:43], 9, v[42:43]
	v_lshl_add_u64 v[28:29], v[130:131], 0, v[28:29]
	v_lshl_add_u64 v[34:35], v[130:131], 0, v[26:27]
	v_lshl_add_u64 v[44:45], v[130:131], 0, v[44:45]
	v_lshl_add_u64 v[46:47], v[130:131], 0, v[42:43]
	global_load_dwordx4 v[26:29], v[28:29], off
	s_nop 0
	global_load_dwordx4 v[34:37], v[34:35], off
	s_nop 0
	global_load_dwordx4 v[42:45], v[44:45], off
	s_nop 0
	global_load_dwordx4 v[46:49], v[46:47], off
.LBB0_2632:
	ds_read_b128 v[146:149], v145 offset:5184
	ds_read_b64_tr_b16 v[152:153], v134 offset:8448
	ds_read_b64_tr_b16 v[150:151], v134 offset:7168
	ds_read_b64_tr_b16 v[154:155], v134 offset:7200
	ds_read_b64_tr_b16 v[156:157], v134 offset:8480
	s_waitcnt lgkmcnt(4)
	v_cndmask_b32_e64 v149, v149, 0, s[10:11]
	v_cndmask_b32_e64 v148, v148, 0, s[10:11]
	v_cndmask_b32_e64 v147, v147, 0, s[10:11]
	v_cndmask_b32_e64 v146, v146, 0, s[10:11]
	ds_read_b64_tr_b16 v[184:185], v134 offset:7232
	ds_read_b64_tr_b16 v[186:187], v134 offset:8512
	ds_read_b64_tr_b16 v[188:189], v134 offset:7264
	ds_read_b64_tr_b16 v[190:191], v134 offset:8544
	ds_read_b64_tr_b16 v[192:193], v134 offset:7296
	ds_read_b64_tr_b16 v[194:195], v134 offset:8576
	ds_read_b64_tr_b16 v[196:197], v134 offset:7328
	ds_read_b64_tr_b16 v[198:199], v134 offset:8608
	s_waitcnt lgkmcnt(10)
	s_nop 0
	v_mfma_f32_16x16x32_bf16 v[122:125], v[146:149], v[150:153], v[122:125]
	ds_read_b64_tr_b16 v[200:201], v134 offset:7360
	ds_read_b64_tr_b16 v[202:203], v134 offset:8640
	ds_read_b64_tr_b16 v[204:205], v134 offset:7392
	ds_read_b64_tr_b16 v[206:207], v134 offset:8672
	s_nop 0
	s_nop 0
	s_waitcnt lgkmcnt(10)
	v_mfma_f32_16x16x32_bf16 v[102:105], v[146:149], v[184:187], v[102:105]
	s_nop 0
	s_nop 0
	s_waitcnt lgkmcnt(8)
	v_mfma_f32_16x16x32_bf16 v[98:101], v[146:149], v[188:191], v[98:101]
	s_nop 0
	s_nop 0
	s_waitcnt lgkmcnt(6)
	v_mfma_f32_16x16x32_bf16 v[126:129], v[146:149], v[192:195], v[126:129]
	s_nop 0
	s_nop 0
	s_waitcnt lgkmcnt(4)
	v_mfma_f32_16x16x32_bf16 v[118:121], v[146:149], v[196:199], v[118:121]
	s_nop 0
	s_nop 0
	s_waitcnt lgkmcnt(2)
	v_mfma_f32_16x16x32_bf16 v[114:117], v[146:149], v[200:203], v[114:117]
	s_nop 0
	s_nop 0
	v_mfma_f32_16x16x32_bf16 v[106:109], v[146:149], v[154:157], v[106:109]
	s_waitcnt lgkmcnt(0)
	v_mfma_f32_16x16x32_bf16 v[110:113], v[146:149], v[204:207], v[110:113]

.LBB0_2640:
	ds_read2_b32 v[208:209], v142 offset0:160 offset1:164
	ds_read2_b32 v[210:211], v142 offset0:168 offset1:172
	ds_write_b128 v143, v[70:73] offset:7168
	ds_write_b128 v143, v[66:69] offset:8448
	ds_write_b128 v143, v[78:81] offset:9728
	ds_write_b128 v143, v[74:77] offset:11008
	ds_write_b128 v143, v[86:89] offset:12288
	ds_write_b128 v143, v[82:85] offset:13568
	ds_write_b128 v143, v[94:97] offset:14848
	ds_write_b128 v143, v[90:93] offset:16128
	s_and_b64 vcc, exec, s[2:3]
	s_cbranch_vccnz .LBB0_2642
	s_nop 0
	s_nop 0
	s_waitcnt lgkmcnt(1)
	v_add_u32_e32 v66, s48, v208
	v_add_u32_e32 v68, s48, v209
	s_waitcnt lgkmcnt(0)
	v_add_u32_e32 v76, s48, v210
	v_add_u32_e32 v74, s48, v211
	v_ashrrev_i32_e32 v67, 31, v66
	v_ashrrev_i32_e32 v69, 31, v68
	v_ashrrev_i32_e32 v77, 31, v76
	v_ashrrev_i32_e32 v75, 31, v74
	v_lshlrev_b64 v[66:67], 9, v[66:67]
	v_lshlrev_b64 v[68:69], 9, v[68:69]
	v_lshlrev_b64 v[76:77], 9, v[76:77]
	v_lshlrev_b64 v[74:75], 9, v[74:75]
	v_lshl_add_u64 v[66:67], v[130:131], 0, v[66:67]
	v_lshl_add_u64 v[68:69], v[130:131], 0, v[68:69]
	v_lshl_add_u64 v[76:77], v[130:131], 0, v[76:77]
	v_lshl_add_u64 v[74:75], v[130:131], 0, v[74:75]
	global_load_dwordx4 v[70:73], v[66:67], off
	s_nop 0
	global_load_dwordx4 v[66:69], v[68:69], off
	ds_read2_b32 v[82:83], v142 offset0:176 offset1:180
	global_load_dwordx4 v[78:81], v[76:77], off
	s_nop 0
	global_load_dwordx4 v[74:77], v[74:75], off
	ds_read2_b32 v[90:91], v142 offset0:184 offset1:188
	s_waitcnt lgkmcnt(1)
	v_add_u32_e32 v84, s48, v82
	v_add_u32_e32 v82, s48, v83
	s_waitcnt lgkmcnt(0)
	v_add_u32_e32 v92, s48, v90
	v_add_u32_e32 v90, s48, v91
	v_ashrrev_i32_e32 v85, 31, v84
	v_ashrrev_i32_e32 v83, 31, v82
	v_ashrrev_i32_e32 v93, 31, v92
	v_ashrrev_i32_e32 v91, 31, v90
	v_lshlrev_b64 v[84:85], 9, v[84:85]
	v_lshlrev_b64 v[82:83], 9, v[82:83]
	v_lshlrev_b64 v[92:93], 9, v[92:93]
	v_lshlrev_b64 v[90:91], 9, v[90:91]
	v_lshl_add_u64 v[84:85], v[130:131], 0, v[84:85]
	v_lshl_add_u64 v[82:83], v[130:131], 0, v[82:83]
	v_lshl_add_u64 v[92:93], v[130:131], 0, v[92:93]
	v_lshl_add_u64 v[90:91], v[130:131], 0, v[90:91]
	global_load_dwordx4 v[86:89], v[84:85], off
	s_nop 0
	global_load_dwordx4 v[82:85], v[82:83], off
	s_nop 0
	global_load_dwordx4 v[94:97], v[92:93], off
	s_nop 0
	global_load_dwordx4 v[90:93], v[90:91], off
.LBB0_2642:
	ds_read_b128 v[146:149], v145 offset:5248
	ds_read_b64_tr_b16 v[152:153], v134 offset:8448
	ds_read_b64_tr_b16 v[150:151], v134 offset:7168
	ds_read_b64_tr_b16 v[154:155], v134 offset:7200
	ds_read_b64_tr_b16 v[156:157], v134 offset:8480
	s_waitcnt lgkmcnt(4)
	v_cndmask_b32_e64 v149, v149, 0, s[10:11]
	v_cndmask_b32_e64 v148, v148, 0, s[10:11]
	v_cndmask_b32_e64 v147, v147, 0, s[10:11]
	v_cndmask_b32_e64 v146, v146, 0, s[10:11]
	ds_read_b64_tr_b16 v[184:185], v134 offset:7232
	ds_read_b64_tr_b16 v[186:187], v134 offset:8512
	ds_read_b64_tr_b16 v[188:189], v134 offset:7264
	ds_read_b64_tr_b16 v[190:191], v134 offset:8544
	ds_read_b64_tr_b16 v[192:193], v134 offset:7296
	ds_read_b64_tr_b16 v[194:195], v134 offset:8576
	ds_read_b64_tr_b16 v[196:197], v134 offset:7328
	ds_read_b64_tr_b16 v[198:199], v134 offset:8608
	s_waitcnt lgkmcnt(10)
	s_nop 0
	v_mfma_f32_16x16x32_bf16 v[122:125], v[146:149], v[150:153], v[122:125]
	ds_read_b64_tr_b16 v[200:201], v134 offset:7360
	ds_read_b64_tr_b16 v[202:203], v134 offset:8640
	ds_read_b64_tr_b16 v[204:205], v134 offset:7392
	ds_read_b64_tr_b16 v[206:207], v134 offset:8672
	s_nop 0
	s_nop 0
	s_waitcnt lgkmcnt(10)
	v_mfma_f32_16x16x32_bf16 v[102:105], v[146:149], v[184:187], v[102:105]
	s_nop 0
	s_nop 0
	s_waitcnt lgkmcnt(8)
	v_mfma_f32_16x16x32_bf16 v[98:101], v[146:149], v[188:191], v[98:101]
	s_nop 0
	s_nop 0
	s_waitcnt lgkmcnt(6)
	v_mfma_f32_16x16x32_bf16 v[126:129], v[146:149], v[192:195], v[126:129]
	s_nop 0
	s_nop 0
	s_waitcnt lgkmcnt(4)
	v_mfma_f32_16x16x32_bf16 v[118:121], v[146:149], v[196:199], v[118:121]
	s_nop 0
	s_nop 0
	s_waitcnt lgkmcnt(2)
	v_mfma_f32_16x16x32_bf16 v[114:117], v[146:149], v[200:203], v[114:117]
	s_nop 0
	s_nop 0
	v_mfma_f32_16x16x32_bf16 v[106:109], v[146:149], v[154:157], v[106:109]
	s_waitcnt lgkmcnt(0)
	v_mfma_f32_16x16x32_bf16 v[110:113], v[146:149], v[204:207], v[110:113]
	v_cndmask_b32_e64 v144, 0, 1, s[34:35]
	s_andn2_b64 vcc, exec, s[26:27]
	v_cmp_ne_u32_e64 s[4:5], 1, v144
	s_cbranch_vccnz .LBB0_2635
.LBB0_2643:
	ds_read2_b32 v[208:209], v142 offset0:192 offset1:196
	ds_read2_b32 v[210:211], v142 offset0:200 offset1:204
	s_waitcnt vmcnt(7)
	ds_write_b128 v143, v[10:13] offset:7168
	s_waitcnt vmcnt(6)
	ds_write_b128 v143, v[18:21] offset:8448
	s_waitcnt vmcnt(5)
	ds_write_b128 v143, v[30:33] offset:9728
	s_waitcnt vmcnt(4)
	ds_write_b128 v143, v[38:41] offset:11008
	s_waitcnt vmcnt(3)
	ds_write_b128 v143, v[50:53] offset:12288
	s_waitcnt vmcnt(2)
	ds_write_b128 v143, v[54:57] offset:13568
	s_waitcnt vmcnt(1)
	ds_write_b128 v143, v[58:61] offset:14848
	s_waitcnt vmcnt(0)
	ds_write_b128 v143, v[62:65] offset:16128
	s_and_b64 vcc, exec, s[4:5]
	s_cbranch_vccnz .LBB0_2645
	s_nop 0
	s_nop 0
	s_waitcnt lgkmcnt(1)
	v_add_u32_e32 v10, s48, v208
	v_add_u32_e32 v12, s48, v209
	s_waitcnt lgkmcnt(0)
	v_add_u32_e32 v32, s48, v210
	v_add_u32_e32 v30, s48, v211
	v_ashrrev_i32_e32 v11, 31, v10
	v_ashrrev_i32_e32 v13, 31, v12
	v_ashrrev_i32_e32 v33, 31, v32
	v_ashrrev_i32_e32 v31, 31, v30
	v_lshlrev_b64 v[10:11], 9, v[10:11]
	v_lshlrev_b64 v[12:13], 9, v[12:13]
	v_lshlrev_b64 v[32:33], 9, v[32:33]
	v_lshlrev_b64 v[30:31], 9, v[30:31]
	v_lshl_add_u64 v[10:11], v[130:131], 0, v[10:11]
	v_lshl_add_u64 v[18:19], v[130:131], 0, v[12:13]
	v_lshl_add_u64 v[32:33], v[130:131], 0, v[32:33]
	v_lshl_add_u64 v[38:39], v[130:131], 0, v[30:31]
	global_load_dwordx4 v[10:13], v[10:11], off
	s_nop 0
	global_load_dwordx4 v[18:21], v[18:19], off
	ds_read2_b32 v[50:51], v142 offset0:208 offset1:212
	global_load_dwordx4 v[30:33], v[32:33], off
	s_nop 0
	global_load_dwordx4 v[38:41], v[38:39], off
	ds_read2_b32 v[58:59], v142 offset0:216 offset1:220
	s_waitcnt lgkmcnt(1)
	v_add_u32_e32 v52, s48, v50
	v_add_u32_e32 v50, s48, v51
	s_waitcnt lgkmcnt(0)
	v_add_u32_e32 v60, s48, v58
	v_add_u32_e32 v58, s48, v59
	v_ashrrev_i32_e32 v53, 31, v52
	v_ashrrev_i32_e32 v51, 31, v50
	v_ashrrev_i32_e32 v61, 31, v60
	v_ashrrev_i32_e32 v59, 31, v58
	v_lshlrev_b64 v[52:53], 9, v[52:53]
	v_lshlrev_b64 v[50:51], 9, v[50:51]
	v_lshlrev_b64 v[60:61], 9, v[60:61]
	v_lshlrev_b64 v[58:59], 9, v[58:59]
	v_lshl_add_u64 v[52:53], v[130:131], 0, v[52:53]
	v_lshl_add_u64 v[54:55], v[130:131], 0, v[50:51]
	v_lshl_add_u64 v[60:61], v[130:131], 0, v[60:61]
	v_lshl_add_u64 v[62:63], v[130:131], 0, v[58:59]
	global_load_dwordx4 v[50:53], v[52:53], off
	s_nop 0
	global_load_dwordx4 v[54:57], v[54:55], off
	s_nop 0
	global_load_dwordx4 v[58:61], v[60:61], off
	s_nop 0
	global_load_dwordx4 v[62:65], v[62:63], off
.LBB0_2645:
	ds_read_b128 v[146:149], v145 offset:5312
	ds_read_b64_tr_b16 v[152:153], v134 offset:8448
	ds_read_b64_tr_b16 v[150:151], v134 offset:7168
	ds_read_b64_tr_b16 v[154:155], v134 offset:7200
	ds_read_b64_tr_b16 v[156:157], v134 offset:8480
	s_waitcnt lgkmcnt(4)
	v_cndmask_b32_e64 v149, v149, 0, s[10:11]
	v_cndmask_b32_e64 v148, v148, 0, s[10:11]
	v_cndmask_b32_e64 v147, v147, 0, s[10:11]
	v_cndmask_b32_e64 v146, v146, 0, s[10:11]
	ds_read_b64_tr_b16 v[184:185], v134 offset:7232
	ds_read_b64_tr_b16 v[186:187], v134 offset:8512
	ds_read_b64_tr_b16 v[188:189], v134 offset:7264
	ds_read_b64_tr_b16 v[190:191], v134 offset:8544
	ds_read_b64_tr_b16 v[192:193], v134 offset:7296
	ds_read_b64_tr_b16 v[194:195], v134 offset:8576
	ds_read_b64_tr_b16 v[196:197], v134 offset:7328
	ds_read_b64_tr_b16 v[198:199], v134 offset:8608
	s_waitcnt lgkmcnt(10)
	s_nop 0
	v_mfma_f32_16x16x32_bf16 v[122:125], v[146:149], v[150:153], v[122:125]
	ds_read_b64_tr_b16 v[200:201], v134 offset:7360
	ds_read_b64_tr_b16 v[202:203], v134 offset:8640
	ds_read_b64_tr_b16 v[204:205], v134 offset:7392
	ds_read_b64_tr_b16 v[206:207], v134 offset:8672
	s_nop 0
	s_nop 0
	s_waitcnt lgkmcnt(10)
	v_mfma_f32_16x16x32_bf16 v[102:105], v[146:149], v[184:187], v[102:105]
	s_nop 0
	s_nop 0
	s_waitcnt lgkmcnt(8)
	v_mfma_f32_16x16x32_bf16 v[98:101], v[146:149], v[188:191], v[98:101]
	s_nop 0
	s_nop 0
	s_waitcnt lgkmcnt(6)
	v_mfma_f32_16x16x32_bf16 v[126:129], v[146:149], v[192:195], v[126:129]
	s_nop 0
	s_nop 0
	s_waitcnt lgkmcnt(4)
	v_mfma_f32_16x16x32_bf16 v[118:121], v[146:149], v[196:199], v[118:121]
	s_nop 0
	s_nop 0
	s_waitcnt lgkmcnt(2)
	v_mfma_f32_16x16x32_bf16 v[114:117], v[146:149], v[200:203], v[114:117]
	s_nop 0
	s_nop 0
	v_mfma_f32_16x16x32_bf16 v[106:109], v[146:149], v[154:157], v[106:109]
	s_waitcnt lgkmcnt(0)
	v_mfma_f32_16x16x32_bf16 v[110:113], v[146:149], v[204:207], v[110:113]
	v_cndmask_b32_e64 v144, 0, 1, s[36:37]
	s_and_b64 vcc, exec, s[0:1]
	v_cmp_ne_u32_e64 s[0:1], 1, v144
	s_cbranch_vccnz .LBB0_2636
.LBB0_2646:
	ds_read2_b32 v[208:209], v142 offset0:224 offset1:228
	ds_read2_b32 v[210:211], v142 offset0:232 offset1:236
	s_waitcnt vmcnt(7)
	ds_write_b128 v143, v[2:5] offset:7168
	s_waitcnt vmcnt(6)
	ds_write_b128 v143, v[6:9] offset:8448
	s_waitcnt vmcnt(5)
	ds_write_b128 v143, v[14:17] offset:9728
	s_waitcnt vmcnt(4)
	ds_write_b128 v143, v[22:25] offset:11008
	s_waitcnt vmcnt(3)
	ds_write_b128 v143, v[26:29] offset:12288
	s_waitcnt vmcnt(2)
	ds_write_b128 v143, v[34:37] offset:13568
	s_waitcnt vmcnt(1)
	ds_write_b128 v143, v[42:45] offset:14848
	s_waitcnt vmcnt(0)
	ds_write_b128 v143, v[46:49] offset:16128
	s_and_b64 vcc, exec, s[0:1]
	s_cbranch_vccnz .LBB0_2648
	s_nop 0
	s_nop 0
	s_waitcnt lgkmcnt(1)
	v_add_u32_e32 v2, s48, v208
	v_add_u32_e32 v4, s48, v209
	s_waitcnt lgkmcnt(0)
	v_add_u32_e32 v16, s48, v210
	v_add_u32_e32 v14, s48, v211
	v_ashrrev_i32_e32 v3, 31, v2
	v_ashrrev_i32_e32 v5, 31, v4
	v_ashrrev_i32_e32 v17, 31, v16
	v_ashrrev_i32_e32 v15, 31, v14
	v_lshlrev_b64 v[2:3], 9, v[2:3]
	v_lshlrev_b64 v[4:5], 9, v[4:5]
	v_lshlrev_b64 v[16:17], 9, v[16:17]
	v_lshlrev_b64 v[14:15], 9, v[14:15]
	v_lshl_add_u64 v[2:3], v[130:131], 0, v[2:3]
	v_lshl_add_u64 v[6:7], v[130:131], 0, v[4:5]
	v_lshl_add_u64 v[16:17], v[130:131], 0, v[16:17]
	v_lshl_add_u64 v[22:23], v[130:131], 0, v[14:15]
	global_load_dwordx4 v[2:5], v[2:3], off
	s_nop 0
	global_load_dwordx4 v[6:9], v[6:7], off
	ds_read2_b32 v[26:27], v142 offset0:240 offset1:244
	global_load_dwordx4 v[14:17], v[16:17], off
	s_nop 0
	global_load_dwordx4 v[22:25], v[22:23], off
	ds_read2_b32 v[42:43], v142 offset0:248 offset1:252
	s_waitcnt lgkmcnt(1)
	v_add_u32_e32 v28, s48, v26
	v_add_u32_e32 v26, s48, v27
	s_waitcnt lgkmcnt(0)
	v_add_u32_e32 v44, s48, v42
	v_add_u32_e32 v42, s48, v43
	v_ashrrev_i32_e32 v29, 31, v28
	v_ashrrev_i32_e32 v27, 31, v26
	v_ashrrev_i32_e32 v45, 31, v44
	v_ashrrev_i32_e32 v43, 31, v42
	v_lshlrev_b64 v[28:29], 9, v[28:29]
	v_lshlrev_b64 v[26:27], 9, v[26:27]
	v_lshlrev_b64 v[44:45], 9, v[44:45]
	v_lshlrev_b64 v[42:43], 9, v[42:43]
	v_lshl_add_u64 v[28:29], v[130:131], 0, v[28:29]
	v_lshl_add_u64 v[34:35], v[130:131], 0, v[26:27]
	v_lshl_add_u64 v[44:45], v[130:131], 0, v[44:45]
	v_lshl_add_u64 v[46:47], v[130:131], 0, v[42:43]
	global_load_dwordx4 v[26:29], v[28:29], off
	s_nop 0
	global_load_dwordx4 v[34:37], v[34:35], off
	s_nop 0
	global_load_dwordx4 v[42:45], v[44:45], off
	s_nop 0
	global_load_dwordx4 v[46:49], v[46:47], off
.LBB0_2648:
	ds_read_b128 v[146:149], v145 offset:5376
	ds_read_b64_tr_b16 v[152:153], v134 offset:8448
	ds_read_b64_tr_b16 v[150:151], v134 offset:7168
	ds_read_b64_tr_b16 v[154:155], v134 offset:7200
	ds_read_b64_tr_b16 v[156:157], v134 offset:8480
	s_waitcnt lgkmcnt(4)
	v_cndmask_b32_e64 v149, v149, 0, s[10:11]
	v_cndmask_b32_e64 v148, v148, 0, s[10:11]
	v_cndmask_b32_e64 v147, v147, 0, s[10:11]
	v_cndmask_b32_e64 v146, v146, 0, s[10:11]
	ds_read_b64_tr_b16 v[184:185], v134 offset:7232
	ds_read_b64_tr_b16 v[186:187], v134 offset:8512
	ds_read_b64_tr_b16 v[188:189], v134 offset:7264
	ds_read_b64_tr_b16 v[190:191], v134 offset:8544
	ds_read_b64_tr_b16 v[192:193], v134 offset:7296
	ds_read_b64_tr_b16 v[194:195], v134 offset:8576
	ds_read_b64_tr_b16 v[196:197], v134 offset:7328
	ds_read_b64_tr_b16 v[198:199], v134 offset:8608
	s_waitcnt lgkmcnt(10)
	s_nop 0
	v_mfma_f32_16x16x32_bf16 v[122:125], v[146:149], v[150:153], v[122:125]
	ds_read_b64_tr_b16 v[200:201], v134 offset:7360
	ds_read_b64_tr_b16 v[202:203], v134 offset:8640
	ds_read_b64_tr_b16 v[204:205], v134 offset:7392
	ds_read_b64_tr_b16 v[206:207], v134 offset:8672
	s_nop 0
	s_nop 0
	s_waitcnt lgkmcnt(10)
	v_mfma_f32_16x16x32_bf16 v[102:105], v[146:149], v[184:187], v[102:105]
	s_nop 0
	s_nop 0
	s_waitcnt lgkmcnt(8)
	v_mfma_f32_16x16x32_bf16 v[98:101], v[146:149], v[188:191], v[98:101]
	s_nop 0
	s_nop 0
	s_waitcnt lgkmcnt(6)
	v_mfma_f32_16x16x32_bf16 v[126:129], v[146:149], v[192:195], v[126:129]
	s_nop 0
	s_nop 0
	s_waitcnt lgkmcnt(4)
	v_mfma_f32_16x16x32_bf16 v[118:121], v[146:149], v[196:199], v[118:121]
	s_nop 0
	s_nop 0
	s_waitcnt lgkmcnt(2)
	v_mfma_f32_16x16x32_bf16 v[114:117], v[146:149], v[200:203], v[114:117]
	s_nop 0
	s_nop 0
	v_mfma_f32_16x16x32_bf16 v[106:109], v[146:149], v[154:157], v[106:109]
	s_waitcnt lgkmcnt(0)
	v_mfma_f32_16x16x32_bf16 v[110:113], v[146:149], v[204:207], v[110:113]
	s_and_b64 vcc, exec, s[2:3]
	s_cbranch_vccnz .LBB0_2637

.LBB0_2996:
	v_mov_b32_e32 v124, v0
	s_lshl_b32 s4, s7, 10
	v_and_b32_e32 v122, 3, v124
	v_lshl_or_b32 v134, v122, 8, s4
	v_lshl_add_u64 v[2:3], s[0:1], 0, v[134:135]
	v_and_b32_e32 v134, 48, v124
	v_bfe_u32 v123, v124, 4, 2
	v_lshl_add_u64 v[14:15], v[2:3], 0, v[134:135]
	global_load_dwordx4 v[2:5], v[14:15], off
	global_load_dwordx4 v[6:9], v[14:15], off offset:64
	global_load_dwordx4 v[10:13], v[14:15], off offset:128
	s_nop 0
	global_load_dwordx4 v[14:17], v[14:15], off offset:192
	v_lshl_add_u32 v121, v123, 2, v138
	ds_read2_b32 v[18:19], v121 offset1:4
	v_readlane_b32 s8, v251, 19
	v_readlane_b32 s9, v251, 20
	v_readlane_b32 s10, v251, 21
	v_readlane_b32 s11, v251, 22
	v_readlane_b32 s12, v251, 23
	v_readlane_b32 s13, v251, 24
	v_readlane_b32 s14, v251, 25
	v_readlane_b32 s15, v251, 26
	v_readlane_b32 s16, v251, 27
	v_readlane_b32 s17, v251, 28
	v_readlane_b32 s18, v251, 29
	v_readlane_b32 s19, v251, 30
	v_readlane_b32 s20, v251, 31
	v_readlane_b32 s21, v251, 32
	v_readlane_b32 s22, v251, 33
	v_readlane_b32 s23, v251, 34
	s_mov_b64 s[8:9], s[16:17]
	s_lshl_b32 s4, s7, 8
	s_mov_b64 s[10:11], s[18:19]
	v_and_b32_e32 v1, 15, v124
	s_add_u32 s4, s10, s4
	ds_read2_b32 v[26:27], v121 offset0:8 offset1:12
	s_waitcnt lgkmcnt(1)
	v_add_u32_e32 v20, s48, v18
	v_add_u32_e32 v18, s48, v19
	s_addc_u32 s5, s11, 0
	v_lshlrev_b32_e32 v114, 4, v1
	v_mov_b32_e32 v115, v135
	v_ashrrev_i32_e32 v21, 31, v20
	v_ashrrev_i32_e32 v19, 31, v18
	v_lshl_add_u64 v[118:119], s[4:5], 0, v[114:115]
	v_lshlrev_b64 v[20:21], 9, v[20:21]
	v_lshlrev_b64 v[18:19], 9, v[18:19]
	v_lshl_add_u64 v[20:21], v[118:119], 0, v[20:21]
	v_lshl_add_u64 v[22:23], v[118:119], 0, v[18:19]
	global_load_dwordx4 v[18:21], v[20:21], off
	s_nop 0
	global_load_dwordx4 v[22:25], v[22:23], off
	ds_read2_b32 v[30:31], v121 offset0:16 offset1:20
	s_waitcnt lgkmcnt(1)
	v_add_u32_e32 v28, s48, v26
	v_add_u32_e32 v26, s48, v27
	v_ashrrev_i32_e32 v29, 31, v28
	v_ashrrev_i32_e32 v27, 31, v26
	v_lshlrev_b64 v[28:29], 9, v[28:29]
	v_lshlrev_b64 v[26:27], 9, v[26:27]
	v_lshl_add_u64 v[28:29], v[118:119], 0, v[28:29]
	v_lshl_add_u64 v[26:27], v[118:119], 0, v[26:27]
	global_load_dwordx4 v[42:45], v[28:29], off
	global_load_dwordx4 v[46:49], v[26:27], off
	s_waitcnt lgkmcnt(0)
	v_add_u32_e32 v26, s48, v30
	v_add_u32_e32 v28, s48, v31
	ds_read2_b32 v[30:31], v121 offset0:24 offset1:28
	v_ashrrev_i32_e32 v27, 31, v26
	v_lshlrev_b64 v[26:27], 9, v[26:27]
	v_ashrrev_i32_e32 v29, 31, v28
	v_lshl_add_u64 v[26:27], v[118:119], 0, v[26:27]
	v_lshlrev_b64 v[28:29], 9, v[28:29]
	v_lshl_add_u64 v[28:29], v[118:119], 0, v[28:29]
	global_load_dwordx4 v[66:69], v[26:27], off
	global_load_dwordx4 v[70:73], v[28:29], off
	s_waitcnt lgkmcnt(0)
	v_add_u32_e32 v26, s48, v30
	v_ashrrev_i32_e32 v27, 31, v26
	v_add_u32_e32 v28, s48, v31
	v_lshlrev_b64 v[26:27], 9, v[26:27]
	v_ashrrev_i32_e32 v29, 31, v28
	v_lshl_add_u64 v[26:27], v[118:119], 0, v[26:27]
	v_lshlrev_b64 v[28:29], 9, v[28:29]
	ds_read2_b32 v[30:31], v121 offset0:32 offset1:36
	v_lshl_add_u64 v[28:29], v[118:119], 0, v[28:29]
	global_load_dwordx4 v[74:77], v[26:27], off
	global_load_dwordx4 v[78:81], v[28:29], off
	ds_read2_b32 v[34:35], v121 offset0:40 offset1:44
	v_add_u32_e32 v125, v138, v114
	s_waitcnt lgkmcnt(1)
	v_add_u32_e32 v26, s48, v30
	v_add_u32_e32 v28, s48, v31
	v_ashrrev_i32_e32 v27, 31, v26
	v_ashrrev_i32_e32 v29, 31, v28
	v_lshlrev_b64 v[26:27], 9, v[26:27]
	v_lshlrev_b64 v[28:29], 9, v[28:29]
	v_lshl_add_u64 v[26:27], v[118:119], 0, v[26:27]
	v_lshl_add_u64 v[30:31], v[118:119], 0, v[28:29]
	global_load_dwordx4 v[26:29], v[26:27], off
	s_nop 0
	global_load_dwordx4 v[30:33], v[30:31], off
	ds_read2_b32 v[38:39], v121 offset0:48 offset1:52
	s_waitcnt lgkmcnt(1)
	v_add_u32_e32 v36, s48, v34
	v_add_u32_e32 v34, s48, v35
	v_ashrrev_i32_e32 v37, 31, v36
	v_ashrrev_i32_e32 v35, 31, v34
	v_lshlrev_b64 v[36:37], 9, v[36:37]
	v_lshlrev_b64 v[34:35], 9, v[34:35]
	v_lshl_add_u64 v[36:37], v[118:119], 0, v[36:37]
	v_lshl_add_u64 v[34:35], v[118:119], 0, v[34:35]
	global_load_dwordx4 v[50:53], v[36:37], off
	global_load_dwordx4 v[54:57], v[34:35], off
	s_waitcnt lgkmcnt(0)
	v_add_u32_e32 v34, s48, v38
	v_add_u32_e32 v36, s48, v39
	ds_read2_b32 v[38:39], v121 offset0:56 offset1:60
	v_ashrrev_i32_e32 v35, 31, v34
	v_lshlrev_b64 v[34:35], 9, v[34:35]
	v_ashrrev_i32_e32 v37, 31, v36
	v_lshl_add_u64 v[34:35], v[118:119], 0, v[34:35]
	v_lshlrev_b64 v[36:37], 9, v[36:37]
	v_lshl_add_u64 v[36:37], v[118:119], 0, v[36:37]
	global_load_dwordx4 v[82:85], v[34:35], off
	global_load_dwordx4 v[86:89], v[36:37], off
	s_waitcnt lgkmcnt(0)
	v_add_u32_e32 v34, s48, v38
	v_ashrrev_i32_e32 v35, 31, v34
	v_add_u32_e32 v36, s48, v39
	v_lshlrev_b64 v[34:35], 9, v[34:35]
	v_ashrrev_i32_e32 v37, 31, v36
	v_lshl_add_u64 v[34:35], v[118:119], 0, v[34:35]
	v_lshlrev_b64 v[36:37], 9, v[36:37]
	ds_read2_b32 v[38:39], v121 offset0:64 offset1:68
	v_lshl_add_u64 v[36:37], v[118:119], 0, v[36:37]
	global_load_dwordx4 v[98:101], v[34:35], off
	global_load_dwordx4 v[102:105], v[36:37], off
	ds_read2_b32 v[58:59], v121 offset0:72 offset1:76
	v_mad_u32_u24 v120, v123, s33, v125
	s_waitcnt lgkmcnt(1)
	v_add_u32_e32 v34, s48, v38
	v_add_u32_e32 v36, s48, v39
	v_ashrrev_i32_e32 v35, 31, v34
	s_waitcnt lgkmcnt(0)
	v_add_u32_e32 v60, s48, v58
	v_add_u32_e32 v58, s48, v59
	v_ashrrev_i32_e32 v37, 31, v36
	v_ashrrev_i32_e32 v61, 31, v60
	v_ashrrev_i32_e32 v59, 31, v58
	v_lshlrev_b64 v[34:35], 9, v[34:35]
	v_lshlrev_b64 v[36:37], 9, v[36:37]
	v_lshlrev_b64 v[60:61], 9, v[60:61]
	v_lshlrev_b64 v[58:59], 9, v[58:59]
	v_lshl_add_u64 v[34:35], v[118:119], 0, v[34:35]
	v_lshl_add_u64 v[38:39], v[118:119], 0, v[36:37]
	v_lshl_add_u64 v[60:61], v[118:119], 0, v[60:61]
	v_lshl_add_u64 v[62:63], v[118:119], 0, v[58:59]
	global_load_dwordx4 v[34:37], v[34:35], off
	s_nop 0
	global_load_dwordx4 v[38:41], v[38:39], off
	ds_read2_b32 v[90:91], v121 offset0:80 offset1:84
	global_load_dwordx4 v[58:61], v[60:61], off
	s_nop 0
	global_load_dwordx4 v[62:65], v[62:63], off
	ds_read2_b32 v[106:107], v121 offset0:88 offset1:92
	s_mov_b64 s[12:13], s[20:21]
	v_add_u32_e32 v126, v138, v134
	s_waitcnt lgkmcnt(1)
	v_add_u32_e32 v92, s48, v90
	v_add_u32_e32 v90, s48, v91
	s_waitcnt lgkmcnt(0)
	v_add_u32_e32 v108, s48, v106
	v_add_u32_e32 v106, s48, v107
	v_ashrrev_i32_e32 v93, 31, v92
	v_ashrrev_i32_e32 v91, 31, v90
	v_ashrrev_i32_e32 v109, 31, v108
	v_ashrrev_i32_e32 v107, 31, v106
	v_lshlrev_b64 v[92:93], 9, v[92:93]
	v_lshlrev_b64 v[90:91], 9, v[90:91]
	v_lshlrev_b64 v[108:109], 9, v[108:109]
	v_lshlrev_b64 v[106:107], 9, v[106:107]
	v_lshl_add_u64 v[92:93], v[118:119], 0, v[92:93]
	v_lshl_add_u64 v[94:95], v[118:119], 0, v[90:91]
	v_lshl_add_u64 v[108:109], v[118:119], 0, v[108:109]
	v_lshl_add_u64 v[110:111], v[118:119], 0, v[106:107]
	global_load_dwordx4 v[90:93], v[92:93], off
	s_nop 0
	global_load_dwordx4 v[94:97], v[94:95], off
	s_nop 0
	global_load_dwordx4 v[106:109], v[108:109], off
	s_nop 0
	global_load_dwordx4 v[110:113], v[110:111], off
	ds_read2_b32 v[208:209], v121 offset0:96 offset1:100
	ds_read2_b32 v[210:211], v121 offset0:104 offset1:108
	s_waitcnt vmcnt(23)
	ds_write_b128 v120, v[18:21] offset:7168
	s_waitcnt vmcnt(22)
	ds_write_b128 v120, v[22:25] offset:8448
	s_waitcnt vmcnt(21)
	ds_write_b128 v120, v[42:45] offset:9728
	s_waitcnt vmcnt(20)
	ds_write_b128 v120, v[46:49] offset:11008
	s_waitcnt vmcnt(19)
	ds_write_b128 v120, v[66:69] offset:12288
	s_waitcnt vmcnt(18)
	ds_write_b128 v120, v[70:73] offset:13568
	s_waitcnt vmcnt(17)
	ds_write_b128 v120, v[74:77] offset:14848
	s_waitcnt vmcnt(16)
	ds_write_b128 v120, v[78:81] offset:16128
	s_nop 0
	s_nop 0
	v_cmp_lt_u32_e64 s[12:13], 3, v1
	v_mad_u32_u24 v127, v1, s33, v126
	v_and_b32_e32 v124, 63, v124
	s_waitcnt lgkmcnt(1)
	v_add_u32_e32 v20, s48, v208
	v_add_u32_e32 v18, s48, v209
	s_waitcnt lgkmcnt(0)
	v_add_u32_e32 v44, s48, v210
	v_add_u32_e32 v42, s48, v211
	v_ashrrev_i32_e32 v21, 31, v20
	v_ashrrev_i32_e32 v19, 31, v18
	v_ashrrev_i32_e32 v45, 31, v44
	v_ashrrev_i32_e32 v43, 31, v42
	v_lshlrev_b64 v[20:21], 9, v[20:21]
	v_lshlrev_b64 v[18:19], 9, v[18:19]
	v_lshlrev_b64 v[44:45], 9, v[44:45]
	v_lshlrev_b64 v[42:43], 9, v[42:43]
	v_lshl_add_u64 v[20:21], v[118:119], 0, v[20:21]
	v_lshl_add_u64 v[22:23], v[118:119], 0, v[18:19]
	v_lshl_add_u64 v[44:45], v[118:119], 0, v[44:45]
	v_lshl_add_u64 v[46:47], v[118:119], 0, v[42:43]
	global_load_dwordx4 v[18:21], v[20:21], off
	s_nop 0
	global_load_dwordx4 v[22:25], v[22:23], off
	ds_read2_b32 v[66:67], v121 offset0:112 offset1:116
	global_load_dwordx4 v[42:45], v[44:45], off
	s_nop 0
	global_load_dwordx4 v[46:49], v[46:47], off
	ds_read2_b32 v[74:75], v121 offset0:120 offset1:124
	v_cndmask_b32_e64 v5, v5, 0, s[12:13]
	v_cndmask_b32_e64 v4, v4, 0, s[12:13]
	s_waitcnt lgkmcnt(1)
	v_add_u32_e32 v68, s48, v66
	v_add_u32_e32 v66, s48, v67
	s_waitcnt lgkmcnt(0)
	v_add_u32_e32 v76, s48, v74
	v_add_u32_e32 v74, s48, v75
	v_ashrrev_i32_e32 v69, 31, v68
	v_ashrrev_i32_e32 v67, 31, v66
	v_ashrrev_i32_e32 v77, 31, v76
	v_ashrrev_i32_e32 v75, 31, v74
	v_lshlrev_b64 v[68:69], 9, v[68:69]
	v_lshlrev_b64 v[66:67], 9, v[66:67]
	v_lshlrev_b64 v[76:77], 9, v[76:77]
	v_lshlrev_b64 v[74:75], 9, v[74:75]
	v_lshl_add_u64 v[68:69], v[118:119], 0, v[68:69]
	v_lshl_add_u64 v[70:71], v[118:119], 0, v[66:67]
	v_lshl_add_u64 v[76:77], v[118:119], 0, v[76:77]
	v_lshl_add_u64 v[78:79], v[118:119], 0, v[74:75]
	global_load_dwordx4 v[66:69], v[68:69], off
	s_nop 0
	global_load_dwordx4 v[70:73], v[70:71], off
	s_nop 0
	global_load_dwordx4 v[74:77], v[76:77], off
	s_nop 0
	global_load_dwordx4 v[78:81], v[78:79], off
	v_cndmask_b32_e64 v3, v3, 0, s[12:13]
	v_cndmask_b32_e64 v2, v2, 0, s[12:13]
	ds_read_b128 v[114:117], v127 offset:7168
	ds_read_b128 v[128:131], v127 offset:7232
	v_cndmask_b32_e64 v9, v9, 0, s[12:13]
	v_cndmask_b32_e64 v8, v8, 0, s[12:13]
	v_cndmask_b32_e64 v7, v7, 0, s[12:13]
	v_cndmask_b32_e64 v6, v6, 0, s[12:13]
	s_waitcnt lgkmcnt(1)
	v_mfma_f32_16x16x32_bf16 v[114:117], v[2:5], v[114:117], 0
	v_cndmask_b32_e64 v13, v13, 0, s[12:13]
	v_cndmask_b32_e64 v12, v12, 0, s[12:13]
	v_cndmask_b32_e64 v11, v11, 0, s[12:13]
	v_cndmask_b32_e64 v10, v10, 0, s[12:13]
	ds_read_b128 v[142:145], v127 offset:7296
	s_waitcnt lgkmcnt(1)
	v_mfma_f32_16x16x32_bf16 v[114:117], v[6:9], v[128:131], v[114:117]
	v_cndmask_b32_e64 v17, v17, 0, s[12:13]
	v_cndmask_b32_e64 v16, v16, 0, s[12:13]
	v_cndmask_b32_e64 v15, v15, 0, s[12:13]
	ds_read_b128 v[128:131], v127 offset:7360
	v_cndmask_b32_e64 v14, v14, 0, s[12:13]
	s_waitcnt lgkmcnt(1)
	v_mfma_f32_16x16x32_bf16 v[114:117], v[10:13], v[142:145], v[114:117]
	v_cmp_gt_u32_e64 s[10:11], 16, v124
	s_mov_b64 s[14:15], s[22:23]
	s_waitcnt lgkmcnt(0)
	v_mfma_f32_16x16x32_bf16 v[114:117], v[14:17], v[128:131], v[114:117]
	s_and_saveexec_b64 s[4:5], s[10:11]
	s_nop 6
	ds_write_b128 v125, v[114:117] offset:1024
	s_or_b64 exec, exec, s[4:5]
	v_mul_u32_u24_e32 v114, 0x140, v1
	v_add_u32_e32 v126, v126, v114
	ds_read_b128 v[114:117], v126 offset:12288
	ds_read_b128 v[128:131], v126 offset:12352
	s_waitcnt lgkmcnt(1)
	v_mfma_f32_16x16x32_bf16 v[114:117], v[2:5], v[114:117], 0
	s_waitcnt lgkmcnt(0)
	v_mfma_f32_16x16x32_bf16 v[114:117], v[6:9], v[128:131], v[114:117]
	ds_read_b128 v[128:131], v126 offset:12416
	ds_read_b128 v[142:145], v126 offset:12480
	s_waitcnt lgkmcnt(1)
	v_mfma_f32_16x16x32_bf16 v[114:117], v[10:13], v[128:131], v[114:117]
	s_waitcnt lgkmcnt(0)
	v_mfma_f32_16x16x32_bf16 v[114:117], v[14:17], v[142:145], v[114:117]
	s_and_saveexec_b64 s[4:5], s[10:11]
	s_nop 6
	ds_write_b128 v125, v[114:117] offset:1280
	s_or_b64 exec, exec, s[4:5]
	ds_read2_b32 v[208:209], v121 offset0:128 offset1:132
	ds_read2_b32 v[210:211], v121 offset0:136 offset1:140
	s_waitcnt vmcnt(23)
	ds_write_b128 v120, v[26:29] offset:7168
	s_waitcnt vmcnt(22)
	ds_write_b128 v120, v[30:33] offset:8448
	s_waitcnt vmcnt(21)
	ds_write_b128 v120, v[50:53] offset:9728
	s_waitcnt vmcnt(20)
	ds_write_b128 v120, v[54:57] offset:11008
	s_waitcnt vmcnt(19)
	ds_write_b128 v120, v[82:85] offset:12288
	s_waitcnt vmcnt(18)
	ds_write_b128 v120, v[86:89] offset:13568
	s_waitcnt vmcnt(17)
	ds_write_b128 v120, v[98:101] offset:14848
	s_waitcnt vmcnt(16)
	ds_write_b128 v120, v[102:105] offset:16128
	s_nop 0
	s_nop 0
	s_waitcnt lgkmcnt(1)
	v_add_u32_e32 v28, s48, v208
	v_add_u32_e32 v26, s48, v209
	v_ashrrev_i32_e32 v29, 31, v28
	v_ashrrev_i32_e32 v27, 31, v26
	v_lshlrev_b64 v[28:29], 9, v[28:29]
	v_lshlrev_b64 v[26:27], 9, v[26:27]
	v_lshl_add_u64 v[28:29], v[118:119], 0, v[28:29]
	v_lshl_add_u64 v[30:31], v[118:119], 0, v[26:27]
	global_load_dwordx4 v[26:29], v[28:29], off
	s_nop 0
	global_load_dwordx4 v[30:33], v[30:31], off
	ds_read2_b32 v[82:83], v121 offset0:144 offset1:148
	s_waitcnt lgkmcnt(1)
	v_add_u32_e32 v52, s48, v210
	v_add_u32_e32 v50, s48, v211
	v_ashrrev_i32_e32 v53, 31, v52
	v_ashrrev_i32_e32 v51, 31, v50
	v_lshlrev_b64 v[52:53], 9, v[52:53]
	v_lshlrev_b64 v[50:51], 9, v[50:51]
	v_lshl_add_u64 v[52:53], v[118:119], 0, v[52:53]
	v_lshl_add_u64 v[54:55], v[118:119], 0, v[50:51]
	global_load_dwordx4 v[50:53], v[52:53], off
	s_nop 0
	global_load_dwordx4 v[54:57], v[54:55], off
	s_waitcnt lgkmcnt(0)
	v_add_u32_e32 v84, s48, v82
	v_add_u32_e32 v82, s48, v83
	ds_read2_b32 v[114:115], v121 offset0:152 offset1:156
	v_ashrrev_i32_e32 v85, 31, v84
	v_ashrrev_i32_e32 v83, 31, v82
	v_lshlrev_b64 v[84:85], 9, v[84:85]
	v_lshlrev_b64 v[82:83], 9, v[82:83]
	v_lshl_add_u64 v[84:85], v[118:119], 0, v[84:85]
	v_lshl_add_u64 v[86:87], v[118:119], 0, v[82:83]
	global_load_dwordx4 v[82:85], v[84:85], off
	s_nop 0
	global_load_dwordx4 v[86:89], v[86:87], off
	ds_read_b128 v[98:101], v126 offset:7168
	s_waitcnt lgkmcnt(1)
	v_add_u32_e32 v102, s48, v114
	v_ashrrev_i32_e32 v103, 31, v102
	v_lshlrev_b64 v[102:103], 9, v[102:103]
	v_lshl_add_u64 v[142:143], v[118:119], 0, v[102:103]
	ds_read_b128 v[102:105], v126 offset:7232
	s_waitcnt lgkmcnt(1)
	v_mfma_f32_16x16x32_bf16 v[98:101], v[2:5], v[98:101], 0
	v_add_u32_e32 v128, s48, v115
	ds_read_b128 v[114:117], v126 offset:7296
	v_ashrrev_i32_e32 v129, 31, v128
	s_waitcnt lgkmcnt(1)
	v_mfma_f32_16x16x32_bf16 v[98:101], v[6:9], v[102:105], v[98:101]
	v_lshlrev_b64 v[102:103], 9, v[128:129]
	v_lshl_add_u64 v[102:103], v[118:119], 0, v[102:103]
	ds_read_b128 v[128:131], v126 offset:7360
	s_waitcnt lgkmcnt(1)
	v_mfma_f32_16x16x32_bf16 v[114:117], v[10:13], v[114:117], v[98:101]
	s_nop 2
	global_load_dwordx4 v[98:101], v[142:143], off
	s_nop 0
	global_load_dwordx4 v[102:105], v[102:103], off
	s_waitcnt lgkmcnt(0)
	v_mfma_f32_16x16x32_bf16 v[114:117], v[14:17], v[128:131], v[114:117]
	s_and_saveexec_b64 s[4:5], s[10:11]
	s_nop 6
	ds_write_b128 v125, v[114:117] offset:1536
	s_or_b64 exec, exec, s[4:5]
	ds_read_b128 v[114:117], v126 offset:12288
	ds_read_b128 v[128:131], v126 offset:12352
	s_waitcnt lgkmcnt(1)
	v_mfma_f32_16x16x32_bf16 v[114:117], v[2:5], v[114:117], 0
	s_waitcnt lgkmcnt(0)
	v_mfma_f32_16x16x32_bf16 v[114:117], v[6:9], v[128:131], v[114:117]
	ds_read_b128 v[128:131], v126 offset:12416
	ds_read_b128 v[142:145], v126 offset:12480
	s_waitcnt lgkmcnt(1)
	v_mfma_f32_16x16x32_bf16 v[114:117], v[10:13], v[128:131], v[114:117]
	s_waitcnt lgkmcnt(0)
	v_mfma_f32_16x16x32_bf16 v[114:117], v[14:17], v[142:145], v[114:117]
	s_and_saveexec_b64 s[4:5], s[10:11]
	s_nop 6
	ds_write_b128 v125, v[114:117] offset:1792
	s_or_b64 exec, exec, s[4:5]
	ds_read2_b32 v[208:209], v121 offset0:160 offset1:164
	ds_read2_b32 v[210:211], v121 offset0:168 offset1:172
	s_waitcnt vmcnt(23)
	ds_write_b128 v120, v[34:37] offset:7168
	s_waitcnt vmcnt(22)
	ds_write_b128 v120, v[38:41] offset:8448
	s_waitcnt vmcnt(21)
	ds_write_b128 v120, v[58:61] offset:9728
	s_waitcnt vmcnt(20)
	ds_write_b128 v120, v[62:65] offset:11008
	s_waitcnt vmcnt(19)
	ds_write_b128 v120, v[90:93] offset:12288
	s_waitcnt vmcnt(18)
	ds_write_b128 v120, v[94:97] offset:13568
	s_waitcnt vmcnt(17)
	ds_write_b128 v120, v[106:109] offset:14848
	s_waitcnt vmcnt(16)
	ds_write_b128 v120, v[110:113] offset:16128
	s_nop 0
	s_nop 0
	s_waitcnt lgkmcnt(1)
	v_add_u32_e32 v36, s48, v208
	v_add_u32_e32 v34, s48, v209
	v_ashrrev_i32_e32 v37, 31, v36
	v_ashrrev_i32_e32 v35, 31, v34
	v_lshlrev_b64 v[36:37], 9, v[36:37]
	v_lshlrev_b64 v[34:35], 9, v[34:35]
	v_lshl_add_u64 v[36:37], v[118:119], 0, v[36:37]
	v_lshl_add_u64 v[38:39], v[118:119], 0, v[34:35]
	global_load_dwordx4 v[34:37], v[36:37], off
	s_nop 0
	global_load_dwordx4 v[38:41], v[38:39], off
	ds_read2_b32 v[90:91], v121 offset0:176 offset1:180
	s_waitcnt lgkmcnt(1)
	v_add_u32_e32 v60, s48, v210
	v_add_u32_e32 v58, s48, v211
	v_ashrrev_i32_e32 v61, 31, v60
	v_ashrrev_i32_e32 v59, 31, v58
	v_lshlrev_b64 v[60:61], 9, v[60:61]
	v_lshlrev_b64 v[58:59], 9, v[58:59]
	v_lshl_add_u64 v[60:61], v[118:119], 0, v[60:61]
	v_lshl_add_u64 v[62:63], v[118:119], 0, v[58:59]
	global_load_dwordx4 v[58:61], v[60:61], off
	s_nop 0
	global_load_dwordx4 v[62:65], v[62:63], off
	s_waitcnt lgkmcnt(0)
	v_add_u32_e32 v92, s48, v90
	v_add_u32_e32 v90, s48, v91
	ds_read2_b32 v[114:115], v121 offset0:184 offset1:188
	v_ashrrev_i32_e32 v93, 31, v92
	v_ashrrev_i32_e32 v91, 31, v90
	v_lshlrev_b64 v[92:93], 9, v[92:93]
	v_lshlrev_b64 v[90:91], 9, v[90:91]
	v_lshl_add_u64 v[92:93], v[118:119], 0, v[92:93]
	v_lshl_add_u64 v[94:95], v[118:119], 0, v[90:91]
	global_load_dwordx4 v[90:93], v[92:93], off
	s_nop 0
	global_load_dwordx4 v[94:97], v[94:95], off
	ds_read_b128 v[106:109], v126 offset:7168
	s_waitcnt lgkmcnt(1)
	v_add_u32_e32 v110, s48, v114
	v_ashrrev_i32_e32 v111, 31, v110
	v_lshlrev_b64 v[110:111], 9, v[110:111]
	v_lshl_add_u64 v[142:143], v[118:119], 0, v[110:111]
	ds_read_b128 v[110:113], v126 offset:7232
	s_waitcnt lgkmcnt(1)
	v_mfma_f32_16x16x32_bf16 v[106:109], v[2:5], v[106:109], 0
	v_add_u32_e32 v128, s48, v115
	ds_read_b128 v[114:117], v126 offset:7296
	v_ashrrev_i32_e32 v129, 31, v128
	s_waitcnt lgkmcnt(1)
	v_mfma_f32_16x16x32_bf16 v[106:109], v[6:9], v[110:113], v[106:109]
	v_lshlrev_b64 v[110:111], 9, v[128:129]
	v_lshl_add_u64 v[110:111], v[118:119], 0, v[110:111]
	ds_read_b128 v[128:131], v126 offset:7360
	s_waitcnt lgkmcnt(1)
	v_mfma_f32_16x16x32_bf16 v[114:117], v[10:13], v[114:117], v[106:109]
	s_nop 2
	global_load_dwordx4 v[106:109], v[142:143], off
	s_nop 0
	global_load_dwordx4 v[110:113], v[110:111], off
	s_waitcnt lgkmcnt(0)
	v_mfma_f32_16x16x32_bf16 v[114:117], v[14:17], v[128:131], v[114:117]
	s_and_saveexec_b64 s[4:5], s[10:11]
	s_nop 6
	ds_write_b128 v125, v[114:117] offset:2048
	s_or_b64 exec, exec, s[4:5]
	ds_read_b128 v[114:117], v126 offset:12288
	ds_read_b128 v[128:131], v126 offset:12352
	s_waitcnt lgkmcnt(1)
	v_mfma_f32_16x16x32_bf16 v[114:117], v[2:5], v[114:117], 0
	s_waitcnt lgkmcnt(0)
	v_mfma_f32_16x16x32_bf16 v[114:117], v[6:9], v[128:131], v[114:117]
	ds_read_b128 v[128:131], v126 offset:12416
	ds_read_b128 v[142:145], v126 offset:12480
	s_waitcnt lgkmcnt(1)
	v_mfma_f32_16x16x32_bf16 v[114:117], v[10:13], v[128:131], v[114:117]
	s_waitcnt lgkmcnt(0)
	v_mfma_f32_16x16x32_bf16 v[114:117], v[14:17], v[142:145], v[114:117]
	s_and_saveexec_b64 s[4:5], s[10:11]
	s_nop 6
	ds_write_b128 v125, v[114:117] offset:2304
	s_or_b64 exec, exec, s[4:5]
	ds_read2_b32 v[208:209], v121 offset0:192 offset1:196
	ds_read2_b32 v[210:211], v121 offset0:200 offset1:204
	s_waitcnt vmcnt(23)
	ds_write_b128 v120, v[18:21] offset:7168
	s_waitcnt vmcnt(22)
	ds_write_b128 v120, v[22:25] offset:8448
	s_waitcnt vmcnt(21)
	ds_write_b128 v120, v[42:45] offset:9728
	s_waitcnt vmcnt(20)
	ds_write_b128 v120, v[46:49] offset:11008
	s_waitcnt vmcnt(19)
	ds_write_b128 v120, v[66:69] offset:12288
	s_waitcnt vmcnt(18)
	ds_write_b128 v120, v[70:73] offset:13568
	s_waitcnt vmcnt(17)
	ds_write_b128 v120, v[74:77] offset:14848
	s_waitcnt vmcnt(16)
	ds_write_b128 v120, v[78:81] offset:16128
	s_nop 0
	s_nop 0
	s_waitcnt lgkmcnt(1)
	v_add_u32_e32 v20, s48, v208
	v_add_u32_e32 v18, s48, v209
	v_ashrrev_i32_e32 v21, 31, v20
	v_ashrrev_i32_e32 v19, 31, v18
	v_lshlrev_b64 v[20:21], 9, v[20:21]
	v_lshlrev_b64 v[18:19], 9, v[18:19]
	v_lshl_add_u64 v[20:21], v[118:119], 0, v[20:21]
	v_lshl_add_u64 v[22:23], v[118:119], 0, v[18:19]
	global_load_dwordx4 v[18:21], v[20:21], off
	s_nop 0
	global_load_dwordx4 v[22:25], v[22:23], off
	ds_read2_b32 v[66:67], v121 offset0:208 offset1:212
	s_waitcnt lgkmcnt(1)
	v_add_u32_e32 v44, s48, v210
	v_add_u32_e32 v42, s48, v211
	v_ashrrev_i32_e32 v45, 31, v44
	v_ashrrev_i32_e32 v43, 31, v42
	v_lshlrev_b64 v[44:45], 9, v[44:45]
	v_lshlrev_b64 v[42:43], 9, v[42:43]
	v_lshl_add_u64 v[44:45], v[118:119], 0, v[44:45]
	v_lshl_add_u64 v[46:47], v[118:119], 0, v[42:43]
	global_load_dwordx4 v[42:45], v[44:45], off
	s_nop 0
	global_load_dwordx4 v[46:49], v[46:47], off
	s_waitcnt lgkmcnt(0)
	v_add_u32_e32 v68, s48, v66
	v_add_u32_e32 v66, s48, v67
	ds_read2_b32 v[114:115], v121 offset0:216 offset1:220
	v_ashrrev_i32_e32 v69, 31, v68
	v_ashrrev_i32_e32 v67, 31, v66
	v_lshlrev_b64 v[68:69], 9, v[68:69]
	v_lshlrev_b64 v[66:67], 9, v[66:67]
	v_lshl_add_u64 v[68:69], v[118:119], 0, v[68:69]
	v_lshl_add_u64 v[70:71], v[118:119], 0, v[66:67]
	global_load_dwordx4 v[66:69], v[68:69], off
	s_nop 0
	global_load_dwordx4 v[70:73], v[70:71], off
	ds_read_b128 v[74:77], v126 offset:7168
	s_waitcnt lgkmcnt(1)
	v_add_u32_e32 v78, s48, v114
	v_ashrrev_i32_e32 v79, 31, v78
	v_lshlrev_b64 v[78:79], 9, v[78:79]
	v_lshl_add_u64 v[142:143], v[118:119], 0, v[78:79]
	ds_read_b128 v[78:81], v126 offset:7232
	s_waitcnt lgkmcnt(1)
	v_mfma_f32_16x16x32_bf16 v[74:77], v[2:5], v[74:77], 0
	v_add_u32_e32 v128, s48, v115
	ds_read_b128 v[114:117], v126 offset:7296
	v_ashrrev_i32_e32 v129, 31, v128
	s_waitcnt lgkmcnt(1)
	v_mfma_f32_16x16x32_bf16 v[74:77], v[6:9], v[78:81], v[74:77]
	v_lshlrev_b64 v[78:79], 9, v[128:129]
	v_lshl_add_u64 v[78:79], v[118:119], 0, v[78:79]
	ds_read_b128 v[128:131], v126 offset:7360
	s_waitcnt lgkmcnt(1)
	v_mfma_f32_16x16x32_bf16 v[114:117], v[10:13], v[114:117], v[74:77]
	s_nop 2
	global_load_dwordx4 v[74:77], v[142:143], off
	s_nop 0
	global_load_dwordx4 v[78:81], v[78:79], off
	s_waitcnt lgkmcnt(0)
	v_mfma_f32_16x16x32_bf16 v[114:117], v[14:17], v[128:131], v[114:117]
	s_and_saveexec_b64 s[4:5], s[10:11]
	s_nop 6
	ds_write_b128 v125, v[114:117] offset:2560
	s_or_b64 exec, exec, s[4:5]
	ds_read_b128 v[114:117], v126 offset:12288
	ds_read_b128 v[128:131], v126 offset:12352
	s_waitcnt lgkmcnt(1)
	v_mfma_f32_16x16x32_bf16 v[114:117], v[2:5], v[114:117], 0
	s_waitcnt lgkmcnt(0)
	v_mfma_f32_16x16x32_bf16 v[114:117], v[6:9], v[128:131], v[114:117]
	ds_read_b128 v[128:131], v126 offset:12416
	ds_read_b128 v[142:145], v126 offset:12480
	s_waitcnt lgkmcnt(1)
	v_mfma_f32_16x16x32_bf16 v[114:117], v[10:13], v[128:131], v[114:117]
	s_waitcnt lgkmcnt(0)
	v_mfma_f32_16x16x32_bf16 v[114:117], v[14:17], v[142:145], v[114:117]
	s_and_saveexec_b64 s[4:5], s[10:11]
	s_nop 6
	ds_write_b128 v125, v[114:117] offset:2816
	s_or_b64 exec, exec, s[4:5]
	ds_read2_b32 v[208:209], v121 offset0:224 offset1:228
	ds_read2_b32 v[210:211], v121 offset0:232 offset1:236
	s_waitcnt vmcnt(23)
	ds_write_b128 v120, v[26:29] offset:7168
	s_waitcnt vmcnt(22)
	ds_write_b128 v120, v[30:33] offset:8448
	s_waitcnt vmcnt(21)
	ds_write_b128 v120, v[50:53] offset:9728
	s_waitcnt vmcnt(20)
	ds_write_b128 v120, v[54:57] offset:11008
	s_waitcnt vmcnt(19)
	ds_write_b128 v120, v[82:85] offset:12288
	s_waitcnt vmcnt(18)
	ds_write_b128 v120, v[86:89] offset:13568
	s_waitcnt vmcnt(17)
	ds_write_b128 v120, v[98:101] offset:14848
	s_waitcnt vmcnt(16)
	ds_write_b128 v120, v[102:105] offset:16128
	s_nop 0
	s_nop 0
	s_waitcnt lgkmcnt(1)
	v_add_u32_e32 v28, s48, v208
	v_add_u32_e32 v26, s48, v209
	v_ashrrev_i32_e32 v29, 31, v28
	v_ashrrev_i32_e32 v27, 31, v26
	v_lshlrev_b64 v[28:29], 9, v[28:29]
	v_lshlrev_b64 v[26:27], 9, v[26:27]
	v_lshl_add_u64 v[28:29], v[118:119], 0, v[28:29]
	v_lshl_add_u64 v[30:31], v[118:119], 0, v[26:27]
	global_load_dwordx4 v[26:29], v[28:29], off
	s_nop 0
	global_load_dwordx4 v[30:33], v[30:31], off
	ds_read2_b32 v[82:83], v121 offset0:240 offset1:244
	s_waitcnt lgkmcnt(1)
	v_add_u32_e32 v52, s48, v210
	v_add_u32_e32 v50, s48, v211
	v_ashrrev_i32_e32 v53, 31, v52
	v_ashrrev_i32_e32 v51, 31, v50
	v_lshlrev_b64 v[52:53], 9, v[52:53]
	v_lshlrev_b64 v[50:51], 9, v[50:51]
	v_lshl_add_u64 v[52:53], v[118:119], 0, v[52:53]
	v_lshl_add_u64 v[54:55], v[118:119], 0, v[50:51]
	global_load_dwordx4 v[50:53], v[52:53], off
	s_nop 0
	global_load_dwordx4 v[54:57], v[54:55], off
	s_waitcnt lgkmcnt(0)
	v_add_u32_e32 v84, s48, v82
	v_add_u32_e32 v82, s48, v83
	ds_read2_b32 v[114:115], v121 offset0:248 offset1:252
	v_ashrrev_i32_e32 v85, 31, v84
	v_ashrrev_i32_e32 v83, 31, v82
	v_lshlrev_b64 v[84:85], 9, v[84:85]
	v_lshlrev_b64 v[82:83], 9, v[82:83]
	v_lshl_add_u64 v[84:85], v[118:119], 0, v[84:85]
	v_lshl_add_u64 v[86:87], v[118:119], 0, v[82:83]
	global_load_dwordx4 v[82:85], v[84:85], off
	s_nop 0
	global_load_dwordx4 v[86:89], v[86:87], off
	ds_read_b128 v[98:101], v126 offset:7168
	s_waitcnt lgkmcnt(1)
	v_add_u32_e32 v102, s48, v114
	v_ashrrev_i32_e32 v103, 31, v102
	v_lshlrev_b64 v[102:103], 9, v[102:103]
	v_lshl_add_u64 v[142:143], v[118:119], 0, v[102:103]
	ds_read_b128 v[102:105], v126 offset:7232
	s_waitcnt lgkmcnt(1)
	v_mfma_f32_16x16x32_bf16 v[98:101], v[2:5], v[98:101], 0
	v_add_u32_e32 v128, s48, v115
	ds_read_b128 v[114:117], v126 offset:7296
	v_ashrrev_i32_e32 v129, 31, v128
	s_waitcnt lgkmcnt(1)
	v_mfma_f32_16x16x32_bf16 v[98:101], v[6:9], v[102:105], v[98:101]
	v_lshlrev_b64 v[102:103], 9, v[128:129]
	v_lshl_add_u64 v[102:103], v[118:119], 0, v[102:103]
	ds_read_b128 v[128:131], v126 offset:7360
	s_waitcnt lgkmcnt(1)
	v_mfma_f32_16x16x32_bf16 v[114:117], v[10:13], v[114:117], v[98:101]
	s_nop 2
	global_load_dwordx4 v[98:101], v[142:143], off
	s_nop 0
	global_load_dwordx4 v[102:105], v[102:103], off
	s_waitcnt lgkmcnt(0)
	v_mfma_f32_16x16x32_bf16 v[114:117], v[14:17], v[128:131], v[114:117]
	s_and_saveexec_b64 s[4:5], s[10:11]
	s_nop 6
	ds_write_b128 v125, v[114:117] offset:3072
	s_or_b64 exec, exec, s[4:5]
	ds_read_b128 v[114:117], v126 offset:12288
	ds_read_b128 v[128:131], v126 offset:12352
	s_waitcnt lgkmcnt(1)
	v_mfma_f32_16x16x32_bf16 v[114:117], v[2:5], v[114:117], 0
	s_waitcnt lgkmcnt(0)
	v_mfma_f32_16x16x32_bf16 v[114:117], v[6:9], v[128:131], v[114:117]
	ds_read_b128 v[128:131], v126 offset:12416
	ds_read_b128 v[142:145], v126 offset:12480
	s_waitcnt lgkmcnt(1)
	v_mfma_f32_16x16x32_bf16 v[114:117], v[10:13], v[128:131], v[114:117]
	s_waitcnt lgkmcnt(0)
	v_mfma_f32_16x16x32_bf16 v[114:117], v[14:17], v[142:145], v[114:117]
	s_and_saveexec_b64 s[4:5], s[10:11]
	s_nop 6
	ds_write_b128 v125, v[114:117] offset:3328
	s_or_b64 exec, exec, s[4:5]
	s_waitcnt vmcnt(23)
	ds_write_b128 v120, v[34:37] offset:7168
	s_waitcnt vmcnt(22)
	ds_write_b128 v120, v[38:41] offset:8448
	s_waitcnt vmcnt(21)
	ds_write_b128 v120, v[58:61] offset:9728
	s_waitcnt vmcnt(20)
	ds_write_b128 v120, v[62:65] offset:11008
	s_waitcnt vmcnt(19)
	ds_write_b128 v120, v[90:93] offset:12288
	s_waitcnt vmcnt(18)
	ds_write_b128 v120, v[94:97] offset:13568
	s_waitcnt vmcnt(17)
	ds_write_b128 v120, v[106:109] offset:14848
	s_waitcnt vmcnt(16)
	ds_write_b128 v120, v[110:113] offset:16128
	ds_read_b128 v[34:37], v126 offset:7168
	ds_read_b128 v[38:41], v126 offset:7232
	s_waitcnt lgkmcnt(1)
	v_mfma_f32_16x16x32_bf16 v[34:37], v[2:5], v[34:37], 0
	s_waitcnt lgkmcnt(0)
	v_mfma_f32_16x16x32_bf16 v[34:37], v[6:9], v[38:41], v[34:37]
	ds_read_b128 v[38:41], v126 offset:7296
	ds_read_b128 v[58:61], v126 offset:7360
	s_waitcnt lgkmcnt(1)
	v_mfma_f32_16x16x32_bf16 v[34:37], v[10:13], v[38:41], v[34:37]
	s_waitcnt lgkmcnt(0)
	v_mfma_f32_16x16x32_bf16 v[34:37], v[14:17], v[58:61], v[34:37]
	s_and_saveexec_b64 s[4:5], s[10:11]
	s_nop 6
	ds_write_b128 v125, v[34:37] offset:3584
	s_or_b64 exec, exec, s[4:5]
	ds_read_b128 v[34:37], v126 offset:12288
	ds_read_b128 v[38:41], v126 offset:12352
	s_waitcnt lgkmcnt(1)
	v_mfma_f32_16x16x32_bf16 v[34:37], v[2:5], v[34:37], 0
	s_waitcnt lgkmcnt(0)
	v_mfma_f32_16x16x32_bf16 v[34:37], v[6:9], v[38:41], v[34:37]
	ds_read_b128 v[38:41], v126 offset:12416
	ds_read_b128 v[58:61], v126 offset:12480
	s_waitcnt lgkmcnt(1)
	v_mfma_f32_16x16x32_bf16 v[34:37], v[10:13], v[38:41], v[34:37]
	s_waitcnt lgkmcnt(0)
	v_mfma_f32_16x16x32_bf16 v[34:37], v[14:17], v[58:61], v[34:37]
	s_and_saveexec_b64 s[4:5], s[10:11]
	s_nop 6
	ds_write_b128 v125, v[34:37] offset:3840
	s_or_b64 exec, exec, s[4:5]
	s_waitcnt vmcnt(15)
	ds_write_b128 v120, v[18:21] offset:7168
	s_waitcnt vmcnt(14)
	ds_write_b128 v120, v[22:25] offset:8448
	s_waitcnt vmcnt(13)
	ds_write_b128 v120, v[42:45] offset:9728
	s_waitcnt vmcnt(12)
	ds_write_b128 v120, v[46:49] offset:11008
	s_waitcnt vmcnt(11)
	ds_write_b128 v120, v[66:69] offset:12288
	s_waitcnt vmcnt(10)
	ds_write_b128 v120, v[70:73] offset:13568
	s_waitcnt vmcnt(9)
	ds_write_b128 v120, v[74:77] offset:14848
	s_waitcnt vmcnt(8)
	ds_write_b128 v120, v[78:81] offset:16128
	ds_read_b128 v[18:21], v126 offset:7168
	ds_read_b128 v[22:25], v126 offset:7232
	s_waitcnt lgkmcnt(1)
	v_mfma_f32_16x16x32_bf16 v[18:21], v[2:5], v[18:21], 0
	s_waitcnt lgkmcnt(0)
	v_mfma_f32_16x16x32_bf16 v[18:21], v[6:9], v[22:25], v[18:21]
	ds_read_b128 v[22:25], v126 offset:7296
	ds_read_b128 v[34:37], v126 offset:7360
	s_waitcnt lgkmcnt(1)
	v_mfma_f32_16x16x32_bf16 v[18:21], v[10:13], v[22:25], v[18:21]
	s_waitcnt lgkmcnt(0)
	v_mfma_f32_16x16x32_bf16 v[18:21], v[14:17], v[34:37], v[18:21]
	s_and_saveexec_b64 s[4:5], s[10:11]
	s_nop 6
	ds_write_b128 v125, v[18:21] offset:4096
	s_or_b64 exec, exec, s[4:5]
	ds_read_b128 v[18:21], v126 offset:12288
	ds_read_b128 v[22:25], v126 offset:12352
	s_waitcnt lgkmcnt(1)
	v_mfma_f32_16x16x32_bf16 v[18:21], v[2:5], v[18:21], 0
	s_waitcnt lgkmcnt(0)
	v_mfma_f32_16x16x32_bf16 v[18:21], v[6:9], v[22:25], v[18:21]
	ds_read_b128 v[22:25], v126 offset:12416
	ds_read_b128 v[34:37], v126 offset:12480
	s_waitcnt lgkmcnt(1)
	v_mfma_f32_16x16x32_bf16 v[18:21], v[10:13], v[22:25], v[18:21]
	s_waitcnt lgkmcnt(0)
	v_mfma_f32_16x16x32_bf16 v[18:21], v[14:17], v[34:37], v[18:21]
	s_and_saveexec_b64 s[4:5], s[10:11]
	s_nop 6
	ds_write_b128 v125, v[18:21] offset:4352
	s_or_b64 exec, exec, s[4:5]
	s_waitcnt vmcnt(7)
	ds_write_b128 v120, v[26:29] offset:7168
	s_waitcnt vmcnt(6)
	ds_write_b128 v120, v[30:33] offset:8448
	s_waitcnt vmcnt(5)
	ds_write_b128 v120, v[50:53] offset:9728
	s_waitcnt vmcnt(4)
	ds_write_b128 v120, v[54:57] offset:11008
	s_waitcnt vmcnt(3)
	ds_write_b128 v120, v[82:85] offset:12288
	s_waitcnt vmcnt(2)
	ds_write_b128 v120, v[86:89] offset:13568
	s_waitcnt vmcnt(1)
	ds_write_b128 v120, v[98:101] offset:14848
	s_waitcnt vmcnt(0)
	ds_write_b128 v120, v[102:105] offset:16128
	ds_read_b128 v[18:21], v126 offset:7168
	ds_read_b128 v[22:25], v126 offset:7232
	s_waitcnt lgkmcnt(1)
	v_mfma_f32_16x16x32_bf16 v[18:21], v[2:5], v[18:21], 0
	s_waitcnt lgkmcnt(0)
	v_mfma_f32_16x16x32_bf16 v[18:21], v[6:9], v[22:25], v[18:21]
	ds_read_b128 v[22:25], v126 offset:7296
	ds_read_b128 v[26:29], v126 offset:7360
	s_waitcnt lgkmcnt(1)
	v_mfma_f32_16x16x32_bf16 v[18:21], v[10:13], v[22:25], v[18:21]
	s_waitcnt lgkmcnt(0)
	v_mfma_f32_16x16x32_bf16 v[18:21], v[14:17], v[26:29], v[18:21]
	s_and_saveexec_b64 s[4:5], s[10:11]
	s_nop 6
	ds_write_b128 v125, v[18:21] offset:4608
	s_or_b64 exec, exec, s[4:5]
	ds_read_b128 v[18:21], v126 offset:12288
	ds_read_b128 v[22:25], v126 offset:12352
	s_lshl_b32 s8, s7, 7
	s_waitcnt lgkmcnt(1)
	v_mfma_f32_16x16x32_bf16 v[2:5], v[2:5], v[18:21], 0
	s_waitcnt lgkmcnt(0)
	v_mfma_f32_16x16x32_bf16 v[2:5], v[6:9], v[22:25], v[2:5]
	ds_read_b128 v[6:9], v126 offset:12416
	ds_read_b128 v[18:21], v126 offset:12480
	s_waitcnt lgkmcnt(1)
	v_mfma_f32_16x16x32_bf16 v[2:5], v[10:13], v[6:9], v[2:5]
	s_waitcnt lgkmcnt(0)
	v_mfma_f32_16x16x32_bf16 v[2:5], v[14:17], v[18:21], v[2:5]
	s_and_saveexec_b64 s[4:5], s[10:11]
	s_nop 6
	ds_write_b128 v125, v[2:5] offset:4864
	s_or_b64 exec, exec, s[4:5]
	v_readlane_b32 s16, v251, 19
	v_readlane_b32 s17, v251, 20
	v_readlane_b32 s18, v251, 21
	v_readlane_b32 s19, v251, 22
	v_readlane_b32 s20, v251, 23
	v_readlane_b32 s21, v251, 24
	v_readlane_b32 s22, v251, 25
	v_readlane_b32 s23, v251, 26
	v_readlane_b32 s24, v251, 27
	v_readlane_b32 s25, v251, 28
	ds_read2_b32 v[2:3], v121 offset1:4
	v_readlane_b32 s26, v251, 29
	v_readlane_b32 s27, v251, 30
	v_readlane_b32 s28, v251, 31
	v_readlane_b32 s29, v251, 32
	v_readlane_b32 s30, v251, 33
	v_readlane_b32 s31, v251, 34
	s_mov_b64 s[16:17], s[24:25]
	s_lshl_b32 s4, s8, 1
	s_mov_b64 s[20:21], s[28:29]
	v_lshlrev_b32_e32 v4, 3, v1
	s_add_u32 s4, s20, s4
	s_addc_u32 s5, s21, 0
	v_lshlrev_b32_e32 v4, 1, v4
	v_mov_b32_e32 v5, v135
	v_lshl_add_u64 v[114:115], s[4:5], 0, v[4:5]
	ds_read2_b32 v[4:5], v121 offset0:8 offset1:12
	s_waitcnt lgkmcnt(1)
	v_add_u32_e32 v6, s48, v2
	v_ashrrev_i32_e32 v7, 31, v6
	v_add_u32_e32 v2, s48, v3
	v_lshlrev_b64 v[6:7], 9, v[6:7]
	v_ashrrev_i32_e32 v3, 31, v2
	v_lshl_add_u64 v[6:7], v[114:115], 0, v[6:7]
	v_lshlrev_b64 v[2:3], 9, v[2:3]
	v_lshl_add_u64 v[2:3], v[114:115], 0, v[2:3]
	global_load_dwordx4 v[66:69], v[6:7], off
	global_load_dwordx4 v[70:73], v[2:3], off
	ds_read2_b32 v[6:7], v121 offset0:16 offset1:20
	s_waitcnt lgkmcnt(1)
	v_add_u32_e32 v2, s48, v4
	v_add_u32_e32 v4, s48, v5
	v_ashrrev_i32_e32 v3, 31, v2
	v_ashrrev_i32_e32 v5, 31, v4
	v_lshlrev_b64 v[2:3], 9, v[2:3]
	v_lshlrev_b64 v[4:5], 9, v[4:5]
	v_lshl_add_u64 v[2:3], v[114:115], 0, v[2:3]
	v_lshl_add_u64 v[4:5], v[114:115], 0, v[4:5]
	global_load_dwordx4 v[74:77], v[2:3], off
	global_load_dwordx4 v[78:81], v[4:5], off
	s_waitcnt lgkmcnt(0)
	v_add_u32_e32 v2, s48, v6
	v_add_u32_e32 v4, s48, v7
	ds_read2_b32 v[6:7], v121 offset0:24 offset1:28
	v_ashrrev_i32_e32 v3, 31, v2
	v_ashrrev_i32_e32 v5, 31, v4
	v_lshlrev_b64 v[2:3], 9, v[2:3]
	v_lshlrev_b64 v[4:5], 9, v[4:5]
	v_lshl_add_u64 v[2:3], v[114:115], 0, v[2:3]
	v_lshl_add_u64 v[4:5], v[114:115], 0, v[4:5]
	global_load_dwordx4 v[82:85], v[2:3], off
	global_load_dwordx4 v[86:89], v[4:5], off
	s_waitcnt lgkmcnt(0)
	v_add_u32_e32 v2, s48, v6
	v_add_u32_e32 v4, s48, v7
	ds_read2_b32 v[6:7], v121 offset0:32 offset1:36
	v_ashrrev_i32_e32 v3, 31, v2
	v_ashrrev_i32_e32 v5, 31, v4
	v_lshlrev_b64 v[2:3], 9, v[2:3]
	v_lshlrev_b64 v[4:5], 9, v[4:5]
	v_lshl_add_u64 v[2:3], v[114:115], 0, v[2:3]
	v_lshl_add_u64 v[4:5], v[114:115], 0, v[4:5]
	global_load_dwordx4 v[90:93], v[2:3], off
	global_load_dwordx4 v[94:97], v[4:5], off
	s_waitcnt lgkmcnt(0)
	v_add_u32_e32 v2, s48, v6
	v_add_u32_e32 v4, s48, v7
	ds_read2_b32 v[6:7], v121 offset0:40 offset1:44
	v_ashrrev_i32_e32 v3, 31, v2
	v_ashrrev_i32_e32 v5, 31, v4
	v_lshlrev_b64 v[2:3], 9, v[2:3]
	v_lshlrev_b64 v[4:5], 9, v[4:5]
	v_lshl_add_u64 v[2:3], v[114:115], 0, v[2:3]
	v_lshl_add_u64 v[4:5], v[114:115], 0, v[4:5]
	global_load_dwordx4 v[18:21], v[2:3], off
	global_load_dwordx4 v[22:25], v[4:5], off
	s_waitcnt lgkmcnt(0)
	v_add_u32_e32 v2, s48, v6
	v_add_u32_e32 v4, s48, v7
	ds_read2_b32 v[6:7], v121 offset0:48 offset1:52
	v_ashrrev_i32_e32 v3, 31, v2
	v_ashrrev_i32_e32 v5, 31, v4
	v_lshlrev_b64 v[2:3], 9, v[2:3]
	v_lshlrev_b64 v[4:5], 9, v[4:5]
	v_lshl_add_u64 v[2:3], v[114:115], 0, v[2:3]
	v_lshl_add_u64 v[4:5], v[114:115], 0, v[4:5]
	global_load_dwordx4 v[34:37], v[2:3], off
	global_load_dwordx4 v[38:41], v[4:5], off
	s_waitcnt lgkmcnt(0)
	v_add_u32_e32 v2, s48, v6
	v_add_u32_e32 v4, s48, v7
	ds_read2_b32 v[6:7], v121 offset0:56 offset1:60
	v_ashrrev_i32_e32 v3, 31, v2
	v_ashrrev_i32_e32 v5, 31, v4
	v_lshlrev_b64 v[2:3], 9, v[2:3]
	v_lshlrev_b64 v[4:5], 9, v[4:5]
	v_lshl_add_u64 v[2:3], v[114:115], 0, v[2:3]
	v_lshl_add_u64 v[4:5], v[114:115], 0, v[4:5]
	global_load_dwordx4 v[42:45], v[2:3], off
	global_load_dwordx4 v[46:49], v[4:5], off
	s_waitcnt lgkmcnt(0)
	v_add_u32_e32 v2, s48, v6
	v_add_u32_e32 v4, s48, v7
	v_ashrrev_i32_e32 v3, 31, v2
	v_ashrrev_i32_e32 v5, 31, v4
	v_lshlrev_b64 v[2:3], 9, v[2:3]
	v_lshlrev_b64 v[4:5], 9, v[4:5]
	v_lshl_add_u64 v[2:3], v[114:115], 0, v[2:3]
	v_lshl_add_u64 v[4:5], v[114:115], 0, v[4:5]
	ds_read2_b32 v[6:7], v121 offset0:64 offset1:68
	global_load_dwordx4 v[50:53], v[2:3], off
	global_load_dwordx4 v[54:57], v[4:5], off
	v_lshl_add_u32 v4, v124, 4, v138
	ds_read_b128 v[102:105], v4 offset:3072
	ds_read_b128 v[98:101], v4 offset:4096
	ds_read_b128 v[110:113], v4 offset:1024
	ds_read_b128 v[106:109], v4 offset:2048
	s_waitcnt lgkmcnt(4)
	v_add_u32_e32 v2, s48, v6
	ds_read2_b32 v[10:11], v121 offset0:72 offset1:76
	s_waitcnt lgkmcnt(4)
	v_max_f32_e32 v5, v102, v102
	s_waitcnt lgkmcnt(3)
	v_max_f32_e32 v4, v98, v98
	v_max_f32_e32 v4, v5, v4
	s_waitcnt lgkmcnt(1)
	v_max3_f32 v6, v110, v106, v4
	ds_bpermute_b32 v8, v132, v6
	v_add_u32_e32 v4, s48, v7
	s_waitcnt lgkmcnt(1)
	v_add_u32_e32 v12, s48, v10
	v_ashrrev_i32_e32 v3, 31, v2
	v_ashrrev_i32_e32 v5, 31, v4
	s_waitcnt lgkmcnt(0)
	v_max_f32_e32 v7, v8, v8
	v_max_f32_e32 v13, v6, v7
	ds_bpermute_b32 v14, v133, v13
	v_lshlrev_b64 v[2:3], 9, v[2:3]
	v_lshlrev_b64 v[4:5], 9, v[4:5]
	v_lshl_add_u64 v[2:3], v[114:115], 0, v[2:3]
	v_lshl_add_u64 v[6:7], v[114:115], 0, v[4:5]
	s_waitcnt lgkmcnt(0)
	v_max_f32_e32 v10, v14, v14
	v_max_f32_e32 v14, v13, v10
	ds_bpermute_b32 v15, v136, v14
	v_add_u32_e32 v10, s48, v11
	global_load_dwordx4 v[2:5], v[2:3], off
	s_nop 0
	global_load_dwordx4 v[6:9], v[6:7], off
	ds_read2_b32 v[26:27], v121 offset0:80 offset1:84
	v_ashrrev_i32_e32 v13, 31, v12
	s_waitcnt lgkmcnt(1)
	v_max_f32_e32 v11, v15, v15
	v_max_f32_e32 v16, v14, v11
	ds_bpermute_b32 v17, v137, v16
	v_ashrrev_i32_e32 v11, 31, v10
	v_lshlrev_b64 v[10:11], 9, v[10:11]
	v_lshl_add_u64 v[14:15], v[114:115], 0, v[10:11]
	s_waitcnt lgkmcnt(1)
	v_add_u32_e32 v28, s48, v26
	s_waitcnt lgkmcnt(0)
	v_max_f32_e32 v10, v17, v17
	v_max_f32_e32 v30, v16, v10
	ds_bpermute_b32 v31, v139, v30
	v_lshlrev_b64 v[12:13], 9, v[12:13]
	v_lshl_add_u64 v[12:13], v[114:115], 0, v[12:13]
	global_load_dwordx4 v[10:13], v[12:13], off
	s_nop 0
	global_load_dwordx4 v[14:17], v[14:15], off
	ds_read2_b32 v[58:59], v121 offset0:88 offset1:92
	s_waitcnt lgkmcnt(1)
	v_max_f32_e32 v26, v31, v31
	v_max_f32_e32 v30, v30, v26
	ds_bpermute_b32 v31, v140, v30
	v_max_f32_e32 v64, v103, v103
	v_lshlrev_b32_e32 v116, 3, v123
	v_add_u32_e32 v26, s48, v27
	v_ashrrev_i32_e32 v29, 31, v28
	s_waitcnt lgkmcnt(0)
	v_max_f32_e32 v31, v31, v31
	v_max_f32_e32 v30, v30, v31
	v_sub_f32_e32 v31, v110, v30
	v_mul_f32_e32 v31, 0x3fb8aa3b, v31
	v_exp_f32_e32 v110, v31
	v_sub_f32_e32 v31, v106, v30
	v_mul_f32_e32 v31, 0x3fb8aa3b, v31
	v_exp_f32_e32 v106, v31
	v_sub_f32_e32 v31, v102, v30
	v_mul_f32_e32 v31, 0x3fb8aa3b, v31
	v_sub_f32_e32 v30, v98, v30
	v_exp_f32_e32 v102, v31
	v_mul_f32_e32 v30, 0x3fb8aa3b, v30
	v_exp_f32_e32 v98, v30
	v_add_f32_e32 v30, 0, v110
	v_add_f32_e32 v30, v106, v30
	v_add_f32_e32 v30, v102, v30
	v_add_f32_e32 v60, v98, v30
	ds_bpermute_b32 v61, v132, v60
	v_ashrrev_i32_e32 v27, 31, v26
	v_lshlrev_b64 v[28:29], 9, v[28:29]
	v_lshlrev_b64 v[26:27], 9, v[26:27]
	v_lshl_add_u64 v[28:29], v[114:115], 0, v[28:29]
	s_waitcnt lgkmcnt(0)
	v_add_f32_e32 v62, v60, v61
	ds_bpermute_b32 v63, v133, v62
	v_add_u32_e32 v60, s48, v58
	v_max_f32_e32 v58, v99, v99
	v_max_f32_e32 v58, v64, v58
	v_max3_f32 v64, v111, v107, v58
	s_waitcnt lgkmcnt(0)
	v_add_f32_e32 v62, v62, v63
	ds_bpermute_b32 v63, v136, v62
	ds_bpermute_b32 v65, v132, v64
	v_add_u32_e32 v58, s48, v59
	v_ashrrev_i32_e32 v59, 31, v58
	v_lshlrev_b64 v[58:59], 9, v[58:59]
	s_waitcnt lgkmcnt(1)
	v_add_f32_e32 v117, v62, v63
	s_waitcnt lgkmcnt(0)
	v_max_f32_e32 v62, v65, v65
	v_max_f32_e32 v64, v64, v62
	ds_bpermute_b32 v65, v133, v64
	v_lshl_add_u64 v[62:63], v[114:115], 0, v[58:59]
	ds_bpermute_b32 v118, v137, v117
	v_ashrrev_i32_e32 v61, 31, v60
	v_lshlrev_b64 v[60:61], 9, v[60:61]
	s_waitcnt lgkmcnt(1)
	v_max_f32_e32 v58, v65, v65
	v_max_f32_e32 v119, v64, v58
	ds_bpermute_b32 v123, v136, v119
	s_waitcnt lgkmcnt(1)
	v_add_f32_e32 v117, v117, v118
	ds_bpermute_b32 v118, v139, v117
	v_lshl_add_u64 v[30:31], v[114:115], 0, v[26:27]
	v_lshl_add_u64 v[60:61], v[114:115], 0, v[60:61]
	s_waitcnt lgkmcnt(1)
	v_max_f32_e32 v123, v123, v123
	v_max_f32_e32 v119, v119, v123
	ds_bpermute_b32 v123, v137, v119
	s_waitcnt lgkmcnt(1)
	v_add_f32_e32 v117, v117, v118
	ds_bpermute_b32 v118, v140, v117
	v_lshl_add_u32 v124, v124, 1, v138
	global_load_dwordx4 v[26:29], v[28:29], off
	s_nop 0
	global_load_dwordx4 v[30:33], v[30:31], off
	s_waitcnt lgkmcnt(1)
	v_max_f32_e32 v123, v123, v123
	v_max_f32_e32 v119, v119, v123
	ds_bpermute_b32 v123, v139, v119
	s_waitcnt lgkmcnt(1)
	v_add_f32_e32 v117, v117, v118
	v_div_scale_f32 v118, s[4:5], v117, v117, 1.0
	v_rcp_f32_e32 v125, v118
	s_waitcnt lgkmcnt(0)
	v_max_f32_e32 v123, v123, v123
	v_max_f32_e32 v119, v119, v123
	ds_bpermute_b32 v123, v140, v119
	v_fma_f32 v126, -v118, v125, 1.0
	v_fmac_f32_e32 v125, v126, v125
	v_div_scale_f32 v126, vcc, 1.0, v117, 1.0
	s_waitcnt lgkmcnt(0)
	v_max_f32_e32 v123, v123, v123
	v_max_f32_e32 v119, v119, v123
	v_sub_f32_e32 v111, v111, v119
	v_mul_f32_e32 v111, 0x3fb8aa3b, v111
	v_sub_f32_e32 v107, v107, v119
	v_exp_f32_e32 v111, v111
	v_mul_f32_e32 v107, 0x3fb8aa3b, v107
	v_sub_f32_e32 v103, v103, v119
	v_exp_f32_e32 v107, v107
	v_mul_f32_e32 v103, 0x3fb8aa3b, v103
	v_sub_f32_e32 v99, v99, v119
	v_exp_f32_e32 v103, v103
	v_mul_f32_e32 v99, 0x3fb8aa3b, v99
	v_exp_f32_e32 v99, v99
	v_add_f32_e32 v119, 0, v111
	v_add_f32_e32 v119, v107, v119
	v_add_f32_e32 v119, v103, v119
	v_add_f32_e32 v119, v99, v119
	v_mul_f32_e32 v127, v126, v125
	ds_bpermute_b32 v123, v132, v119
	v_fma_f32 v128, -v118, v127, v126
	v_fmac_f32_e32 v127, v128, v125
	v_fma_f32 v118, -v118, v127, v126
	v_div_fmas_f32 v118, v118, v125, v127
	v_div_fixup_f32 v117, v118, v117, 1.0
	s_waitcnt lgkmcnt(0)
	v_add_f32_e32 v118, v119, v123
	ds_bpermute_b32 v119, v133, v118
	v_mul_f32_e32 v106, v106, v117
	v_cvt_pk_bf16_f32 v106, v106, s0
	global_load_dwordx4 v[58:61], v[60:61], off
	s_nop 0
	global_load_dwordx4 v[62:65], v[62:63], off
	ds_write_b16 v124, v106 offset:5248
	s_waitcnt lgkmcnt(1)
	v_add_f32_e32 v106, v118, v119
	v_max_f32_e32 v118, v100, v100
	v_max_f32_e32 v119, v104, v104
	v_max_f32_e32 v118, v119, v118
	v_mul_f32_e32 v110, v110, v117
	v_max3_f32 v118, v112, v108, v118
	v_cvt_pk_bf16_f32 v110, v110, s0
	ds_bpermute_b32 v119, v132, v118
	ds_write_b16 v124, v110 offset:5120
	ds_bpermute_b32 v110, v136, v106
	v_mul_f32_e32 v102, v102, v117
	v_cvt_pk_bf16_f32 v102, v102, s0
	s_waitcnt lgkmcnt(2)
	v_max_f32_e32 v119, v119, v119
	v_max_f32_e32 v118, v118, v119
	s_waitcnt lgkmcnt(0)
	v_add_f32_e32 v106, v106, v110
	ds_bpermute_b32 v110, v137, v106
	ds_bpermute_b32 v119, v133, v118
	ds_write_b16 v124, v102 offset:5376
	v_mul_f32_e32 v98, v98, v117
	v_cvt_pk_bf16_f32 v98, v98, s0
	s_waitcnt lgkmcnt(2)
	v_add_f32_e32 v102, v106, v110
	s_waitcnt lgkmcnt(1)
	v_max_f32_e32 v110, v119, v119
	v_max_f32_e32 v110, v118, v110
	ds_bpermute_b32 v117, v136, v110
	ds_write_b16 v124, v98 offset:5504
	ds_bpermute_b32 v106, v139, v102
	s_mov_b64 s[18:19], s[26:27]
	s_mov_b64 s[22:23], s[30:31]
	s_waitcnt lgkmcnt(2)
	v_max_f32_e32 v98, v117, v117
	v_max_f32_e32 v98, v110, v98
	ds_bpermute_b32 v110, v137, v98
	s_waitcnt lgkmcnt(1)
	v_add_f32_e32 v102, v102, v106
	ds_bpermute_b32 v106, v140, v102
	s_waitcnt lgkmcnt(1)
	v_max_f32_e32 v110, v110, v110
	v_max_f32_e32 v98, v98, v110
	ds_bpermute_b32 v110, v139, v98
	s_waitcnt lgkmcnt(1)
	v_add_f32_e32 v102, v102, v106
	v_div_scale_f32 v106, s[4:5], v102, v102, 1.0
	v_rcp_f32_e32 v117, v106
	s_waitcnt lgkmcnt(0)
	v_max_f32_e32 v110, v110, v110
	v_max_f32_e32 v98, v98, v110
	ds_bpermute_b32 v110, v140, v98
	v_fma_f32 v118, -v106, v117, 1.0
	v_fmac_f32_e32 v117, v118, v117
	v_div_scale_f32 v118, vcc, 1.0, v102, 1.0
	s_waitcnt lgkmcnt(0)
	v_max_f32_e32 v110, v110, v110
	v_max_f32_e32 v98, v98, v110
	v_sub_f32_e32 v110, v112, v98
	v_mul_f32_e32 v110, 0x3fb8aa3b, v110
	v_sub_f32_e32 v108, v108, v98
	v_exp_f32_e32 v110, v110
	v_mul_f32_e32 v108, 0x3fb8aa3b, v108
	v_sub_f32_e32 v104, v104, v98
	v_exp_f32_e32 v108, v108
	v_mul_f32_e32 v104, 0x3fb8aa3b, v104
	v_sub_f32_e32 v98, v100, v98
	v_mul_f32_e32 v119, v118, v117
	v_exp_f32_e32 v104, v104
	v_mul_f32_e32 v98, 0x3fb8aa3b, v98
	v_fma_f32 v123, -v106, v119, v118
	v_exp_f32_e32 v98, v98
	v_fmac_f32_e32 v119, v123, v117
	v_add_f32_e32 v100, 0, v110
	v_fma_f32 v106, -v106, v119, v118
	v_add_f32_e32 v100, v108, v100
	v_max_f32_e32 v118, v101, v101
	v_max_f32_e32 v123, v105, v105
	v_add_f32_e32 v100, v104, v100
	v_max_f32_e32 v118, v123, v118
	v_add_f32_e32 v100, v98, v100
	v_max3_f32 v118, v113, v109, v118
	ds_bpermute_b32 v112, v132, v100
	ds_bpermute_b32 v123, v132, v118
	v_div_fmas_f32 v106, v106, v117, v119
	v_div_fixup_f32 v102, v106, v102, 1.0
	v_mul_f32_e32 v111, v111, v102
	s_waitcnt lgkmcnt(1)
	v_add_f32_e32 v100, v100, v112
	s_waitcnt lgkmcnt(0)
	v_max_f32_e32 v112, v123, v123
	v_max_f32_e32 v112, v118, v112
	ds_bpermute_b32 v117, v133, v112
	ds_bpermute_b32 v106, v133, v100
	v_cvt_pk_bf16_f32 v111, v111, s0
	ds_write_b16 v124, v111 offset:5632
	v_mul_f32_e32 v107, v107, v102
	s_waitcnt lgkmcnt(2)
	v_max_f32_e32 v117, v117, v117
	v_max_f32_e32 v112, v112, v117
	ds_bpermute_b32 v117, v136, v112
	s_waitcnt lgkmcnt(2)
	v_add_f32_e32 v100, v100, v106
	ds_bpermute_b32 v106, v136, v100
	v_cvt_pk_bf16_f32 v107, v107, s0
	ds_write_b16 v124, v107 offset:5760
	s_waitcnt lgkmcnt(2)
	v_max_f32_e32 v111, v117, v117
	v_max_f32_e32 v111, v112, v111
	ds_bpermute_b32 v112, v137, v111
	s_waitcnt lgkmcnt(2)
	v_add_f32_e32 v100, v100, v106
	ds_bpermute_b32 v106, v137, v100
	v_mul_f32_e32 v103, v103, v102
	v_mul_f32_e32 v99, v99, v102
	s_waitcnt lgkmcnt(1)
	v_max_f32_e32 v107, v112, v112
	v_max_f32_e32 v107, v111, v107
	ds_bpermute_b32 v111, v139, v107
	s_waitcnt lgkmcnt(1)
	v_add_f32_e32 v100, v100, v106
	ds_bpermute_b32 v106, v139, v100
	v_cvt_pk_bf16_f32 v103, v103, s0
	ds_write_b16 v124, v103 offset:5888
	s_waitcnt lgkmcnt(2)
	v_max_f32_e32 v111, v111, v111
	v_max_f32_e32 v107, v107, v111
	ds_bpermute_b32 v111, v140, v107
	s_waitcnt lgkmcnt(2)
	v_add_f32_e32 v100, v100, v106
	ds_bpermute_b32 v106, v140, v100
	v_cvt_pk_bf16_f32 v99, v99, s0
	ds_write_b16 v124, v99 offset:6016
	s_waitcnt lgkmcnt(2)
	v_max_f32_e32 v102, v111, v111
	v_max_f32_e32 v102, v107, v102
	v_sub_f32_e32 v103, v113, v102
	s_waitcnt lgkmcnt(1)
	v_add_f32_e32 v100, v100, v106
	v_mul_f32_e32 v103, 0x3fb8aa3b, v103
	v_sub_f32_e32 v106, v109, v102
	v_exp_f32_e32 v103, v103
	v_mul_f32_e32 v106, 0x3fb8aa3b, v106
	v_sub_f32_e32 v105, v105, v102
	v_exp_f32_e32 v106, v106
	v_mul_f32_e32 v105, 0x3fb8aa3b, v105
	v_sub_f32_e32 v101, v101, v102
	v_exp_f32_e32 v105, v105
	v_mul_f32_e32 v101, 0x3fb8aa3b, v101
	v_exp_f32_e32 v101, v101
	v_add_f32_e32 v102, 0, v103
	v_add_f32_e32 v102, v106, v102
	v_add_f32_e32 v102, v105, v102
	v_add_f32_e32 v102, v101, v102
	ds_bpermute_b32 v107, v132, v102
	v_div_scale_f32 v109, s[4:5], v100, v100, 1.0
	v_rcp_f32_e32 v111, v109
	s_waitcnt lgkmcnt(0)
	v_add_f32_e32 v99, v102, v107
	ds_bpermute_b32 v102, v133, v99
	v_fma_f32 v107, -v109, v111, 1.0
	v_fmac_f32_e32 v111, v107, v111
	v_div_scale_f32 v107, vcc, 1.0, v100, 1.0
	s_waitcnt lgkmcnt(0)
	v_add_f32_e32 v99, v99, v102
	ds_bpermute_b32 v102, v136, v99
	v_mul_f32_e32 v112, v107, v111
	v_fma_f32 v113, -v109, v112, v107
	v_fmac_f32_e32 v112, v113, v111
	v_fma_f32 v107, -v109, v112, v107
	s_waitcnt lgkmcnt(0)
	v_add_f32_e32 v99, v99, v102
	ds_bpermute_b32 v102, v137, v99
	v_div_fmas_f32 v107, v107, v111, v112
	v_div_fixup_f32 v100, v107, v100, 1.0
	v_mul_f32_e32 v104, v104, v100
	v_cvt_pk_bf16_f32 v104, v104, s0
	s_waitcnt lgkmcnt(0)
	v_add_f32_e32 v99, v99, v102
	ds_bpermute_b32 v102, v139, v99
	ds_write_b16 v124, v104 offset:6400
	v_mul_f32_e32 v98, v98, v100
	v_mul_f32_e32 v107, v110, v100
	v_cvt_pk_bf16_f32 v98, v98, s0
	s_waitcnt lgkmcnt(1)
	v_add_f32_e32 v99, v99, v102
	ds_bpermute_b32 v102, v140, v99
	v_cvt_pk_bf16_f32 v107, v107, s0
	ds_write_b16 v124, v98 offset:6528
	ds_write_b16 v124, v107 offset:6144
	v_mul_f32_e32 v107, v108, v100
	s_waitcnt lgkmcnt(2)
	v_add_f32_e32 v99, v99, v102
	v_div_scale_f32 v102, s[4:5], v99, v99, 1.0
	v_rcp_f32_e32 v104, v102
	v_cvt_pk_bf16_f32 v107, v107, s0
	ds_write_b16 v124, v107 offset:6272
	v_fma_f32 v98, -v102, v104, 1.0
	v_fmac_f32_e32 v104, v98, v104
	v_div_scale_f32 v98, vcc, 1.0, v99, 1.0
	v_mul_f32_e32 v100, v98, v104
	v_fma_f32 v107, -v102, v100, v98
	v_fmac_f32_e32 v100, v107, v104
	v_fma_f32 v98, -v102, v100, v98
	v_div_fmas_f32 v98, v98, v104, v100
	v_div_fixup_f32 v98, v98, v99, 1.0
	v_mul_f32_e32 v99, v103, v98
	v_cvt_pk_bf16_f32 v99, v99, s0
	ds_write_b16 v124, v99 offset:6656
	v_mul_f32_e32 v99, v106, v98
	v_cvt_pk_bf16_f32 v99, v99, s0
	ds_write_b16 v124, v99 offset:6784
	v_mul_f32_e32 v99, v105, v98
	v_mul_f32_e32 v98, v101, v98
	v_cvt_pk_bf16_f32 v99, v99, s0
	v_cvt_pk_bf16_f32 v98, v98, s0
	ds_write_b16 v124, v99 offset:6912
	ds_write_b16 v124, v98 offset:7040
	ds_read2_b32 v[208:209], v121 offset0:96 offset1:100
	s_waitcnt vmcnt(23)
	ds_write_b128 v120, v[66:69] offset:7168
	s_waitcnt vmcnt(22)
	ds_write_b128 v120, v[70:73] offset:8448
	s_waitcnt vmcnt(21)
	ds_write_b128 v120, v[74:77] offset:9728
	s_waitcnt vmcnt(20)
	ds_write_b128 v120, v[78:81] offset:11008
	s_waitcnt vmcnt(19)
	ds_write_b128 v120, v[82:85] offset:12288
	s_waitcnt vmcnt(18)
	ds_write_b128 v120, v[86:89] offset:13568
	s_waitcnt vmcnt(17)
	ds_write_b128 v120, v[90:93] offset:14848
	s_waitcnt vmcnt(16)
	ds_write_b128 v120, v[94:97] offset:16128
	s_nop 0
	v_lshrrev_b32_e32 v98, 2, v1
	v_or_b32_e32 v98, v116, v98
	v_mul_u32_u24_e32 v68, 0x140, v98
	v_lshlrev_b32_e32 v69, 3, v122
	v_add3_u32 v116, v138, v68, v69
	s_waitcnt lgkmcnt(0)
	v_add_u32_e32 v68, s48, v208
	v_add_u32_e32 v66, s48, v209
	v_ashrrev_i32_e32 v69, 31, v68
	v_ashrrev_i32_e32 v67, 31, v66
	v_lshlrev_b64 v[68:69], 9, v[68:69]
	v_lshlrev_b64 v[66:67], 9, v[66:67]
	ds_read2_b32 v[74:75], v121 offset0:104 offset1:108
	v_lshl_add_u64 v[68:69], v[114:115], 0, v[68:69]
	v_lshl_add_u64 v[70:71], v[114:115], 0, v[66:67]
	global_load_dwordx4 v[66:69], v[68:69], off
	s_nop 0
	global_load_dwordx4 v[70:73], v[70:71], off
	ds_read2_b32 v[82:83], v121 offset0:112 offset1:116
	s_waitcnt lgkmcnt(1)
	v_add_u32_e32 v76, s48, v74
	v_add_u32_e32 v74, s48, v75
	v_ashrrev_i32_e32 v77, 31, v76
	v_ashrrev_i32_e32 v75, 31, v74
	s_waitcnt lgkmcnt(0)
	v_add_u32_e32 v84, s48, v82
	v_lshlrev_b32_e32 v99, 9, v122
	v_lshlrev_b64 v[76:77], 9, v[76:77]
	v_lshlrev_b64 v[74:75], 9, v[74:75]
	v_ashrrev_i32_e32 v85, 31, v84
	v_add3_u32 v117, v138, v99, v134
	v_lshl_add_u64 v[76:77], v[114:115], 0, v[76:77]
	v_lshl_add_u64 v[78:79], v[114:115], 0, v[74:75]
	v_lshlrev_b64 v[84:85], 9, v[84:85]
	global_load_dwordx4 v[74:77], v[76:77], off
	s_nop 0
	global_load_dwordx4 v[78:81], v[78:79], off
	v_lshl_add_u64 v[96:97], v[114:115], 0, v[84:85]
	v_add_u32_e32 v86, s48, v83
	ds_read_b128 v[82:85], v117 offset:5120
	v_ashrrev_i32_e32 v87, 31, v86
	v_lshlrev_b64 v[86:87], 9, v[86:87]
	v_lshl_add_u64 v[104:105], v[114:115], 0, v[86:87]
	ds_read_b64_tr_b16 v[86:87], v116 offset:7168
	s_waitcnt lgkmcnt(1)
	v_cndmask_b32_e64 v101, v85, 0, s[12:13]
	v_cndmask_b32_e64 v100, v84, 0, s[12:13]
	v_cndmask_b32_e64 v99, v83, 0, s[12:13]
	v_cndmask_b32_e64 v98, v82, 0, s[12:13]
	ds_read_b64_tr_b16 v[88:89], v116 offset:8448
	ds_read2_b32 v[108:109], v121 offset0:120 offset1:124
	ds_read_b64_tr_b16 v[90:91], v116 offset:7328
	ds_read_b64_tr_b16 v[102:103], v116 offset:7360
	ds_read_b64_tr_b16 v[106:107], v116 offset:7392
	ds_read_b64_tr_b16 v[84:85], v116 offset:8480
	ds_read_b64_tr_b16 v[82:83], v116 offset:7200
	ds_read_b64_tr_b16 v[92:93], v116 offset:7232
	ds_read_b64_tr_b16 v[122:123], v116 offset:7264
	ds_read_b64_tr_b16 v[126:127], v116 offset:7296
	ds_read_b64_tr_b16 v[94:95], v116 offset:8512
	ds_read_b64_tr_b16 v[124:125], v116 offset:8544
	ds_read_b64_tr_b16 v[128:129], v116 offset:8576
	s_waitcnt lgkmcnt(12)
	v_mfma_f32_16x16x32_bf16 v[110:113], v[98:101], v[86:89], 0
	s_waitcnt lgkmcnt(6)
	v_mfma_f32_16x16x32_bf16 v[142:145], v[98:101], v[82:85], 0
	global_load_dwordx4 v[82:85], v[96:97], off
	global_load_dwordx4 v[86:89], v[104:105], off
	v_add_u32_e32 v96, s48, v108
	v_ashrrev_i32_e32 v97, 31, v96
	s_waitcnt lgkmcnt(2)
	v_mfma_f32_16x16x32_bf16 v[146:149], v[98:101], v[92:95], 0
	v_lshlrev_b64 v[92:93], 9, v[96:97]
	v_lshl_add_u64 v[94:95], v[114:115], 0, v[92:93]
	ds_read_b64_tr_b16 v[92:93], v116 offset:8608
	v_add_u32_e32 v96, s48, v109
	v_ashrrev_i32_e32 v97, 31, v96
	v_lshlrev_b64 v[96:97], 9, v[96:97]
	v_lshl_add_u64 v[96:97], v[114:115], 0, v[96:97]
	ds_read_b64_tr_b16 v[104:105], v116 offset:8640
	ds_read_b64_tr_b16 v[108:109], v116 offset:8672
	s_waitcnt lgkmcnt(2)
	v_mfma_f32_16x16x32_bf16 v[150:153], v[98:101], v[90:93], 0
	global_load_dwordx4 v[90:93], v[94:95], off
	s_nop 0
	global_load_dwordx4 v[94:97], v[96:97], off
	ds_read2_b32 v[208:209], v121 offset0:128 offset1:132
	ds_read2_b32 v[210:211], v121 offset0:136 offset1:140
	s_waitcnt vmcnt(23)
	ds_write_b128 v120, v[18:21] offset:7168
	s_waitcnt vmcnt(22)
	ds_write_b128 v120, v[22:25] offset:8448
	s_waitcnt vmcnt(21)
	ds_write_b128 v120, v[34:37] offset:9728
	s_waitcnt vmcnt(20)
	ds_write_b128 v120, v[38:41] offset:11008
	s_waitcnt vmcnt(19)
	ds_write_b128 v120, v[42:45] offset:12288
	s_waitcnt vmcnt(18)
	ds_write_b128 v120, v[46:49] offset:13568
	s_waitcnt vmcnt(17)
	ds_write_b128 v120, v[50:53] offset:14848
	s_waitcnt vmcnt(16)
	ds_write_b128 v120, v[54:57] offset:16128
	s_nop 0
	s_nop 0
	v_mfma_f32_16x16x32_bf16 v[122:125], v[98:101], v[122:125], 0
	s_waitcnt lgkmcnt(1)
	v_add_u32_e32 v20, s48, v208
	v_add_u32_e32 v18, s48, v209
	v_ashrrev_i32_e32 v21, 31, v20
	v_ashrrev_i32_e32 v19, 31, v18
	v_lshlrev_b64 v[20:21], 9, v[20:21]
	v_lshlrev_b64 v[18:19], 9, v[18:19]
	v_lshl_add_u64 v[20:21], v[114:115], 0, v[20:21]
	v_lshl_add_u64 v[22:23], v[114:115], 0, v[18:19]
	global_load_dwordx4 v[18:21], v[20:21], off
	s_nop 0
	global_load_dwordx4 v[22:25], v[22:23], off
	ds_read2_b32 v[46:47], v121 offset0:144 offset1:148
	s_waitcnt lgkmcnt(1)
	v_add_u32_e32 v36, s48, v210
	v_add_u32_e32 v34, s48, v211
	v_ashrrev_i32_e32 v37, 31, v36
	v_ashrrev_i32_e32 v35, 31, v34
	s_waitcnt lgkmcnt(0)
	v_add_u32_e32 v48, s48, v46
	v_lshlrev_b64 v[36:37], 9, v[36:37]
	v_lshlrev_b64 v[34:35], 9, v[34:35]
	v_ashrrev_i32_e32 v49, 31, v48
	v_lshl_add_u64 v[36:37], v[114:115], 0, v[36:37]
	v_lshl_add_u64 v[38:39], v[114:115], 0, v[34:35]
	v_lshlrev_b64 v[48:49], 9, v[48:49]
	global_load_dwordx4 v[34:37], v[36:37], off
	s_nop 0
	global_load_dwordx4 v[38:41], v[38:39], off
	v_lshl_add_u64 v[54:55], v[114:115], 0, v[48:49]
	v_add_u32_e32 v50, s48, v47
	ds_read_b128 v[46:49], v117 offset:5184
	v_ashrrev_i32_e32 v51, 31, v50
	v_lshlrev_b64 v[50:51], 9, v[50:51]
	v_lshl_add_u64 v[56:57], v[114:115], 0, v[50:51]
	ds_read_b64_tr_b16 v[50:51], v116 offset:7168
	s_waitcnt lgkmcnt(1)
	v_cndmask_b32_e64 v49, v49, 0, s[12:13]
	v_cndmask_b32_e64 v48, v48, 0, s[12:13]
	v_cndmask_b32_e64 v47, v47, 0, s[12:13]
	v_cndmask_b32_e64 v46, v46, 0, s[12:13]
	v_mfma_f32_16x16x32_bf16 v[126:129], v[98:101], v[126:129], 0
	v_mfma_f32_16x16x32_bf16 v[154:157], v[98:101], v[102:105], 0
	v_mfma_f32_16x16x32_bf16 v[42:45], v[98:101], v[106:109], 0
	ds_read_b64_tr_b16 v[52:53], v116 offset:8448
	ds_read2_b32 v[104:105], v121 offset0:152 offset1:156
	ds_read_b64_tr_b16 v[98:99], v116 offset:7328
	ds_read_b64_tr_b16 v[106:107], v116 offset:7360
	ds_read_b64_tr_b16 v[158:159], v116 offset:7392
	s_waitcnt lgkmcnt(3)
	v_add_u32_e32 v108, s48, v104
	v_mfma_f32_16x16x32_bf16 v[110:113], v[46:49], v[50:53], v[110:113]
	ds_read_b64_tr_b16 v[52:53], v116 offset:8480
	ds_read_b64_tr_b16 v[50:51], v116 offset:7200
	ds_read_b64_tr_b16 v[100:101], v116 offset:7232
	ds_read_b64_tr_b16 v[160:161], v116 offset:7264
	ds_read_b64_tr_b16 v[164:165], v116 offset:7296
	ds_read_b64_tr_b16 v[102:103], v116 offset:8512
	ds_read_b64_tr_b16 v[162:163], v116 offset:8544
	ds_read_b64_tr_b16 v[166:167], v116 offset:8576
	v_ashrrev_i32_e32 v109, 31, v108
	v_add_u32_e32 v104, s48, v105
	s_waitcnt lgkmcnt(2)
	v_mfma_f32_16x16x32_bf16 v[146:149], v[46:49], v[100:103], v[146:149]
	v_lshlrev_b64 v[100:101], 9, v[108:109]
	v_lshl_add_u64 v[102:103], v[114:115], 0, v[100:101]
	v_ashrrev_i32_e32 v105, 31, v104
	v_mfma_f32_16x16x32_bf16 v[142:145], v[46:49], v[50:53], v[142:145]
	global_load_dwordx4 v[50:53], v[54:55], off
	s_nop 0
	global_load_dwordx4 v[54:57], v[56:57], off
	ds_read_b64_tr_b16 v[100:101], v116 offset:8608
	v_lshlrev_b64 v[104:105], 9, v[104:105]
	v_lshl_add_u64 v[104:105], v[114:115], 0, v[104:105]
	s_waitcnt lgkmcnt(2)
	v_mfma_f32_16x16x32_bf16 v[122:125], v[46:49], v[160:163], v[122:125]
	ds_read_b64_tr_b16 v[108:109], v116 offset:8640
	ds_read_b64_tr_b16 v[160:161], v116 offset:8672
	s_waitcnt lgkmcnt(2)
	v_mfma_f32_16x16x32_bf16 v[150:153], v[46:49], v[98:101], v[150:153]
	global_load_dwordx4 v[98:101], v[102:103], off
	s_nop 0
	global_load_dwordx4 v[102:105], v[104:105], off
	ds_read2_b32 v[208:209], v121 offset0:160 offset1:164
	ds_read2_b32 v[210:211], v121 offset0:168 offset1:172
	s_waitcnt vmcnt(23)
	ds_write_b128 v120, v[2:5] offset:7168
	s_waitcnt vmcnt(22)
	ds_write_b128 v120, v[6:9] offset:8448
	s_waitcnt vmcnt(21)
	ds_write_b128 v120, v[10:13] offset:9728
	s_waitcnt vmcnt(20)
	ds_write_b128 v120, v[14:17] offset:11008
	s_waitcnt vmcnt(19)
	ds_write_b128 v120, v[26:29] offset:12288
	s_waitcnt vmcnt(18)
	ds_write_b128 v120, v[30:33] offset:13568
	s_waitcnt vmcnt(17)
	ds_write_b128 v120, v[58:61] offset:14848
	s_waitcnt vmcnt(16)
	ds_write_b128 v120, v[62:65] offset:16128
	s_nop 0
	s_nop 0
	v_mfma_f32_16x16x32_bf16 v[126:129], v[46:49], v[164:167], v[126:129]
	s_waitcnt lgkmcnt(1)
	v_add_u32_e32 v4, s48, v208
	v_add_u32_e32 v2, s48, v209
	v_ashrrev_i32_e32 v5, 31, v4
	v_ashrrev_i32_e32 v3, 31, v2
	v_lshlrev_b64 v[4:5], 9, v[4:5]
	v_lshlrev_b64 v[2:3], 9, v[2:3]
	v_lshl_add_u64 v[4:5], v[114:115], 0, v[4:5]
	v_lshl_add_u64 v[6:7], v[114:115], 0, v[2:3]
	global_load_dwordx4 v[2:5], v[4:5], off
	s_nop 0
	global_load_dwordx4 v[6:9], v[6:7], off
	ds_read2_b32 v[30:31], v121 offset0:176 offset1:180
	s_waitcnt lgkmcnt(1)
	v_add_u32_e32 v12, s48, v210
	v_add_u32_e32 v10, s48, v211
	v_ashrrev_i32_e32 v13, 31, v12
	v_ashrrev_i32_e32 v11, 31, v10
	s_waitcnt lgkmcnt(0)
	v_add_u32_e32 v32, s48, v30
	v_lshlrev_b64 v[12:13], 9, v[12:13]
	v_lshlrev_b64 v[10:11], 9, v[10:11]
	v_ashrrev_i32_e32 v33, 31, v32
	v_lshl_add_u64 v[12:13], v[114:115], 0, v[12:13]
	v_lshl_add_u64 v[14:15], v[114:115], 0, v[10:11]
	v_lshlrev_b64 v[32:33], 9, v[32:33]
	v_mfma_f32_16x16x32_bf16 v[154:157], v[46:49], v[106:109], v[154:157]
	global_load_dwordx4 v[10:13], v[12:13], off
	s_nop 0
	global_load_dwordx4 v[14:17], v[14:15], off
	v_mfma_f32_16x16x32_bf16 v[26:29], v[46:49], v[158:161], v[42:45]
	v_lshl_add_u64 v[48:49], v[114:115], 0, v[32:33]
	s_nop 1
	v_add_u32_e32 v42, s48, v31
	ds_read_b128 v[30:33], v117 offset:5248
	v_ashrrev_i32_e32 v43, 31, v42
	v_lshlrev_b64 v[42:43], 9, v[42:43]
	v_lshl_add_u64 v[62:63], v[114:115], 0, v[42:43]
	ds_read_b64_tr_b16 v[42:43], v116 offset:7168
	s_waitcnt lgkmcnt(1)
	v_cndmask_b32_e64 v33, v33, 0, s[12:13]
	v_cndmask_b32_e64 v32, v32, 0, s[12:13]
	v_cndmask_b32_e64 v31, v31, 0, s[12:13]
	v_cndmask_b32_e64 v30, v30, 0, s[12:13]
	ds_read_b64_tr_b16 v[44:45], v116 offset:8448
	ds_read2_b32 v[118:119], v121 offset0:184 offset1:188
	ds_read_b64_tr_b16 v[46:47], v116 offset:7328
	ds_read_b64_tr_b16 v[158:159], v116 offset:7360
	ds_read_b64_tr_b16 v[162:163], v116 offset:7392
	s_waitcnt lgkmcnt(4)
	v_mfma_f32_16x16x32_bf16 v[166:169], v[30:33], v[42:45], v[110:113]
	ds_read_b64_tr_b16 v[44:45], v116 offset:8480
	ds_read_b64_tr_b16 v[42:43], v116 offset:7200
	ds_read_b64_tr_b16 v[106:107], v116 offset:7232
	ds_read_b64_tr_b16 v[110:111], v116 offset:7264
	ds_read_b64_tr_b16 v[170:171], v116 offset:7296
	ds_read_b64_tr_b16 v[108:109], v116 offset:8512
	ds_read_b64_tr_b16 v[112:113], v116 offset:8544
	ds_read_b64_tr_b16 v[172:173], v116 offset:8576
	global_load_dwordx4 v[58:61], v[48:49], off
	s_nop 0
	global_load_dwordx4 v[62:65], v[62:63], off
	ds_read_b64_tr_b16 v[48:49], v116 offset:8608
	s_waitcnt lgkmcnt(7)
	v_mfma_f32_16x16x32_bf16 v[142:145], v[30:33], v[42:45], v[142:145]
	v_add_u32_e32 v42, s48, v118
	v_ashrrev_i32_e32 v43, 31, v42
	v_add_u32_e32 v44, s48, v119
	v_lshlrev_b64 v[42:43], 9, v[42:43]
	v_ashrrev_i32_e32 v45, 31, v44
	v_lshl_add_u64 v[42:43], v[114:115], 0, v[42:43]
	v_lshlrev_b64 v[44:45], 9, v[44:45]
	s_waitcnt lgkmcnt(3)
	v_mfma_f32_16x16x32_bf16 v[146:149], v[30:33], v[106:109], v[146:149]
	ds_read_b64_tr_b16 v[160:161], v116 offset:8640
	ds_read_b64_tr_b16 v[164:165], v116 offset:8672
	v_lshl_add_u64 v[44:45], v[114:115], 0, v[44:45]
	s_waitcnt lgkmcnt(4)
	v_mfma_f32_16x16x32_bf16 v[122:125], v[30:33], v[110:113], v[122:125]
	global_load_dwordx4 v[106:109], v[42:43], off
	global_load_dwordx4 v[110:113], v[44:45], off
	ds_read2_b32 v[208:209], v121 offset0:192 offset1:196
	s_waitcnt vmcnt(23)
	ds_write_b128 v120, v[66:69] offset:7168
	s_waitcnt vmcnt(22)
	ds_write_b128 v120, v[70:73] offset:8448
	s_waitcnt vmcnt(21)
	ds_write_b128 v120, v[74:77] offset:9728
	s_waitcnt vmcnt(20)
	ds_write_b128 v120, v[78:81] offset:11008
	s_waitcnt vmcnt(19)
	ds_write_b128 v120, v[82:85] offset:12288
	s_waitcnt vmcnt(18)
	ds_write_b128 v120, v[86:89] offset:13568
	s_waitcnt vmcnt(17)
	ds_write_b128 v120, v[90:93] offset:14848
	s_waitcnt vmcnt(16)
	ds_write_b128 v120, v[94:97] offset:16128
	s_nop 0
	s_waitcnt lgkmcnt(9)
	v_mfma_f32_16x16x32_bf16 v[82:85], v[30:33], v[162:165], v[26:29]
	ds_read2_b32 v[44:45], v121 offset0:200 offset1:204
	s_waitcnt lgkmcnt(1)
	s_nop 0
	v_add_u32_e32 v26, s48, v208
	v_add_u32_e32 v28, s48, v209
	v_ashrrev_i32_e32 v27, 31, v26
	v_ashrrev_i32_e32 v29, 31, v28
	v_lshlrev_b64 v[26:27], 9, v[26:27]
	v_lshlrev_b64 v[28:29], 9, v[28:29]
	v_mfma_f32_16x16x32_bf16 v[126:129], v[30:33], v[170:173], v[126:129]
	v_lshl_add_u64 v[26:27], v[114:115], 0, v[26:27]
	s_waitcnt lgkmcnt(0)
	v_add_u32_e32 v42, s48, v44
	v_add_u32_e32 v44, s48, v45
	v_mfma_f32_16x16x32_bf16 v[150:153], v[30:33], v[46:49], v[150:153]
	v_ashrrev_i32_e32 v43, 31, v42
	v_ashrrev_i32_e32 v45, 31, v44
	v_lshlrev_b64 v[42:43], 9, v[42:43]
	v_mfma_f32_16x16x32_bf16 v[154:157], v[30:33], v[158:161], v[154:157]
	v_lshl_add_u64 v[30:31], v[114:115], 0, v[28:29]
	global_load_dwordx4 v[26:29], v[26:27], off
	s_nop 0
	global_load_dwordx4 v[30:33], v[30:31], off
	ds_read2_b32 v[66:67], v121 offset0:208 offset1:212
	v_lshlrev_b64 v[44:45], 9, v[44:45]
	v_lshl_add_u64 v[42:43], v[114:115], 0, v[42:43]
	v_lshl_add_u64 v[46:47], v[114:115], 0, v[44:45]
	global_load_dwordx4 v[42:45], v[42:43], off
	s_nop 0
	global_load_dwordx4 v[46:49], v[46:47], off
	s_waitcnt lgkmcnt(0)
	v_add_u32_e32 v68, s48, v66
	v_ashrrev_i32_e32 v69, 31, v68
	v_lshlrev_b64 v[68:69], 9, v[68:69]
	v_lshl_add_u64 v[80:81], v[114:115], 0, v[68:69]
	v_add_u32_e32 v70, s48, v67
	ds_read_b128 v[66:69], v117 offset:5312
	v_ashrrev_i32_e32 v71, 31, v70
	v_lshlrev_b64 v[70:71], 9, v[70:71]
	v_lshl_add_u64 v[92:93], v[114:115], 0, v[70:71]
	ds_read_b64_tr_b16 v[70:71], v116 offset:7168
	s_waitcnt lgkmcnt(1)
	v_cndmask_b32_e64 v89, v69, 0, s[12:13]
	v_cndmask_b32_e64 v88, v68, 0, s[12:13]
	v_cndmask_b32_e64 v87, v67, 0, s[12:13]
	v_cndmask_b32_e64 v86, v66, 0, s[12:13]
	ds_read_b64_tr_b16 v[72:73], v116 offset:8448
	ds_read2_b32 v[96:97], v121 offset0:216 offset1:220
	ds_read_b64_tr_b16 v[74:75], v116 offset:7328
	ds_read_b64_tr_b16 v[90:91], v116 offset:7360
	ds_read_b64_tr_b16 v[94:95], v116 offset:7392
	s_waitcnt lgkmcnt(4)
	v_mfma_f32_16x16x32_bf16 v[158:161], v[86:89], v[70:73], v[166:169]
	ds_read_b64_tr_b16 v[68:69], v116 offset:8480
	ds_read_b64_tr_b16 v[66:67], v116 offset:7200
	ds_read_b64_tr_b16 v[76:77], v116 offset:7232
	ds_read_b64_tr_b16 v[162:163], v116 offset:7264
	ds_read_b64_tr_b16 v[166:167], v116 offset:7296
	ds_read_b64_tr_b16 v[78:79], v116 offset:8512
	ds_read_b64_tr_b16 v[164:165], v116 offset:8544
	ds_read_b64_tr_b16 v[168:169], v116 offset:8576
	s_waitcnt lgkmcnt(6)
	v_mfma_f32_16x16x32_bf16 v[142:145], v[86:89], v[66:69], v[142:145]
	global_load_dwordx4 v[66:69], v[80:81], off
	global_load_dwordx4 v[70:73], v[92:93], off
	v_add_u32_e32 v80, s48, v96
	v_ashrrev_i32_e32 v81, 31, v80
	s_waitcnt lgkmcnt(2)
	v_mfma_f32_16x16x32_bf16 v[146:149], v[86:89], v[76:79], v[146:149]
	v_lshlrev_b64 v[76:77], 9, v[80:81]
	v_lshl_add_u64 v[78:79], v[114:115], 0, v[76:77]
	ds_read_b64_tr_b16 v[76:77], v116 offset:8608
	v_add_u32_e32 v80, s48, v97
	v_ashrrev_i32_e32 v81, 31, v80
	v_lshlrev_b64 v[80:81], 9, v[80:81]
	v_lshl_add_u64 v[80:81], v[114:115], 0, v[80:81]
	ds_read_b64_tr_b16 v[92:93], v116 offset:8640
	ds_read_b64_tr_b16 v[96:97], v116 offset:8672
	s_waitcnt lgkmcnt(2)
	v_mfma_f32_16x16x32_bf16 v[150:153], v[86:89], v[74:77], v[150:153]
	global_load_dwordx4 v[74:77], v[78:79], off
	s_nop 0
	global_load_dwordx4 v[78:81], v[80:81], off
	ds_read2_b32 v[208:209], v121 offset0:224 offset1:228
	ds_read2_b32 v[210:211], v121 offset0:232 offset1:236
	s_waitcnt vmcnt(23)
	ds_write_b128 v120, v[18:21] offset:7168
	s_waitcnt vmcnt(22)
	ds_write_b128 v120, v[22:25] offset:8448
	s_waitcnt vmcnt(21)
	ds_write_b128 v120, v[34:37] offset:9728
	s_waitcnt vmcnt(20)
	ds_write_b128 v120, v[38:41] offset:11008
	s_waitcnt vmcnt(19)
	ds_write_b128 v120, v[50:53] offset:12288
	s_waitcnt vmcnt(18)
	ds_write_b128 v120, v[54:57] offset:13568
	s_waitcnt vmcnt(17)
	ds_write_b128 v120, v[98:101] offset:14848
	s_waitcnt vmcnt(16)
	ds_write_b128 v120, v[102:105] offset:16128
	s_nop 0
	s_nop 0
	v_mfma_f32_16x16x32_bf16 v[122:125], v[86:89], v[162:165], v[122:125]
	s_waitcnt lgkmcnt(1)
	v_add_u32_e32 v20, s48, v208
	v_add_u32_e32 v18, s48, v209
	v_ashrrev_i32_e32 v21, 31, v20
	v_ashrrev_i32_e32 v19, 31, v18
	v_lshlrev_b64 v[20:21], 9, v[20:21]
	v_lshlrev_b64 v[18:19], 9, v[18:19]
	v_lshl_add_u64 v[20:21], v[114:115], 0, v[20:21]
	v_lshl_add_u64 v[22:23], v[114:115], 0, v[18:19]
	global_load_dwordx4 v[18:21], v[20:21], off
	s_nop 0
	global_load_dwordx4 v[22:25], v[22:23], off
	ds_read2_b32 v[54:55], v121 offset0:240 offset1:244
	s_waitcnt lgkmcnt(1)
	v_add_u32_e32 v36, s48, v210
	v_add_u32_e32 v34, s48, v211
	v_ashrrev_i32_e32 v37, 31, v36
	v_ashrrev_i32_e32 v35, 31, v34
	s_waitcnt lgkmcnt(0)
	v_add_u32_e32 v56, s48, v54
	v_lshlrev_b64 v[36:37], 9, v[36:37]
	v_lshlrev_b64 v[34:35], 9, v[34:35]
	v_ashrrev_i32_e32 v57, 31, v56
	v_lshl_add_u64 v[36:37], v[114:115], 0, v[36:37]
	v_lshl_add_u64 v[38:39], v[114:115], 0, v[34:35]
	v_lshlrev_b64 v[56:57], 9, v[56:57]
	v_mfma_f32_16x16x32_bf16 v[126:129], v[86:89], v[166:169], v[126:129]
	global_load_dwordx4 v[34:37], v[36:37], off
	s_nop 0
	global_load_dwordx4 v[38:41], v[38:39], off
	v_mfma_f32_16x16x32_bf16 v[90:93], v[86:89], v[90:93], v[154:157]
	v_mfma_f32_16x16x32_bf16 v[50:53], v[86:89], v[94:97], v[82:85]
	v_lshl_add_u64 v[88:89], v[114:115], 0, v[56:57]
	s_nop 1
	v_add_u32_e32 v82, s48, v55
	ds_read_b128 v[54:57], v117 offset:5376
	v_ashrrev_i32_e32 v83, 31, v82
	v_lshlrev_b64 v[82:83], 9, v[82:83]
	v_lshl_add_u64 v[96:97], v[114:115], 0, v[82:83]
	ds_read_b64_tr_b16 v[82:83], v116 offset:7168
	s_waitcnt lgkmcnt(1)
	v_cndmask_b32_e64 v57, v57, 0, s[12:13]
	v_cndmask_b32_e64 v56, v56, 0, s[12:13]
	v_cndmask_b32_e64 v55, v55, 0, s[12:13]
	v_cndmask_b32_e64 v54, v54, 0, s[12:13]
	ds_read_b64_tr_b16 v[84:85], v116 offset:8448
	ds_read2_b32 v[118:119], v121 offset0:248 offset1:252
	ds_read_b64_tr_b16 v[86:87], v116 offset:7328
	ds_read_b64_tr_b16 v[94:95], v116 offset:7360
	ds_read_b64_tr_b16 v[98:99], v116 offset:7392
	s_waitcnt lgkmcnt(4)
	v_mfma_f32_16x16x32_bf16 v[82:85], v[54:57], v[82:85], v[158:161]
	ds_read_b64_tr_b16 v[102:103], v116 offset:8480
	ds_read_b64_tr_b16 v[100:101], v116 offset:7200
	ds_read_b64_tr_b16 v[154:155], v116 offset:7232
	ds_read_b64_tr_b16 v[158:159], v116 offset:7264
	ds_read_b64_tr_b16 v[162:163], v116 offset:7296
	ds_read_b64_tr_b16 v[156:157], v116 offset:8512
	ds_read_b64_tr_b16 v[160:161], v116 offset:8544
	ds_read_b64_tr_b16 v[164:165], v116 offset:8576
	s_waitcnt lgkmcnt(6)
	v_mfma_f32_16x16x32_bf16 v[102:105], v[54:57], v[100:103], v[142:145]
	s_nop 2
	global_load_dwordx4 v[142:145], v[88:89], off
	global_load_dwordx4 v[166:169], v[96:97], off
	v_add_u32_e32 v88, s48, v118
	v_ashrrev_i32_e32 v89, 31, v88
	v_lshlrev_b64 v[88:89], 9, v[88:89]
	v_lshl_add_u64 v[130:131], v[114:115], 0, v[88:89]
	ds_read_b64_tr_b16 v[88:89], v116 offset:8608
	v_add_u32_e32 v96, s48, v119
	v_ashrrev_i32_e32 v97, 31, v96
	v_lshlrev_b64 v[118:119], 9, v[96:97]
	s_waitcnt lgkmcnt(3)
	v_mfma_f32_16x16x32_bf16 v[146:149], v[54:57], v[154:157], v[146:149]
	ds_read_b64_tr_b16 v[96:97], v116 offset:8640
	ds_read_b64_tr_b16 v[100:101], v116 offset:8672
	v_lshl_add_u64 v[114:115], v[114:115], 0, v[118:119]
	s_waitcnt lgkmcnt(2)
	v_mfma_f32_16x16x32_bf16 v[86:89], v[54:57], v[86:89], v[150:153]
	s_nop 2
	global_load_dwordx4 v[150:153], v[130:131], off
	global_load_dwordx4 v[154:157], v[114:115], off
	s_waitcnt vmcnt(23)
	ds_write_b128 v120, v[2:5] offset:7168
	s_waitcnt vmcnt(22)
	ds_write_b128 v120, v[6:9] offset:8448
	s_waitcnt vmcnt(21)
	ds_write_b128 v120, v[10:13] offset:9728
	s_waitcnt vmcnt(20)
	ds_write_b128 v120, v[14:17] offset:11008
	s_waitcnt vmcnt(19)
	ds_write_b128 v120, v[58:61] offset:12288
	s_waitcnt vmcnt(18)
	ds_write_b128 v120, v[62:65] offset:13568
	s_waitcnt vmcnt(17)
	ds_write_b128 v120, v[106:109] offset:14848
	s_waitcnt vmcnt(16)
	ds_write_b128 v120, v[110:113] offset:16128
	ds_read_b128 v[2:5], v117 offset:5440
	ds_read_b64_tr_b16 v[10:11], v116 offset:7168
	ds_read_b64_tr_b16 v[12:13], v116 offset:8448
	ds_read_b64_tr_b16 v[14:15], v116 offset:7392
	v_mfma_f32_16x16x32_bf16 v[122:125], v[54:57], v[158:161], v[122:125]
	s_waitcnt lgkmcnt(3)
	v_cndmask_b32_e64 v5, v5, 0, s[12:13]
	v_cndmask_b32_e64 v4, v4, 0, s[12:13]
	v_cndmask_b32_e64 v3, v3, 0, s[12:13]
	v_cndmask_b32_e64 v2, v2, 0, s[12:13]
	v_mfma_f32_16x16x32_bf16 v[126:129], v[54:57], v[162:165], v[126:129]
	v_mfma_f32_16x16x32_bf16 v[90:93], v[54:57], v[94:97], v[90:93]
	v_mfma_f32_16x16x32_bf16 v[6:9], v[54:57], v[98:101], v[50:53]
	s_nop 2
	ds_read_b64_tr_b16 v[52:53], v116 offset:8480
	ds_read_b64_tr_b16 v[50:51], v116 offset:7200
	ds_read_b64_tr_b16 v[54:55], v116 offset:7232
	ds_read_b64_tr_b16 v[58:59], v116 offset:7264
	ds_read_b64_tr_b16 v[62:63], v116 offset:7296
	ds_read_b64_tr_b16 v[56:57], v116 offset:8512
	ds_read_b64_tr_b16 v[60:61], v116 offset:8544
	ds_read_b64_tr_b16 v[64:65], v116 offset:8576
	s_waitcnt lgkmcnt(9)
	v_mfma_f32_16x16x32_bf16 v[10:13], v[2:5], v[10:13], v[82:85]
	s_nop 2
	ds_read_b64_tr_b16 v[82:83], v116 offset:7328
	ds_read_b64_tr_b16 v[84:85], v116 offset:8608
	ds_read_b64_tr_b16 v[94:95], v116 offset:7360
	ds_read_b64_tr_b16 v[96:97], v116 offset:8640
	ds_read_b64_tr_b16 v[16:17], v116 offset:8672
	s_waitcnt vmcnt(15)
	ds_write_b128 v120, v[26:29] offset:7168
	s_waitcnt vmcnt(14)
	ds_write_b128 v120, v[30:33] offset:8448
	s_waitcnt vmcnt(13)
	ds_write_b128 v120, v[42:45] offset:9728
	s_waitcnt vmcnt(12)
	ds_write_b128 v120, v[46:49] offset:11008
	s_waitcnt vmcnt(11)
	ds_write_b128 v120, v[66:69] offset:12288
	s_waitcnt vmcnt(10)
	ds_write_b128 v120, v[70:73] offset:13568
	s_waitcnt vmcnt(9)
	ds_write_b128 v120, v[74:77] offset:14848
	s_waitcnt vmcnt(8)
	ds_write_b128 v120, v[78:81] offset:16128
	ds_read_b128 v[26:29], v117 offset:5504
	s_waitcnt lgkmcnt(14)
	v_mfma_f32_16x16x32_bf16 v[50:53], v[2:5], v[50:53], v[102:105]
	v_mfma_f32_16x16x32_bf16 v[54:57], v[2:5], v[54:57], v[146:149]
	v_mfma_f32_16x16x32_bf16 v[58:61], v[2:5], v[58:61], v[122:125]
	v_mfma_f32_16x16x32_bf16 v[62:65], v[2:5], v[62:65], v[126:129]
	s_waitcnt lgkmcnt(12)
	v_mfma_f32_16x16x32_bf16 v[82:85], v[2:5], v[82:85], v[86:89]
	s_waitcnt lgkmcnt(10)
	v_mfma_f32_16x16x32_bf16 v[86:89], v[2:5], v[94:97], v[90:93]
	s_waitcnt lgkmcnt(9)
	v_mfma_f32_16x16x32_bf16 v[2:5], v[2:5], v[14:17], v[6:9]
	s_nop 2
	ds_read_b64_tr_b16 v[6:7], v116 offset:7168
	s_waitcnt lgkmcnt(1)
	v_cndmask_b32_e64 v17, v29, 0, s[12:13]
	v_cndmask_b32_e64 v16, v28, 0, s[12:13]
	v_cndmask_b32_e64 v15, v27, 0, s[12:13]
	v_cndmask_b32_e64 v14, v26, 0, s[12:13]
	ds_read_b64_tr_b16 v[8:9], v116 offset:8448
	ds_read_b64_tr_b16 v[26:27], v116 offset:7392
	s_waitcnt lgkmcnt(1)
	v_mfma_f32_16x16x32_bf16 v[6:9], v[14:17], v[6:9], v[10:13]
	s_nop 2
	ds_read_b64_tr_b16 v[12:13], v116 offset:8480
	ds_read_b64_tr_b16 v[10:11], v116 offset:7200
	ds_read_b64_tr_b16 v[28:29], v116 offset:7232
	ds_read_b64_tr_b16 v[42:43], v116 offset:7264
	ds_read_b64_tr_b16 v[46:47], v116 offset:7296
	ds_read_b64_tr_b16 v[30:31], v116 offset:8512
	ds_read_b64_tr_b16 v[44:45], v116 offset:8544
	ds_read_b64_tr_b16 v[48:49], v116 offset:8576
	s_waitcnt lgkmcnt(6)
	v_mfma_f32_16x16x32_bf16 v[10:13], v[14:17], v[10:13], v[50:53]
	s_waitcnt lgkmcnt(2)
	v_mfma_f32_16x16x32_bf16 v[50:53], v[14:17], v[28:31], v[54:57]
	ds_read_b64_tr_b16 v[30:31], v116 offset:7328
	ds_read_b64_tr_b16 v[32:33], v116 offset:8608
	s_nop 0
	ds_read_b64_tr_b16 v[54:55], v116 offset:7360
	ds_read_b64_tr_b16 v[56:57], v116 offset:8640
	ds_read_b64_tr_b16 v[28:29], v116 offset:8672
	s_waitcnt vmcnt(7)
	ds_write_b128 v120, v[18:21] offset:7168
	s_waitcnt vmcnt(6)
	ds_write_b128 v120, v[22:25] offset:8448
	s_waitcnt vmcnt(5)
	ds_write_b128 v120, v[34:37] offset:9728
	s_waitcnt vmcnt(4)
	ds_write_b128 v120, v[38:41] offset:11008
	s_waitcnt vmcnt(3)
	ds_write_b128 v120, v[142:145] offset:12288
	s_waitcnt vmcnt(2)
	ds_write_b128 v120, v[166:169] offset:13568
	s_waitcnt vmcnt(1)
	ds_write_b128 v120, v[150:153] offset:14848
	s_waitcnt vmcnt(0)
	ds_write_b128 v120, v[154:157] offset:16128
	ds_read_b128 v[18:21], v117 offset:5568
	s_waitcnt lgkmcnt(14)
	v_mfma_f32_16x16x32_bf16 v[42:45], v[14:17], v[42:45], v[58:61]
	v_mfma_f32_16x16x32_bf16 v[46:49], v[14:17], v[46:49], v[62:65]
	s_waitcnt lgkmcnt(12)
	v_mfma_f32_16x16x32_bf16 v[58:61], v[14:17], v[30:33], v[82:85]
	s_waitcnt lgkmcnt(10)
	v_mfma_f32_16x16x32_bf16 v[54:57], v[14:17], v[54:57], v[86:89]
	s_waitcnt lgkmcnt(9)
	v_mfma_f32_16x16x32_bf16 v[2:5], v[14:17], v[26:29], v[2:5]
	ds_read_b64_tr_b16 v[14:15], v116 offset:7168
	s_waitcnt lgkmcnt(1)
	v_cndmask_b32_e64 v37, v21, 0, s[12:13]
	v_cndmask_b32_e64 v36, v20, 0, s[12:13]
	v_cndmask_b32_e64 v35, v19, 0, s[12:13]
	v_cndmask_b32_e64 v34, v18, 0, s[12:13]
	ds_read_b64_tr_b16 v[16:17], v116 offset:8448
	ds_read_b64_tr_b16 v[38:39], v116 offset:7392
	s_waitcnt lgkmcnt(1)
	v_mfma_f32_16x16x32_bf16 v[30:33], v[34:37], v[14:17], v[6:9]
	s_nop 2
	ds_read_b64_tr_b16 v[8:9], v116 offset:8480
	ds_read_b64_tr_b16 v[6:7], v116 offset:7200
	ds_read_b64_tr_b16 v[14:15], v116 offset:7232
	ds_read_b64_tr_b16 v[18:19], v116 offset:7264
	ds_read_b64_tr_b16 v[62:63], v116 offset:7296
	ds_read_b64_tr_b16 v[16:17], v116 offset:8512
	ds_read_b64_tr_b16 v[20:21], v116 offset:8544
	ds_read_b64_tr_b16 v[64:65], v116 offset:8576
	s_waitcnt lgkmcnt(6)
	v_mfma_f32_16x16x32_bf16 v[26:29], v[34:37], v[6:9], v[10:13]
	ds_read_b64_tr_b16 v[6:7], v116 offset:7328
	ds_read_b64_tr_b16 v[8:9], v116 offset:8608
	s_waitcnt lgkmcnt(3)
	v_mfma_f32_16x16x32_bf16 v[18:21], v[34:37], v[18:21], v[42:45]
	s_nop 2
	ds_read_b64_tr_b16 v[42:43], v116 offset:7360
	ds_read_b64_tr_b16 v[44:45], v116 offset:8640
	ds_read_b64_tr_b16 v[40:41], v116 offset:8672
	v_mfma_f32_16x16x32_bf16 v[22:25], v[34:37], v[14:17], v[50:53]
	s_waitcnt lgkmcnt(5)
	v_mfma_f32_16x16x32_bf16 v[14:17], v[34:37], v[62:65], v[46:49]
	s_waitcnt lgkmcnt(3)
	v_mfma_f32_16x16x32_bf16 v[10:13], v[34:37], v[6:9], v[58:61]
	s_waitcnt lgkmcnt(1)
	v_mfma_f32_16x16x32_bf16 v[6:9], v[34:37], v[42:45], v[54:57]
	s_waitcnt lgkmcnt(0)
	v_mfma_f32_16x16x32_bf16 v[2:5], v[34:37], v[38:41], v[2:5]
	s_and_saveexec_b64 s[4:5], s[10:11]
	s_cbranch_execz .LBB0_2995
	s_lshl_b32 s7, s7, 9
	v_or_b32_e32 v1, s6, v1
	v_or_b32_e32 v34, s7, v1
	v_readlane_b32 s8, v251, 35
	v_cvt_pk_bf16_f32 v30, v30, s0
	v_lshlrev_b32_e32 v34, 1, v34
	v_readlane_b32 s22, v251, 49
	v_readlane_b32 s23, v251, 50
	v_add_u32_e32 v134, s7, v1
	v_cvt_pk_bf16_f32 v1, v32, s0
	v_add_u32_e32 v32, 0x100, v134
	v_readlane_b32 s9, v251, 36
	v_readlane_b32 s10, v251, 37
	global_store_short v34, v30, s[22:23]
	v_cvt_pk_bf16_f32 v34, v31, s0
	v_lshl_add_u64 v[30:31], v[134:135], 1, s[22:23]
	global_store_short v[30:31], v1, off offset:512
	v_cvt_pk_bf16_f32 v1, v33, s0
	global_store_short v[30:31], v1, off offset:768
	v_cvt_pk_bf16_f32 v1, v26, s0
	global_store_short v[30:31], v1, off offset:32
	v_cvt_pk_bf16_f32 v1, v27, s0
	v_add_u32_e32 v26, 0x80, v134
	v_mov_b32_e32 v27, v135
	v_lshl_add_u64 v[26:27], v[26:27], 1, s[22:23]
	v_mov_b32_e32 v33, v135
	global_store_short v[30:31], v34, off offset:256
	global_store_short v[26:27], v1, off offset:32
	v_cvt_pk_bf16_f32 v1, v28, s0
	v_lshl_add_u64 v[32:33], v[32:33], 1, s[22:23]
	v_add_u32_e32 v134, 0x180, v134
	global_store_short v[32:33], v1, off offset:32
	v_cvt_pk_bf16_f32 v1, v29, s0
	v_lshl_add_u64 v[28:29], v[134:135], 1, s[22:23]
	global_store_short v[28:29], v1, off offset:32
	v_cvt_pk_bf16_f32 v1, v22, s0
	global_store_short v[30:31], v1, off offset:64
	v_cvt_pk_bf16_f32 v1, v23, s0
	global_store_short v[26:27], v1, off offset:64
	v_cvt_pk_bf16_f32 v1, v24, s0
	global_store_short v[32:33], v1, off offset:64
	v_cvt_pk_bf16_f32 v1, v25, s0
	global_store_short v[28:29], v1, off offset:64
	v_cvt_pk_bf16_f32 v1, v18, s0
	global_store_short v[30:31], v1, off offset:96
	v_cvt_pk_bf16_f32 v1, v19, s0
	global_store_short v[26:27], v1, off offset:96
	v_cvt_pk_bf16_f32 v1, v20, s0
	global_store_short v[32:33], v1, off offset:96
	v_cvt_pk_bf16_f32 v1, v21, s0
	global_store_short v[28:29], v1, off offset:96
	v_cvt_pk_bf16_f32 v1, v14, s0
	global_store_short v[30:31], v1, off offset:128
	v_cvt_pk_bf16_f32 v1, v15, s0
	global_store_short v[26:27], v1, off offset:128
	v_cvt_pk_bf16_f32 v1, v16, s0
	global_store_short v[32:33], v1, off offset:128
	v_cvt_pk_bf16_f32 v1, v17, s0
	global_store_short v[28:29], v1, off offset:128
	v_cvt_pk_bf16_f32 v1, v10, s0
	global_store_short v[30:31], v1, off offset:160
	v_cvt_pk_bf16_f32 v1, v11, s0
	global_store_short v[26:27], v1, off offset:160
	v_cvt_pk_bf16_f32 v1, v12, s0
	global_store_short v[32:33], v1, off offset:160
	v_cvt_pk_bf16_f32 v1, v13, s0
	global_store_short v[28:29], v1, off offset:160
	v_cvt_pk_bf16_f32 v1, v6, s0
	global_store_short v[30:31], v1, off offset:192
	v_cvt_pk_bf16_f32 v1, v7, s0
	global_store_short v[26:27], v1, off offset:192
	v_cvt_pk_bf16_f32 v1, v8, s0
	global_store_short v[32:33], v1, off offset:192
	v_cvt_pk_bf16_f32 v1, v9, s0
	global_store_short v[28:29], v1, off offset:192
	v_cvt_pk_bf16_f32 v1, v2, s0
	global_store_short v[30:31], v1, off offset:224
	v_cvt_pk_bf16_f32 v1, v3, s0
	global_store_short v[26:27], v1, off offset:224
	v_cvt_pk_bf16_f32 v1, v4, s0
	global_store_short v[32:33], v1, off offset:224
	v_cvt_pk_bf16_f32 v1, v5, s0
	v_readlane_b32 s11, v251, 38
	v_readlane_b32 s12, v251, 39
	v_readlane_b32 s13, v251, 40
	v_readlane_b32 s14, v251, 41
	v_readlane_b32 s15, v251, 42
	v_readlane_b32 s16, v251, 43
	v_readlane_b32 s17, v251, 44
	v_readlane_b32 s18, v251, 45
	v_readlane_b32 s19, v251, 46
	v_readlane_b32 s20, v251, 47
	v_readlane_b32 s21, v251, 48
	global_store_short v[28:29], v1, off offset:224
	s_branch .LBB0_2995
